# norm phases (6 of 8): wave sum-of-squares reduction with v_permlane32_swap / DPP row rotations instead of ds_bpermute for the xor-32/8/4/2 steps
# baseline (speedup 1.0000x reference)
; DI float wave_sum(float v) {
;     v += __shfl_xor(v, 32); v += __shfl_xor(v, 16); v += __shfl_xor(v, 8); v += __shfl_xor(v, 4); v += __shfl_xor(v, 2); v += __shfl_xor(v, 1);
;     return v;
; }
; DI void norm_phase(const Params& p, int layer, int which, bool lat_only, const float* __restrict__ part, int npart, int srcmode) {
;     ...
;                 for (int j = 0; j < 4; ++j) ss[q] += v[q][j][0] * v[q][j][0] + v[q][j][1] * v[q][j][1] + v[q][j][2] * v[q][j][2] + v[q][j][3] * v[q][j][3];
;             }
;         }
;         ss[0] = wave_sum(ss[0]); ss[1] = wave_sum(ss[1]); ss[2] = wave_sum(ss[2]);
; #pragma unroll
;         for (int q = 0; q < 3; ++q) {
;             if (!ok[q]) continue;
;             const int row = r0 + 256 * q; const int ci = cond_idx(row);
;             if (ci != cur_ci) { cur_ci = ci; const float* mo = mod + (size_t)ci * 6144 + which * 3072;
; #pragma unroll
;                 for (int j = 0; j < 4; ++j) { const int col = j * 256 + lane * 4; gm[j] = *(const f32x4*)(gain + col) * (1.f + *(const f32x4*)(mo + 1024 + col)); sh[j] = *(const f32x4*)(mo + col); } }
.LBB0_648:
	s_or_b64 exec, exec, s[14:15]
	s_waitcnt vmcnt(7)
	v_mul_f32_e32 v102, v65, v65
	s_waitcnt vmcnt(6)
	v_mul_f32_e32 v103, v57, v57
	v_fmac_f32_e32 v102, v64, v64
	v_fmac_f32_e32 v103, v56, v56
	v_fmac_f32_e32 v102, v66, v66
	v_fmac_f32_e32 v103, v58, v58
	v_fmac_f32_e32 v102, v67, v67
	v_fmac_f32_e32 v103, v59, v59
	v_add_f32_e32 v102, v103, v102
	s_waitcnt vmcnt(5)
	v_mul_f32_e32 v103, v53, v53
	v_fmac_f32_e32 v103, v52, v52
	v_fmac_f32_e32 v103, v54, v54
	v_fmac_f32_e32 v103, v55, v55
	v_add_f32_e32 v102, v103, v102
	s_waitcnt vmcnt(4)
	v_mul_f32_e32 v103, v45, v45
	v_fmac_f32_e32 v103, v44, v44
	v_fmac_f32_e32 v103, v46, v46
	v_fmac_f32_e32 v103, v47, v47
	v_add_f32_e32 v102, v103, v102
	v_mul_f32_e32 v103, v49, v49
	v_mul_f32_e32 v106, v41, v41
	v_fmac_f32_e32 v103, v48, v48
	v_fmac_f32_e32 v106, v40, v40
	v_fmac_f32_e32 v103, v50, v50
	v_fmac_f32_e32 v106, v42, v42
	v_fmac_f32_e32 v103, v51, v51
	v_fmac_f32_e32 v106, v43, v43
	v_add_f32_e32 v103, v106, v103
	v_mul_f32_e32 v106, v37, v37
	v_fmac_f32_e32 v106, v36, v36
	v_fmac_f32_e32 v106, v38, v38
	v_fmac_f32_e32 v106, v39, v39
	v_add_f32_e32 v103, v106, v103
	v_mul_f32_e32 v106, v33, v33
	v_fmac_f32_e32 v106, v32, v32
	v_fmac_f32_e32 v106, v34, v34
	v_fmac_f32_e32 v106, v35, v35
	v_add_f32_e32 v103, v106, v103
	s_waitcnt vmcnt(3)
	v_mul_f32_e32 v106, v77, v77
	s_waitcnt vmcnt(2)
	v_mul_f32_e32 v107, v73, v73
	v_fmac_f32_e32 v106, v76, v76
	v_fmac_f32_e32 v107, v72, v72
	v_fmac_f32_e32 v106, v78, v78
	v_fmac_f32_e32 v107, v74, v74
	v_fmac_f32_e32 v106, v79, v79
	v_fmac_f32_e32 v107, v75, v75
	v_add_f32_e32 v106, v107, v106
	s_waitcnt vmcnt(1)
	v_mul_f32_e32 v107, v69, v69
	v_fmac_f32_e32 v107, v68, v68
	v_fmac_f32_e32 v107, v70, v70
	v_fmac_f32_e32 v107, v71, v71
	v_add_f32_e32 v106, v107, v106
	s_waitcnt vmcnt(0)
	v_mul_f32_e32 v107, v61, v61
	v_fmac_f32_e32 v107, v60, v60
	v_fmac_f32_e32 v107, v62, v62
	v_fmac_f32_e32 v107, v63, v63
	v_add_f32_e32 v106, v107, v106
	s_nop 0
	s_nop 0
	s_nop 0
	v_cndmask_b32_e64 v105, v105, 8, vcc
	v_cmp_ne_u32_e32 vcc, v105, v109
	s_waitcnt lgkmcnt(2)
	v_mov_b32_e32 v108, v103
	s_nop 1
	v_permlane32_swap_b32_e32 v103, v108
	v_add_f32_e32 v103, v103, v108
	s_waitcnt lgkmcnt(1)
	v_mov_b32_e32 v114, v102
	s_nop 1
	v_permlane32_swap_b32_e32 v102, v114
	v_add_f32_e32 v102, v102, v114
	s_waitcnt lgkmcnt(0)
	v_mov_b32_e32 v107, v106
	s_nop 1
	v_permlane32_swap_b32_e32 v106, v107
	v_add_f32_e32 v106, v106, v107
	ds_bpermute_b32 v108, v93, v103
	ds_bpermute_b32 v114, v93, v102
	ds_bpermute_b32 v107, v93, v106
	s_waitcnt lgkmcnt(2)
	v_add_f32_e32 v103, v103, v108
	s_waitcnt lgkmcnt(1)
	v_add_f32_e32 v102, v102, v114
	s_waitcnt lgkmcnt(0)
	v_add_f32_e32 v106, v106, v107
	s_nop 0
	s_nop 0
	s_nop 0
	s_waitcnt lgkmcnt(2)
	s_nop 1
	v_add_f32_dpp v103, v103, v103 row_ror:8 row_mask:0xf bank_mask:0xf
	s_waitcnt lgkmcnt(1)
	s_nop 1
	v_add_f32_dpp v102, v102, v102 row_ror:8 row_mask:0xf bank_mask:0xf
	s_waitcnt lgkmcnt(0)
	s_nop 1
	v_add_f32_dpp v106, v106, v106 row_ror:8 row_mask:0xf bank_mask:0xf
	s_nop 0
	s_nop 0
	s_nop 0
	s_waitcnt lgkmcnt(2)
	s_nop 1
	v_add_f32_dpp v103, v103, v103 row_ror:4 row_mask:0xf bank_mask:0xf
	s_waitcnt lgkmcnt(1)
	s_nop 1
	v_add_f32_dpp v102, v102, v102 row_ror:4 row_mask:0xf bank_mask:0xf
	s_waitcnt lgkmcnt(0)
	s_nop 1
	v_add_f32_dpp v106, v106, v106 row_ror:4 row_mask:0xf bank_mask:0xf
	s_nop 0
	s_nop 0
	s_nop 0
	s_waitcnt lgkmcnt(2)
	s_nop 1
	v_add_f32_dpp v118, v103, v103 row_ror:2 row_mask:0xf bank_mask:0xf
	s_waitcnt lgkmcnt(1)
	s_nop 1
	v_add_f32_dpp v116, v102, v102 row_ror:2 row_mask:0xf bank_mask:0xf
	s_waitcnt lgkmcnt(0)
	s_nop 1
	v_add_f32_dpp v114, v106, v106 row_ror:2 row_mask:0xf bank_mask:0xf
	ds_bpermute_b32 v119, v122, v118
	ds_bpermute_b32 v117, v122, v116
	ds_bpermute_b32 v115, v122, v114
	v_lshlrev_b32_e32 v108, 2, v88
	v_lshlrev_b32_e32 v106, 2, v92
	v_lshlrev_b32_e32 v102, 2, v96
	s_and_saveexec_b64 s[0:1], vcc
	s_cbranch_execz .LBB0_650
	v_mul_hi_i32_i24_e32 v1, 0x6000, v105
	v_mul_i32_i24_e32 v0, 0x6000, v105
	v_lshl_add_u64 v[0:1], s[10:11], 0, v[0:1]
	v_lshl_add_u64 v[2:3], v[0:1], 0, s[8:9]
	v_lshl_add_u64 v[4:5], v[2:3], 0, v[82:83]
	v_mov_b32_e32 v109, v83
	global_load_dwordx4 v[16:19], v[4:5], off
	v_lshl_add_u64 v[4:5], v[2:3], 0, v[108:109]
	v_mov_b32_e32 v107, v83
	global_load_dwordx4 v[20:23], v[4:5], off
	v_lshl_add_u64 v[4:5], v[2:3], 0, v[106:107]
	v_mov_b32_e32 v103, v83
	global_load_dwordx4 v[24:27], v[4:5], off
	v_lshl_add_u64 v[2:3], v[2:3], 0, v[102:103]
	global_load_dwordx4 v[28:31], v[2:3], off
	global_load_dwordx4 v[124:127], v[86:87], off
	global_load_dwordx4 v[128:131], v[90:91], off
	v_lshl_add_u64 v[12:13], v[0:1], 0, v[82:83]
	global_load_dwordx4 v[132:135], v[94:95], off
	global_load_dwordx4 v[0:3], v[12:13], off
	global_load_dwordx4 v[136:139], v[98:99], off
	global_load_dwordx4 v[4:7], v[12:13], off offset:1024
	global_load_dwordx4 v[8:11], v[12:13], off offset:2048
	s_nop 0
	global_load_dwordx4 v[12:15], v[12:13], off offset:3072
	v_mov_b32_e32 v109, v105
	s_waitcnt vmcnt(11)
	v_pk_add_f32 v[18:19], v[18:19], 1.0 op_sel_hi:[1,0]
	v_pk_add_f32 v[16:17], v[16:17], 1.0 op_sel_hi:[1,0]
	s_waitcnt vmcnt(10)
	v_pk_add_f32 v[22:23], v[22:23], 1.0 op_sel_hi:[1,0]
	v_pk_add_f32 v[20:21], v[20:21], 1.0 op_sel_hi:[1,0]
	s_waitcnt vmcnt(9)
	v_pk_add_f32 v[26:27], v[26:27], 1.0 op_sel_hi:[1,0]
	v_pk_add_f32 v[24:25], v[24:25], 1.0 op_sel_hi:[1,0]
	s_waitcnt vmcnt(8)
	v_pk_add_f32 v[30:31], v[30:31], 1.0 op_sel_hi:[1,0]
	v_pk_add_f32 v[28:29], v[28:29], 1.0 op_sel_hi:[1,0]
	s_waitcnt vmcnt(7)
	v_pk_mul_f32 v[18:19], v[126:127], v[18:19]
	v_pk_mul_f32 v[16:17], v[124:125], v[16:17]
	s_waitcnt vmcnt(6)
	v_pk_mul_f32 v[22:23], v[130:131], v[22:23]
	v_pk_mul_f32 v[20:21], v[128:129], v[20:21]
	s_waitcnt vmcnt(5)
	v_pk_mul_f32 v[26:27], v[134:135], v[26:27]
	v_pk_mul_f32 v[24:25], v[132:133], v[24:25]
	s_waitcnt vmcnt(3)
	v_pk_mul_f32 v[30:31], v[138:139], v[30:31]
	v_pk_mul_f32 v[28:29], v[136:137], v[28:29]

; DI float wave_sum(float v) {
;     v += __shfl_xor(v, 32); v += __shfl_xor(v, 16); v += __shfl_xor(v, 8); v += __shfl_xor(v, 4); v += __shfl_xor(v, 2); v += __shfl_xor(v, 1);
;     return v;
; }
; DI void norm_phase(const Params& p, int layer, int which, bool lat_only, const float* __restrict__ part, int npart, int srcmode) {
;     ...
;                 for (int j = 0; j < 4; ++j) ss[q] += v[q][j][0] * v[q][j][0] + v[q][j][1] * v[q][j][1] + v[q][j][2] * v[q][j][2] + v[q][j][3] * v[q][j][3];
;             }
;         }
;         ss[0] = wave_sum(ss[0]); ss[1] = wave_sum(ss[1]); ss[2] = wave_sum(ss[2]);
; #pragma unroll
;         for (int q = 0; q < 3; ++q) {
;             if (!ok[q]) continue;
;             const int row = r0 + 256 * q; const int ci = cond_idx(row);
;             if (ci != cur_ci) { cur_ci = ci; const float* mo = mod + (size_t)ci * 6144 + which * 3072;
; #pragma unroll
;                 for (int j = 0; j < 4; ++j) { const int col = j * 256 + lane * 4; gm[j] = *(const f32x4*)(gain + col) * (1.f + *(const f32x4*)(mo + 1024 + col)); sh[j] = *(const f32x4*)(mo + col); } }
.LBB0_672:
	s_or_b64 exec, exec, s[14:15]
	s_waitcnt vmcnt(7)
	v_mul_f32_e32 v107, v65, v65
	s_waitcnt vmcnt(6)
	v_mul_f32_e32 v111, v57, v57
	v_fmac_f32_e32 v107, v64, v64
	v_fmac_f32_e32 v111, v56, v56
	v_fmac_f32_e32 v107, v66, v66
	v_fmac_f32_e32 v111, v58, v58
	v_fmac_f32_e32 v107, v67, v67
	v_fmac_f32_e32 v111, v59, v59
	v_add_f32_e32 v107, v111, v107
	s_waitcnt vmcnt(5)
	v_mul_f32_e32 v111, v53, v53
	v_fmac_f32_e32 v111, v52, v52
	v_fmac_f32_e32 v111, v54, v54
	v_fmac_f32_e32 v111, v55, v55
	v_add_f32_e32 v107, v111, v107
	s_waitcnt vmcnt(4)
	v_mul_f32_e32 v111, v45, v45
	v_fmac_f32_e32 v111, v44, v44
	v_fmac_f32_e32 v111, v46, v46
	v_fmac_f32_e32 v111, v47, v47
	v_add_f32_e32 v107, v111, v107
	v_mul_f32_e32 v111, v49, v49
	v_mul_f32_e32 v113, v41, v41
	v_fmac_f32_e32 v111, v48, v48
	v_fmac_f32_e32 v113, v40, v40
	v_fmac_f32_e32 v111, v50, v50
	v_fmac_f32_e32 v113, v42, v42
	v_fmac_f32_e32 v111, v51, v51
	v_fmac_f32_e32 v113, v43, v43
	v_add_f32_e32 v111, v113, v111
	v_mul_f32_e32 v113, v37, v37
	v_fmac_f32_e32 v113, v36, v36
	v_fmac_f32_e32 v113, v38, v38
	v_fmac_f32_e32 v113, v39, v39
	v_add_f32_e32 v111, v113, v111
	v_mul_f32_e32 v113, v33, v33
	v_fmac_f32_e32 v113, v32, v32
	v_fmac_f32_e32 v113, v34, v34
	v_fmac_f32_e32 v113, v35, v35
	v_add_f32_e32 v111, v113, v111
	s_waitcnt vmcnt(3)
	v_mul_f32_e32 v113, v77, v77
	s_waitcnt vmcnt(2)
	v_mul_f32_e32 v116, v73, v73
	v_fmac_f32_e32 v113, v76, v76
	v_fmac_f32_e32 v116, v72, v72
	v_fmac_f32_e32 v113, v78, v78
	v_fmac_f32_e32 v116, v74, v74
	v_fmac_f32_e32 v113, v79, v79
	v_fmac_f32_e32 v116, v75, v75
	v_add_f32_e32 v113, v116, v113
	s_waitcnt vmcnt(1)
	v_mul_f32_e32 v116, v69, v69
	v_fmac_f32_e32 v116, v68, v68
	v_fmac_f32_e32 v116, v70, v70
	v_fmac_f32_e32 v116, v71, v71
	v_add_f32_e32 v113, v116, v113
	s_waitcnt vmcnt(0)
	v_mul_f32_e32 v116, v61, v61
	v_fmac_f32_e32 v116, v60, v60
	v_fmac_f32_e32 v116, v62, v62
	v_fmac_f32_e32 v116, v63, v63
	v_add_f32_e32 v113, v116, v113
	s_nop 0
	s_nop 0
	s_nop 0
	s_waitcnt lgkmcnt(2)
	v_mov_b32_e32 v117, v111
	s_nop 1
	v_permlane32_swap_b32_e32 v111, v117
	v_add_f32_e32 v111, v111, v117
	s_waitcnt lgkmcnt(1)
	v_mov_b32_e32 v118, v107
	s_nop 1
	v_permlane32_swap_b32_e32 v107, v118
	v_add_f32_e32 v107, v107, v118
	s_waitcnt lgkmcnt(0)
	v_mov_b32_e32 v116, v113
	s_nop 1
	v_permlane32_swap_b32_e32 v113, v116
	v_add_f32_e32 v113, v113, v116
	ds_bpermute_b32 v117, v93, v111
	ds_bpermute_b32 v118, v93, v107
	ds_bpermute_b32 v116, v93, v113
	s_waitcnt lgkmcnt(2)
	v_add_f32_e32 v111, v111, v117
	s_waitcnt lgkmcnt(1)
	v_add_f32_e32 v107, v107, v118
	s_waitcnt lgkmcnt(0)
	v_add_f32_e32 v113, v113, v116
	s_nop 0
	s_nop 0
	s_nop 0
	s_waitcnt lgkmcnt(2)
	s_nop 1
	v_add_f32_dpp v111, v111, v111 row_ror:8 row_mask:0xf bank_mask:0xf
	s_waitcnt lgkmcnt(1)
	s_nop 1
	v_add_f32_dpp v107, v107, v107 row_ror:8 row_mask:0xf bank_mask:0xf
	s_waitcnt lgkmcnt(0)
	s_nop 1
	v_add_f32_dpp v113, v113, v113 row_ror:8 row_mask:0xf bank_mask:0xf
	s_nop 0
	s_nop 0
	s_nop 0
	s_waitcnt lgkmcnt(2)
	s_nop 1
	v_add_f32_dpp v111, v111, v111 row_ror:4 row_mask:0xf bank_mask:0xf
	s_waitcnt lgkmcnt(1)
	s_nop 1
	v_add_f32_dpp v107, v107, v107 row_ror:4 row_mask:0xf bank_mask:0xf
	s_waitcnt lgkmcnt(0)
	s_nop 1
	v_add_f32_dpp v116, v113, v113 row_ror:4 row_mask:0xf bank_mask:0xf
	s_nop 0
	s_nop 0
	s_nop 0
	s_waitcnt lgkmcnt(2)
	s_nop 1
	v_add_f32_dpp v111, v111, v111 row_ror:2 row_mask:0xf bank_mask:0xf
	s_waitcnt lgkmcnt(1)
	s_nop 1
	v_add_f32_dpp v113, v107, v107 row_ror:2 row_mask:0xf bank_mask:0xf
	s_waitcnt lgkmcnt(0)
	s_nop 1
	v_add_f32_dpp v116, v116, v116 row_ror:2 row_mask:0xf bank_mask:0xf
	ds_bpermute_b32 v119, v122, v111
	ds_bpermute_b32 v118, v122, v113
	ds_bpermute_b32 v117, v122, v116
	v_cndmask_b32_e64 v124, v103, 8, vcc
	v_cmp_ne_u32_e32 vcc, v124, v109
	s_and_saveexec_b64 s[0:1], vcc
	s_cbranch_execz .LBB0_674
	v_mul_hi_i32_i24_e32 v1, 0x6000, v124
	v_mul_i32_i24_e32 v0, 0x6000, v124
	v_lshl_add_u64 v[0:1], s[10:11], 0, v[0:1]
	v_lshl_add_u64 v[2:3], v[0:1], 0, s[8:9]
	v_lshl_add_u64 v[4:5], v[2:3], 0, v[82:83]
	v_mov_b32_e32 v109, v83
	global_load_dwordx4 v[16:19], v[4:5], off
	v_lshl_add_u64 v[4:5], v[2:3], 0, v[108:109]
	v_mov_b32_e32 v107, v83
	global_load_dwordx4 v[20:23], v[4:5], off
	v_lshl_add_u64 v[4:5], v[2:3], 0, v[106:107]
	v_mov_b32_e32 v103, v83
	global_load_dwordx4 v[24:27], v[4:5], off
	v_lshl_add_u64 v[2:3], v[2:3], 0, v[102:103]
	global_load_dwordx4 v[28:31], v[2:3], off
	global_load_dwordx4 v[126:129], v[86:87], off
	global_load_dwordx4 v[130:133], v[90:91], off
	v_lshl_add_u64 v[12:13], v[0:1], 0, v[82:83]
	global_load_dwordx4 v[134:137], v[94:95], off
	global_load_dwordx4 v[0:3], v[12:13], off
	global_load_dwordx4 v[138:141], v[98:99], off
	global_load_dwordx4 v[4:7], v[12:13], off offset:1024
	global_load_dwordx4 v[8:11], v[12:13], off offset:2048
	s_nop 0
	global_load_dwordx4 v[12:15], v[12:13], off offset:3072
	v_mov_b32_e32 v109, v124
	s_waitcnt vmcnt(11)
	v_pk_add_f32 v[18:19], v[18:19], 1.0 op_sel_hi:[1,0]
	v_pk_add_f32 v[16:17], v[16:17], 1.0 op_sel_hi:[1,0]
	s_waitcnt vmcnt(10)
	v_pk_add_f32 v[22:23], v[22:23], 1.0 op_sel_hi:[1,0]
	v_pk_add_f32 v[20:21], v[20:21], 1.0 op_sel_hi:[1,0]
	s_waitcnt vmcnt(9)
	v_pk_add_f32 v[26:27], v[26:27], 1.0 op_sel_hi:[1,0]
	v_pk_add_f32 v[24:25], v[24:25], 1.0 op_sel_hi:[1,0]
	s_waitcnt vmcnt(8)
	v_pk_add_f32 v[30:31], v[30:31], 1.0 op_sel_hi:[1,0]
	v_pk_add_f32 v[28:29], v[28:29], 1.0 op_sel_hi:[1,0]
	s_waitcnt vmcnt(7)
	v_pk_mul_f32 v[18:19], v[128:129], v[18:19]
	v_pk_mul_f32 v[16:17], v[126:127], v[16:17]
	s_waitcnt vmcnt(6)
	v_pk_mul_f32 v[22:23], v[132:133], v[22:23]
	v_pk_mul_f32 v[20:21], v[130:131], v[20:21]
	s_waitcnt vmcnt(5)
	v_pk_mul_f32 v[26:27], v[136:137], v[26:27]
	v_pk_mul_f32 v[24:25], v[134:135], v[24:25]
	s_waitcnt vmcnt(3)
	v_pk_mul_f32 v[30:31], v[140:141], v[30:31]
	v_pk_mul_f32 v[28:29], v[138:139], v[28:29]

; DI float wave_sum(float v) {
;     v += __shfl_xor(v, 32); v += __shfl_xor(v, 16); v += __shfl_xor(v, 8); v += __shfl_xor(v, 4); v += __shfl_xor(v, 2); v += __shfl_xor(v, 1);
;     return v;
; }
; DI void norm_phase(const Params& p, int layer, int which, bool lat_only, const float* __restrict__ part, int npart, int srcmode) {
;     ...
;                 for (int j = 0; j < 4; ++j) ss[q] += v[q][j][0] * v[q][j][0] + v[q][j][1] * v[q][j][1] + v[q][j][2] * v[q][j][2] + v[q][j][3] * v[q][j][3];
;             }
;         }
;         ss[0] = wave_sum(ss[0]); ss[1] = wave_sum(ss[1]); ss[2] = wave_sum(ss[2]);
; #pragma unroll
;         for (int q = 0; q < 3; ++q) {
;             if (!ok[q]) continue;
;             const int row = r0 + 256 * q; const int ci = cond_idx(row);
;             if (ci != cur_ci) { cur_ci = ci; const float* mo = mod + (size_t)ci * 6144 + which * 3072;
; #pragma unroll
;                 for (int j = 0; j < 4; ++j) { const int col = j * 256 + lane * 4; gm[j] = *(const f32x4*)(gain + col) * (1.f + *(const f32x4*)(mo + 1024 + col)); sh[j] = *(const f32x4*)(mo + col); } }
.LBB0_696:
	s_or_b64 exec, exec, s[14:15]
	s_waitcnt vmcnt(7)
	v_mul_f32_e32 v107, v65, v65
	s_waitcnt vmcnt(6)
	v_mul_f32_e32 v111, v57, v57
	v_fmac_f32_e32 v107, v64, v64
	v_fmac_f32_e32 v111, v56, v56
	v_fmac_f32_e32 v107, v66, v66
	v_fmac_f32_e32 v111, v58, v58
	v_fmac_f32_e32 v107, v67, v67
	v_fmac_f32_e32 v111, v59, v59
	v_add_f32_e32 v107, v111, v107
	s_waitcnt vmcnt(5)
	v_mul_f32_e32 v111, v53, v53
	v_fmac_f32_e32 v111, v52, v52
	v_fmac_f32_e32 v111, v54, v54
	v_fmac_f32_e32 v111, v55, v55
	v_add_f32_e32 v107, v111, v107
	s_waitcnt vmcnt(4)
	v_mul_f32_e32 v111, v45, v45
	v_fmac_f32_e32 v111, v44, v44
	v_fmac_f32_e32 v111, v46, v46
	v_fmac_f32_e32 v111, v47, v47
	v_add_f32_e32 v107, v111, v107
	v_mul_f32_e32 v111, v49, v49
	v_mul_f32_e32 v113, v41, v41
	v_fmac_f32_e32 v111, v48, v48
	v_fmac_f32_e32 v113, v40, v40
	v_fmac_f32_e32 v111, v50, v50
	v_fmac_f32_e32 v113, v42, v42
	v_fmac_f32_e32 v111, v51, v51
	v_fmac_f32_e32 v113, v43, v43
	v_add_f32_e32 v111, v113, v111
	v_mul_f32_e32 v113, v37, v37
	v_fmac_f32_e32 v113, v36, v36
	v_fmac_f32_e32 v113, v38, v38
	v_fmac_f32_e32 v113, v39, v39
	v_add_f32_e32 v111, v113, v111
	v_mul_f32_e32 v113, v33, v33
	v_fmac_f32_e32 v113, v32, v32
	v_fmac_f32_e32 v113, v34, v34
	v_fmac_f32_e32 v113, v35, v35
	v_add_f32_e32 v111, v113, v111
	s_waitcnt vmcnt(3)
	v_mul_f32_e32 v113, v77, v77
	s_waitcnt vmcnt(2)
	v_mul_f32_e32 v114, v73, v73
	v_fmac_f32_e32 v113, v76, v76
	v_fmac_f32_e32 v114, v72, v72
	v_fmac_f32_e32 v113, v78, v78
	v_fmac_f32_e32 v114, v74, v74
	v_fmac_f32_e32 v113, v79, v79
	v_fmac_f32_e32 v114, v75, v75
	v_add_f32_e32 v113, v114, v113
	s_waitcnt vmcnt(1)
	v_mul_f32_e32 v114, v69, v69
	v_fmac_f32_e32 v114, v68, v68
	v_fmac_f32_e32 v114, v70, v70
	v_fmac_f32_e32 v114, v71, v71
	v_add_f32_e32 v113, v114, v113
	s_waitcnt vmcnt(0)
	v_mul_f32_e32 v114, v61, v61
	v_fmac_f32_e32 v114, v60, v60
	v_fmac_f32_e32 v114, v62, v62
	v_fmac_f32_e32 v114, v63, v63
	v_add_f32_e32 v113, v114, v113
	s_nop 0
	s_nop 0
	s_nop 0
	s_waitcnt lgkmcnt(2)
	v_mov_b32_e32 v115, v111
	s_nop 1
	v_permlane32_swap_b32_e32 v111, v115
	v_add_f32_e32 v111, v111, v115
	s_waitcnt lgkmcnt(1)
	v_mov_b32_e32 v116, v107
	s_nop 1
	v_permlane32_swap_b32_e32 v107, v116
	v_add_f32_e32 v107, v107, v116
	s_waitcnt lgkmcnt(0)
	v_mov_b32_e32 v114, v113
	s_nop 1
	v_permlane32_swap_b32_e32 v113, v114
	v_add_f32_e32 v113, v113, v114
	ds_bpermute_b32 v115, v93, v111
	ds_bpermute_b32 v116, v93, v107
	ds_bpermute_b32 v114, v93, v113
	s_waitcnt lgkmcnt(2)
	v_add_f32_e32 v111, v111, v115
	s_waitcnt lgkmcnt(1)
	v_add_f32_e32 v107, v107, v116
	s_waitcnt lgkmcnt(0)
	v_add_f32_e32 v113, v113, v114
	s_nop 0
	s_nop 0
	s_nop 0
	s_waitcnt lgkmcnt(2)
	s_nop 1
	v_add_f32_dpp v111, v111, v111 row_ror:8 row_mask:0xf bank_mask:0xf
	s_waitcnt lgkmcnt(1)
	s_nop 1
	v_add_f32_dpp v107, v107, v107 row_ror:8 row_mask:0xf bank_mask:0xf
	s_waitcnt lgkmcnt(0)
	s_nop 1
	v_add_f32_dpp v113, v113, v113 row_ror:8 row_mask:0xf bank_mask:0xf
	s_nop 0
	s_nop 0
	s_nop 0
	s_waitcnt lgkmcnt(2)
	s_nop 1
	v_add_f32_dpp v111, v111, v111 row_ror:4 row_mask:0xf bank_mask:0xf
	s_waitcnt lgkmcnt(1)
	s_nop 1
	v_add_f32_dpp v107, v107, v107 row_ror:4 row_mask:0xf bank_mask:0xf
	s_waitcnt lgkmcnt(0)
	s_nop 1
	v_add_f32_dpp v114, v113, v113 row_ror:4 row_mask:0xf bank_mask:0xf
	s_nop 0
	s_nop 0
	s_nop 0
	s_waitcnt lgkmcnt(2)
	s_nop 1
	v_add_f32_dpp v111, v111, v111 row_ror:2 row_mask:0xf bank_mask:0xf
	s_waitcnt lgkmcnt(1)
	s_nop 1
	v_add_f32_dpp v113, v107, v107 row_ror:2 row_mask:0xf bank_mask:0xf
	s_waitcnt lgkmcnt(0)
	s_nop 1
	v_add_f32_dpp v114, v114, v114 row_ror:2 row_mask:0xf bank_mask:0xf
	ds_bpermute_b32 v117, v122, v111
	ds_bpermute_b32 v116, v122, v113
	ds_bpermute_b32 v115, v122, v114
	v_cndmask_b32_e64 v119, v103, 8, vcc
	v_cmp_ne_u32_e32 vcc, v119, v109
	s_and_saveexec_b64 s[0:1], vcc
	s_cbranch_execz .LBB0_698
	v_mul_hi_i32_i24_e32 v1, 0x6000, v119
	v_mul_i32_i24_e32 v0, 0x6000, v119
	v_lshl_add_u64 v[0:1], s[10:11], 0, v[0:1]
	v_lshl_add_u64 v[2:3], v[0:1], 0, s[8:9]
	v_lshl_add_u64 v[4:5], v[2:3], 0, v[82:83]
	v_mov_b32_e32 v109, v83
	global_load_dwordx4 v[16:19], v[4:5], off
	v_lshl_add_u64 v[4:5], v[2:3], 0, v[108:109]
	v_mov_b32_e32 v107, v83
	global_load_dwordx4 v[20:23], v[4:5], off
	v_lshl_add_u64 v[4:5], v[2:3], 0, v[106:107]
	v_mov_b32_e32 v103, v83
	global_load_dwordx4 v[24:27], v[4:5], off
	v_lshl_add_u64 v[2:3], v[2:3], 0, v[102:103]
	global_load_dwordx4 v[28:31], v[2:3], off
	global_load_dwordx4 v[124:127], v[86:87], off
	global_load_dwordx4 v[128:131], v[90:91], off
	v_lshl_add_u64 v[12:13], v[0:1], 0, v[82:83]
	global_load_dwordx4 v[132:135], v[94:95], off
	global_load_dwordx4 v[0:3], v[12:13], off
	global_load_dwordx4 v[136:139], v[98:99], off
	global_load_dwordx4 v[4:7], v[12:13], off offset:1024
	global_load_dwordx4 v[8:11], v[12:13], off offset:2048
	s_nop 0
	global_load_dwordx4 v[12:15], v[12:13], off offset:3072
	v_mov_b32_e32 v109, v119
	s_waitcnt vmcnt(11)
	v_pk_add_f32 v[18:19], v[18:19], 1.0 op_sel_hi:[1,0]
	v_pk_add_f32 v[16:17], v[16:17], 1.0 op_sel_hi:[1,0]
	s_waitcnt vmcnt(10)
	v_pk_add_f32 v[22:23], v[22:23], 1.0 op_sel_hi:[1,0]
	v_pk_add_f32 v[20:21], v[20:21], 1.0 op_sel_hi:[1,0]
	s_waitcnt vmcnt(9)
	v_pk_add_f32 v[26:27], v[26:27], 1.0 op_sel_hi:[1,0]
	v_pk_add_f32 v[24:25], v[24:25], 1.0 op_sel_hi:[1,0]
	s_waitcnt vmcnt(8)
	v_pk_add_f32 v[30:31], v[30:31], 1.0 op_sel_hi:[1,0]
	v_pk_add_f32 v[28:29], v[28:29], 1.0 op_sel_hi:[1,0]
	s_waitcnt vmcnt(7)
	v_pk_mul_f32 v[18:19], v[126:127], v[18:19]
	v_pk_mul_f32 v[16:17], v[124:125], v[16:17]
	s_waitcnt vmcnt(6)
	v_pk_mul_f32 v[22:23], v[130:131], v[22:23]
	v_pk_mul_f32 v[20:21], v[128:129], v[20:21]
	s_waitcnt vmcnt(5)
	v_pk_mul_f32 v[26:27], v[134:135], v[26:27]
	v_pk_mul_f32 v[24:25], v[132:133], v[24:25]
	s_waitcnt vmcnt(3)
	v_pk_mul_f32 v[30:31], v[138:139], v[30:31]
	v_pk_mul_f32 v[28:29], v[136:137], v[28:29]

; DI float wave_sum(float v) {
;     v += __shfl_xor(v, 32); v += __shfl_xor(v, 16); v += __shfl_xor(v, 8); v += __shfl_xor(v, 4); v += __shfl_xor(v, 2); v += __shfl_xor(v, 1);
;     return v;
; }
; DI void norm_phase(const Params& p, int layer, int which, bool lat_only, const float* __restrict__ part, int npart, int srcmode) {
;     ...
;                 for (int j = 0; j < 4; ++j) ss[q] += v[q][j][0] * v[q][j][0] + v[q][j][1] * v[q][j][1] + v[q][j][2] * v[q][j][2] + v[q][j][3] * v[q][j][3];
;             }
;         }
;         ss[0] = wave_sum(ss[0]); ss[1] = wave_sum(ss[1]); ss[2] = wave_sum(ss[2]);
; #pragma unroll
;         for (int q = 0; q < 3; ++q) {
;             if (!ok[q]) continue;
;             const int row = r0 + 256 * q; const int ci = cond_idx(row);
;             if (ci != cur_ci) { cur_ci = ci; const float* mo = mod + (size_t)ci * 6144 + which * 3072;
; #pragma unroll
;                 for (int j = 0; j < 4; ++j) { const int col = j * 256 + lane * 4; gm[j] = *(const f32x4*)(gain + col) * (1.f + *(const f32x4*)(mo + 1024 + col)); sh[j] = *(const f32x4*)(mo + col); } }
.LBB0_976:
	s_or_b64 exec, exec, s[14:15]
	s_waitcnt vmcnt(7)
	v_mul_f32_e32 v104, v61, v61
	s_waitcnt vmcnt(6)
	v_mul_f32_e32 v105, v57, v57
	v_fmac_f32_e32 v104, v60, v60
	v_fmac_f32_e32 v105, v56, v56
	v_fmac_f32_e32 v104, v62, v62
	v_fmac_f32_e32 v105, v58, v58
	v_fmac_f32_e32 v104, v63, v63
	v_fmac_f32_e32 v105, v59, v59
	v_add_f32_e32 v104, v105, v104
	s_waitcnt vmcnt(5)
	v_mul_f32_e32 v105, v53, v53
	v_fmac_f32_e32 v105, v52, v52
	v_fmac_f32_e32 v105, v54, v54
	v_fmac_f32_e32 v105, v55, v55
	v_add_f32_e32 v104, v105, v104
	s_waitcnt vmcnt(4)
	v_mul_f32_e32 v105, v49, v49
	v_fmac_f32_e32 v105, v48, v48
	v_fmac_f32_e32 v105, v50, v50
	v_fmac_f32_e32 v105, v51, v51
	v_add_f32_e32 v104, v105, v104
	v_mul_f32_e32 v105, v45, v45
	v_mul_f32_e32 v106, v41, v41
	v_fmac_f32_e32 v105, v44, v44
	v_fmac_f32_e32 v106, v40, v40
	v_fmac_f32_e32 v105, v46, v46
	v_fmac_f32_e32 v106, v42, v42
	v_fmac_f32_e32 v105, v47, v47
	v_fmac_f32_e32 v106, v43, v43
	v_add_f32_e32 v105, v106, v105
	v_mul_f32_e32 v106, v37, v37
	v_fmac_f32_e32 v106, v36, v36
	v_fmac_f32_e32 v106, v38, v38
	v_fmac_f32_e32 v106, v39, v39
	v_add_f32_e32 v105, v106, v105
	v_mul_f32_e32 v106, v33, v33
	v_fmac_f32_e32 v106, v32, v32
	v_fmac_f32_e32 v106, v34, v34
	v_fmac_f32_e32 v106, v35, v35
	v_add_f32_e32 v105, v106, v105
	s_waitcnt vmcnt(3)
	v_mul_f32_e32 v106, v77, v77
	s_waitcnt vmcnt(2)
	v_mul_f32_e32 v107, v73, v73
	v_fmac_f32_e32 v106, v76, v76
	v_fmac_f32_e32 v107, v72, v72
	v_fmac_f32_e32 v106, v78, v78
	v_fmac_f32_e32 v107, v74, v74
	v_fmac_f32_e32 v106, v79, v79
	v_fmac_f32_e32 v107, v75, v75
	v_add_f32_e32 v106, v107, v106
	s_waitcnt vmcnt(1)
	v_mul_f32_e32 v107, v69, v69
	v_fmac_f32_e32 v107, v68, v68
	v_fmac_f32_e32 v107, v70, v70
	v_fmac_f32_e32 v107, v71, v71
	v_add_f32_e32 v106, v107, v106
	s_waitcnt vmcnt(0)
	v_mul_f32_e32 v107, v65, v65
	v_fmac_f32_e32 v107, v64, v64
	v_fmac_f32_e32 v107, v66, v66
	v_fmac_f32_e32 v107, v67, v67
	v_add_f32_e32 v106, v107, v106
	s_nop 0
	s_nop 0
	s_nop 0
	v_cndmask_b32_e64 v103, v103, 8, vcc
	v_cmp_ne_u32_e32 vcc, v103, v109
	s_waitcnt lgkmcnt(2)
	v_mov_b32_e32 v108, v105
	s_nop 1
	v_permlane32_swap_b32_e32 v105, v108
	v_add_f32_e32 v105, v105, v108
	s_waitcnt lgkmcnt(1)
	v_mov_b32_e32 v114, v104
	s_nop 1
	v_permlane32_swap_b32_e32 v104, v114
	v_add_f32_e32 v104, v104, v114
	s_waitcnt lgkmcnt(0)
	v_mov_b32_e32 v107, v106
	s_nop 1
	v_permlane32_swap_b32_e32 v106, v107
	v_add_f32_e32 v106, v106, v107
	ds_bpermute_b32 v108, v93, v105
	ds_bpermute_b32 v114, v93, v104
	ds_bpermute_b32 v107, v93, v106
	s_waitcnt lgkmcnt(2)
	v_add_f32_e32 v105, v105, v108
	s_waitcnt lgkmcnt(1)
	v_add_f32_e32 v104, v104, v114
	s_waitcnt lgkmcnt(0)
	v_add_f32_e32 v106, v106, v107
	s_nop 0
	s_nop 0
	s_nop 0
	s_waitcnt lgkmcnt(2)
	s_nop 1
	v_add_f32_dpp v105, v105, v105 row_ror:8 row_mask:0xf bank_mask:0xf
	s_waitcnt lgkmcnt(1)
	s_nop 1
	v_add_f32_dpp v104, v104, v104 row_ror:8 row_mask:0xf bank_mask:0xf
	s_waitcnt lgkmcnt(0)
	s_nop 1
	v_add_f32_dpp v106, v106, v106 row_ror:8 row_mask:0xf bank_mask:0xf
	s_nop 0
	s_nop 0
	s_nop 0
	s_waitcnt lgkmcnt(2)
	s_nop 1
	v_add_f32_dpp v105, v105, v105 row_ror:4 row_mask:0xf bank_mask:0xf
	s_waitcnt lgkmcnt(1)
	s_nop 1
	v_add_f32_dpp v104, v104, v104 row_ror:4 row_mask:0xf bank_mask:0xf
	s_waitcnt lgkmcnt(0)
	s_nop 1
	v_add_f32_dpp v106, v106, v106 row_ror:4 row_mask:0xf bank_mask:0xf
	s_nop 0
	s_nop 0
	s_nop 0
	s_waitcnt lgkmcnt(2)
	s_nop 1
	v_add_f32_dpp v118, v105, v105 row_ror:2 row_mask:0xf bank_mask:0xf
	s_waitcnt lgkmcnt(1)
	s_nop 1
	v_add_f32_dpp v116, v104, v104 row_ror:2 row_mask:0xf bank_mask:0xf
	s_waitcnt lgkmcnt(0)
	s_nop 1
	v_add_f32_dpp v114, v106, v106 row_ror:2 row_mask:0xf bank_mask:0xf
	ds_bpermute_b32 v119, v122, v118
	ds_bpermute_b32 v117, v122, v116
	ds_bpermute_b32 v115, v122, v114
	v_lshlrev_b32_e32 v108, 2, v88
	v_lshlrev_b32_e32 v106, 2, v92
	v_lshlrev_b32_e32 v104, 2, v96
	s_and_saveexec_b64 s[0:1], vcc
	s_cbranch_execz .LBB0_978
	v_mul_hi_i32_i24_e32 v1, 0x6000, v103
	v_mul_i32_i24_e32 v0, 0x6000, v103
	v_lshl_add_u64 v[0:1], s[10:11], 0, v[0:1]
	v_lshl_add_u64 v[2:3], v[0:1], 0, s[30:31]
	v_lshl_add_u64 v[4:5], v[2:3], 0, v[82:83]
	v_mov_b32_e32 v109, v83
	global_load_dwordx4 v[16:19], v[4:5], off
	v_lshl_add_u64 v[4:5], v[2:3], 0, v[108:109]
	v_mov_b32_e32 v107, v83
	global_load_dwordx4 v[20:23], v[4:5], off
	v_lshl_add_u64 v[4:5], v[2:3], 0, v[106:107]
	v_mov_b32_e32 v105, v83
	global_load_dwordx4 v[24:27], v[4:5], off
	v_lshl_add_u64 v[2:3], v[2:3], 0, v[104:105]
	global_load_dwordx4 v[28:31], v[2:3], off
	global_load_dwordx4 v[124:127], v[86:87], off
	global_load_dwordx4 v[128:131], v[90:91], off
	v_lshl_add_u64 v[12:13], v[0:1], 0, v[82:83]
	global_load_dwordx4 v[132:135], v[94:95], off
	global_load_dwordx4 v[0:3], v[12:13], off
	global_load_dwordx4 v[136:139], v[98:99], off
	global_load_dwordx4 v[4:7], v[12:13], off offset:1024
	global_load_dwordx4 v[8:11], v[12:13], off offset:2048
	s_nop 0
	global_load_dwordx4 v[12:15], v[12:13], off offset:3072
	v_mov_b32_e32 v109, v103
	s_waitcnt vmcnt(11)
	v_pk_add_f32 v[18:19], v[18:19], 1.0 op_sel_hi:[1,0]
	v_pk_add_f32 v[16:17], v[16:17], 1.0 op_sel_hi:[1,0]
	s_waitcnt vmcnt(10)
	v_pk_add_f32 v[22:23], v[22:23], 1.0 op_sel_hi:[1,0]
	v_pk_add_f32 v[20:21], v[20:21], 1.0 op_sel_hi:[1,0]
	s_waitcnt vmcnt(9)
	v_pk_add_f32 v[26:27], v[26:27], 1.0 op_sel_hi:[1,0]
	v_pk_add_f32 v[24:25], v[24:25], 1.0 op_sel_hi:[1,0]
	s_waitcnt vmcnt(8)
	v_pk_add_f32 v[30:31], v[30:31], 1.0 op_sel_hi:[1,0]
	v_pk_add_f32 v[28:29], v[28:29], 1.0 op_sel_hi:[1,0]
	s_waitcnt vmcnt(7)
	v_pk_mul_f32 v[18:19], v[126:127], v[18:19]
	v_pk_mul_f32 v[16:17], v[124:125], v[16:17]
	s_waitcnt vmcnt(6)
	v_pk_mul_f32 v[22:23], v[130:131], v[22:23]
	v_pk_mul_f32 v[20:21], v[128:129], v[20:21]
	s_waitcnt vmcnt(5)
	v_pk_mul_f32 v[26:27], v[134:135], v[26:27]
	v_pk_mul_f32 v[24:25], v[132:133], v[24:25]
	s_waitcnt vmcnt(3)
	v_pk_mul_f32 v[30:31], v[138:139], v[30:31]
	v_pk_mul_f32 v[28:29], v[136:137], v[28:29]

; DI float wave_sum(float v) {
;     v += __shfl_xor(v, 32); v += __shfl_xor(v, 16); v += __shfl_xor(v, 8); v += __shfl_xor(v, 4); v += __shfl_xor(v, 2); v += __shfl_xor(v, 1);
;     return v;
; }
; DI void norm_phase(const Params& p, int layer, int which, bool lat_only, const float* __restrict__ part, int npart, int srcmode) {
;     ...
;                 for (int j = 0; j < 4; ++j) ss[q] += v[q][j][0] * v[q][j][0] + v[q][j][1] * v[q][j][1] + v[q][j][2] * v[q][j][2] + v[q][j][3] * v[q][j][3];
;             }
;         }
;         ss[0] = wave_sum(ss[0]); ss[1] = wave_sum(ss[1]); ss[2] = wave_sum(ss[2]);
; #pragma unroll
;         for (int q = 0; q < 3; ++q) {
;             if (!ok[q]) continue;
;             const int row = r0 + 256 * q; const int ci = cond_idx(row);
;             if (ci != cur_ci) { cur_ci = ci; const float* mo = mod + (size_t)ci * 6144 + which * 3072;
; #pragma unroll
;                 for (int j = 0; j < 4; ++j) { const int col = j * 256 + lane * 4; gm[j] = *(const f32x4*)(gain + col) * (1.f + *(const f32x4*)(mo + 1024 + col)); sh[j] = *(const f32x4*)(mo + col); } }
.LBB0_1000:
	s_or_b64 exec, exec, s[14:15]
	s_waitcnt vmcnt(7)
	v_mul_f32_e32 v105, v61, v61
	s_waitcnt vmcnt(6)
	v_mul_f32_e32 v107, v57, v57
	v_fmac_f32_e32 v105, v60, v60
	v_fmac_f32_e32 v107, v56, v56
	v_fmac_f32_e32 v105, v62, v62
	v_fmac_f32_e32 v107, v58, v58
	v_fmac_f32_e32 v105, v63, v63
	v_fmac_f32_e32 v107, v59, v59
	v_add_f32_e32 v105, v107, v105
	s_waitcnt vmcnt(5)
	v_mul_f32_e32 v107, v53, v53
	v_fmac_f32_e32 v107, v52, v52
	v_fmac_f32_e32 v107, v54, v54
	v_fmac_f32_e32 v107, v55, v55
	v_add_f32_e32 v105, v107, v105
	s_waitcnt vmcnt(4)
	v_mul_f32_e32 v107, v49, v49
	v_fmac_f32_e32 v107, v48, v48
	v_fmac_f32_e32 v107, v50, v50
	v_fmac_f32_e32 v107, v51, v51
	v_add_f32_e32 v105, v107, v105
	v_mul_f32_e32 v107, v45, v45
	v_mul_f32_e32 v111, v41, v41
	v_fmac_f32_e32 v107, v44, v44
	v_fmac_f32_e32 v111, v40, v40
	v_fmac_f32_e32 v107, v46, v46
	v_fmac_f32_e32 v111, v42, v42
	v_fmac_f32_e32 v107, v47, v47
	v_fmac_f32_e32 v111, v43, v43
	v_add_f32_e32 v107, v111, v107
	v_mul_f32_e32 v111, v37, v37
	v_fmac_f32_e32 v111, v36, v36
	v_fmac_f32_e32 v111, v38, v38
	v_fmac_f32_e32 v111, v39, v39
	v_add_f32_e32 v107, v111, v107
	v_mul_f32_e32 v111, v33, v33
	v_fmac_f32_e32 v111, v32, v32
	v_fmac_f32_e32 v111, v34, v34
	v_fmac_f32_e32 v111, v35, v35
	v_add_f32_e32 v107, v111, v107
	s_waitcnt vmcnt(3)
	v_mul_f32_e32 v111, v77, v77
	s_waitcnt vmcnt(2)
	v_mul_f32_e32 v116, v73, v73
	v_fmac_f32_e32 v111, v76, v76
	v_fmac_f32_e32 v116, v72, v72
	v_fmac_f32_e32 v111, v78, v78
	v_fmac_f32_e32 v116, v74, v74
	v_fmac_f32_e32 v111, v79, v79
	v_fmac_f32_e32 v116, v75, v75
	v_add_f32_e32 v111, v116, v111
	s_waitcnt vmcnt(1)
	v_mul_f32_e32 v116, v69, v69
	v_fmac_f32_e32 v116, v68, v68
	v_fmac_f32_e32 v116, v70, v70
	v_fmac_f32_e32 v116, v71, v71
	v_add_f32_e32 v111, v116, v111
	s_waitcnt vmcnt(0)
	v_mul_f32_e32 v116, v65, v65
	v_fmac_f32_e32 v116, v64, v64
	v_fmac_f32_e32 v116, v66, v66
	v_fmac_f32_e32 v116, v67, v67
	v_add_f32_e32 v111, v116, v111
	s_nop 0
	s_nop 0
	s_nop 0
	v_cndmask_b32_e64 v103, v103, 8, vcc
	v_cmp_ne_u32_e32 vcc, v103, v109
	s_waitcnt lgkmcnt(2)
	v_mov_b32_e32 v117, v107
	s_nop 1
	v_permlane32_swap_b32_e32 v107, v117
	v_add_f32_e32 v107, v107, v117
	s_waitcnt lgkmcnt(1)
	v_mov_b32_e32 v118, v105
	s_nop 1
	v_permlane32_swap_b32_e32 v105, v118
	v_add_f32_e32 v105, v105, v118
	s_waitcnt lgkmcnt(0)
	v_mov_b32_e32 v116, v111
	s_nop 1
	v_permlane32_swap_b32_e32 v111, v116
	v_add_f32_e32 v111, v111, v116
	ds_bpermute_b32 v117, v93, v107
	ds_bpermute_b32 v118, v93, v105
	ds_bpermute_b32 v116, v93, v111
	s_waitcnt lgkmcnt(2)
	v_add_f32_e32 v107, v107, v117
	s_waitcnt lgkmcnt(1)
	v_add_f32_e32 v105, v105, v118
	s_waitcnt lgkmcnt(0)
	v_add_f32_e32 v111, v111, v116
	s_nop 0
	s_nop 0
	s_nop 0
	s_waitcnt lgkmcnt(2)
	s_nop 1
	v_add_f32_dpp v107, v107, v107 row_ror:8 row_mask:0xf bank_mask:0xf
	s_waitcnt lgkmcnt(1)
	s_nop 1
	v_add_f32_dpp v105, v105, v105 row_ror:8 row_mask:0xf bank_mask:0xf
	s_waitcnt lgkmcnt(0)
	s_nop 1
	v_add_f32_dpp v111, v111, v111 row_ror:8 row_mask:0xf bank_mask:0xf
	s_nop 0
	s_nop 0
	s_nop 0
	s_waitcnt lgkmcnt(2)
	s_nop 1
	v_add_f32_dpp v107, v107, v107 row_ror:4 row_mask:0xf bank_mask:0xf
	s_waitcnt lgkmcnt(1)
	s_nop 1
	v_add_f32_dpp v105, v105, v105 row_ror:4 row_mask:0xf bank_mask:0xf
	s_waitcnt lgkmcnt(0)
	s_nop 1
	v_add_f32_dpp v116, v111, v111 row_ror:4 row_mask:0xf bank_mask:0xf
	s_nop 0
	s_nop 0
	s_nop 0
	s_waitcnt lgkmcnt(2)
	s_nop 1
	v_add_f32_dpp v111, v107, v107 row_ror:2 row_mask:0xf bank_mask:0xf
	s_waitcnt lgkmcnt(1)
	s_nop 1
	v_add_f32_dpp v118, v105, v105 row_ror:2 row_mask:0xf bank_mask:0xf
	s_waitcnt lgkmcnt(0)
	s_nop 1
	v_add_f32_dpp v116, v116, v116 row_ror:2 row_mask:0xf bank_mask:0xf
	ds_bpermute_b32 v124, v122, v111
	ds_bpermute_b32 v119, v122, v118
	ds_bpermute_b32 v117, v122, v116
	s_and_saveexec_b64 s[0:1], vcc
	s_cbranch_execz .LBB0_1002
	v_mul_hi_i32_i24_e32 v1, 0x6000, v103
	v_mul_i32_i24_e32 v0, 0x6000, v103
	v_lshl_add_u64 v[0:1], s[10:11], 0, v[0:1]
	v_lshl_add_u64 v[2:3], v[0:1], 0, s[30:31]
	v_lshl_add_u64 v[4:5], v[2:3], 0, v[82:83]
	v_mov_b32_e32 v109, v83
	global_load_dwordx4 v[16:19], v[4:5], off
	v_lshl_add_u64 v[4:5], v[2:3], 0, v[108:109]
	v_mov_b32_e32 v107, v83
	global_load_dwordx4 v[20:23], v[4:5], off
	v_lshl_add_u64 v[4:5], v[2:3], 0, v[106:107]
	v_mov_b32_e32 v105, v83
	global_load_dwordx4 v[24:27], v[4:5], off
	v_lshl_add_u64 v[2:3], v[2:3], 0, v[104:105]
	global_load_dwordx4 v[28:31], v[2:3], off
	global_load_dwordx4 v[126:129], v[86:87], off
	global_load_dwordx4 v[130:133], v[90:91], off
	v_lshl_add_u64 v[12:13], v[0:1], 0, v[82:83]
	global_load_dwordx4 v[134:137], v[94:95], off
	global_load_dwordx4 v[0:3], v[12:13], off
	global_load_dwordx4 v[138:141], v[98:99], off
	global_load_dwordx4 v[4:7], v[12:13], off offset:1024
	global_load_dwordx4 v[8:11], v[12:13], off offset:2048
	s_nop 0
	global_load_dwordx4 v[12:15], v[12:13], off offset:3072
	v_mov_b32_e32 v109, v103
	s_waitcnt vmcnt(11)
	v_pk_add_f32 v[18:19], v[18:19], 1.0 op_sel_hi:[1,0]
	v_pk_add_f32 v[16:17], v[16:17], 1.0 op_sel_hi:[1,0]
	s_waitcnt vmcnt(10)
	v_pk_add_f32 v[22:23], v[22:23], 1.0 op_sel_hi:[1,0]
	v_pk_add_f32 v[20:21], v[20:21], 1.0 op_sel_hi:[1,0]
	s_waitcnt vmcnt(9)
	v_pk_add_f32 v[26:27], v[26:27], 1.0 op_sel_hi:[1,0]
	v_pk_add_f32 v[24:25], v[24:25], 1.0 op_sel_hi:[1,0]
	s_waitcnt vmcnt(8)
	v_pk_add_f32 v[30:31], v[30:31], 1.0 op_sel_hi:[1,0]
	v_pk_add_f32 v[28:29], v[28:29], 1.0 op_sel_hi:[1,0]
	s_waitcnt vmcnt(7)
	v_pk_mul_f32 v[18:19], v[128:129], v[18:19]
	v_pk_mul_f32 v[16:17], v[126:127], v[16:17]
	s_waitcnt vmcnt(6)
	v_pk_mul_f32 v[22:23], v[132:133], v[22:23]
	v_pk_mul_f32 v[20:21], v[130:131], v[20:21]
	s_waitcnt vmcnt(5)
	v_pk_mul_f32 v[26:27], v[136:137], v[26:27]
	v_pk_mul_f32 v[24:25], v[134:135], v[24:25]
	s_waitcnt vmcnt(3)
	v_pk_mul_f32 v[30:31], v[140:141], v[30:31]
	v_pk_mul_f32 v[28:29], v[138:139], v[28:29]

; DI float wave_sum(float v) {
;     v += __shfl_xor(v, 32); v += __shfl_xor(v, 16); v += __shfl_xor(v, 8); v += __shfl_xor(v, 4); v += __shfl_xor(v, 2); v += __shfl_xor(v, 1);
;     return v;
; DI void norm_phase(const Params& p, int layer, int which, bool lat_only, const float* __restrict__ part, int npart, int srcmode) {
;     ...
;                 for (int j = 0; j < 4; ++j) ss[q] += v[q][j][0] * v[q][j][0] + v[q][j][1] * v[q][j][1] + v[q][j][2] * v[q][j][2] + v[q][j][3] * v[q][j][3];
;             }
;         }
;         ss[0] = wave_sum(ss[0]); ss[1] = wave_sum(ss[1]); ss[2] = wave_sum(ss[2]);
; #pragma unroll
;         for (int q = 0; q < 3; ++q) {
;             if (!ok[q]) continue;
;             const int row = r0 + 256 * q; const int ci = cond_idx(row);
;             if (ci != cur_ci) { cur_ci = ci; const float* mo = mod + (size_t)ci * 6144 + which * 3072;
; #pragma unroll
;                 for (int j = 0; j < 4; ++j) { const int col = j * 256 + lane * 4; gm[j] = *(const f32x4*)(gain + col) * (1.f + *(const f32x4*)(mo + 1024 + col)); sh[j] = *(const f32x4*)(mo + col); } }
.LBB0_1024:
	s_or_b64 exec, exec, s[14:15]
	s_waitcnt vmcnt(7)
	v_mul_f32_e32 v105, v61, v61
	s_waitcnt vmcnt(6)
	v_mul_f32_e32 v107, v57, v57
	v_fmac_f32_e32 v105, v60, v60
	v_fmac_f32_e32 v107, v56, v56
	v_fmac_f32_e32 v105, v62, v62
	v_fmac_f32_e32 v107, v58, v58
	v_fmac_f32_e32 v105, v63, v63
	v_fmac_f32_e32 v107, v59, v59
	v_add_f32_e32 v105, v107, v105
	s_waitcnt vmcnt(5)
	v_mul_f32_e32 v107, v53, v53
	v_fmac_f32_e32 v107, v52, v52
	v_fmac_f32_e32 v107, v54, v54
	v_fmac_f32_e32 v107, v55, v55
	v_add_f32_e32 v105, v107, v105
	s_waitcnt vmcnt(4)
	v_mul_f32_e32 v107, v49, v49
	v_fmac_f32_e32 v107, v48, v48
	v_fmac_f32_e32 v107, v50, v50
	v_fmac_f32_e32 v107, v51, v51
	v_add_f32_e32 v105, v107, v105
	v_mul_f32_e32 v107, v45, v45
	v_mul_f32_e32 v111, v41, v41
	v_fmac_f32_e32 v107, v44, v44
	v_fmac_f32_e32 v111, v40, v40
	v_fmac_f32_e32 v107, v46, v46
	v_fmac_f32_e32 v111, v42, v42
	v_fmac_f32_e32 v107, v47, v47
	v_fmac_f32_e32 v111, v43, v43
	v_add_f32_e32 v107, v111, v107
	v_mul_f32_e32 v111, v37, v37
	v_fmac_f32_e32 v111, v36, v36
	v_fmac_f32_e32 v111, v38, v38
	v_fmac_f32_e32 v111, v39, v39
	v_add_f32_e32 v107, v111, v107
	v_mul_f32_e32 v111, v33, v33
	v_fmac_f32_e32 v111, v32, v32
	v_fmac_f32_e32 v111, v34, v34
	v_fmac_f32_e32 v111, v35, v35
	v_add_f32_e32 v107, v111, v107
	s_waitcnt vmcnt(3)
	v_mul_f32_e32 v111, v77, v77
	s_waitcnt vmcnt(2)
	v_mul_f32_e32 v114, v73, v73
	v_fmac_f32_e32 v111, v76, v76
	v_fmac_f32_e32 v114, v72, v72
	v_fmac_f32_e32 v111, v78, v78
	v_fmac_f32_e32 v114, v74, v74
	v_fmac_f32_e32 v111, v79, v79
	v_fmac_f32_e32 v114, v75, v75
	v_add_f32_e32 v111, v114, v111
	s_waitcnt vmcnt(1)
	v_mul_f32_e32 v114, v69, v69
	v_fmac_f32_e32 v114, v68, v68
	v_fmac_f32_e32 v114, v70, v70
	v_fmac_f32_e32 v114, v71, v71
	v_add_f32_e32 v111, v114, v111
	s_waitcnt vmcnt(0)
	v_mul_f32_e32 v114, v65, v65
	v_fmac_f32_e32 v114, v64, v64
	v_fmac_f32_e32 v114, v66, v66
	v_fmac_f32_e32 v114, v67, v67
	v_add_f32_e32 v111, v114, v111
	s_nop 0
	s_nop 0
	s_nop 0
	v_cndmask_b32_e64 v103, v103, 8, vcc
	v_cmp_ne_u32_e32 vcc, v103, v109
	s_waitcnt lgkmcnt(2)
	v_mov_b32_e32 v115, v107
	s_nop 1
	v_permlane32_swap_b32_e32 v107, v115
	v_add_f32_e32 v107, v107, v115
	s_waitcnt lgkmcnt(1)
	v_mov_b32_e32 v116, v105
	s_nop 1
	v_permlane32_swap_b32_e32 v105, v116
	v_add_f32_e32 v105, v105, v116
	s_waitcnt lgkmcnt(0)
	v_mov_b32_e32 v114, v111
	s_nop 1
	v_permlane32_swap_b32_e32 v111, v114
	v_add_f32_e32 v111, v111, v114
	ds_bpermute_b32 v115, v93, v107
	ds_bpermute_b32 v116, v93, v105
	ds_bpermute_b32 v114, v93, v111
	s_waitcnt lgkmcnt(2)
	v_add_f32_e32 v107, v107, v115
	s_waitcnt lgkmcnt(1)
	v_add_f32_e32 v105, v105, v116
	s_waitcnt lgkmcnt(0)
	v_add_f32_e32 v111, v111, v114
	s_nop 0
	s_nop 0
	s_nop 0
	s_waitcnt lgkmcnt(2)
	s_nop 1
	v_add_f32_dpp v107, v107, v107 row_ror:8 row_mask:0xf bank_mask:0xf
	s_waitcnt lgkmcnt(1)
	s_nop 1
	v_add_f32_dpp v105, v105, v105 row_ror:8 row_mask:0xf bank_mask:0xf
	s_waitcnt lgkmcnt(0)
	s_nop 1
	v_add_f32_dpp v111, v111, v111 row_ror:8 row_mask:0xf bank_mask:0xf
	s_nop 0
	s_nop 0
	s_nop 0
	s_waitcnt lgkmcnt(2)
	s_nop 1
	v_add_f32_dpp v107, v107, v107 row_ror:4 row_mask:0xf bank_mask:0xf
	s_waitcnt lgkmcnt(1)
	s_nop 1
	v_add_f32_dpp v105, v105, v105 row_ror:4 row_mask:0xf bank_mask:0xf
	s_waitcnt lgkmcnt(0)
	s_nop 1
	v_add_f32_dpp v114, v111, v111 row_ror:4 row_mask:0xf bank_mask:0xf
	s_nop 0
	s_nop 0
	s_nop 0
	s_waitcnt lgkmcnt(2)
	s_nop 1
	v_add_f32_dpp v111, v107, v107 row_ror:2 row_mask:0xf bank_mask:0xf
	s_waitcnt lgkmcnt(1)
	s_nop 1
	v_add_f32_dpp v116, v105, v105 row_ror:2 row_mask:0xf bank_mask:0xf
	s_waitcnt lgkmcnt(0)
	s_nop 1
	v_add_f32_dpp v114, v114, v114 row_ror:2 row_mask:0xf bank_mask:0xf
	ds_bpermute_b32 v119, v122, v111
	ds_bpermute_b32 v117, v122, v116
	ds_bpermute_b32 v115, v122, v114
	s_and_saveexec_b64 s[0:1], vcc
	s_cbranch_execz .LBB0_1026
	v_mul_hi_i32_i24_e32 v1, 0x6000, v103
	v_mul_i32_i24_e32 v0, 0x6000, v103
	v_lshl_add_u64 v[0:1], s[10:11], 0, v[0:1]
	v_lshl_add_u64 v[2:3], v[0:1], 0, s[30:31]
	v_lshl_add_u64 v[4:5], v[2:3], 0, v[82:83]
	v_mov_b32_e32 v109, v83
	global_load_dwordx4 v[16:19], v[4:5], off
	v_lshl_add_u64 v[4:5], v[2:3], 0, v[108:109]
	v_mov_b32_e32 v107, v83
	global_load_dwordx4 v[20:23], v[4:5], off
	v_lshl_add_u64 v[4:5], v[2:3], 0, v[106:107]
	v_mov_b32_e32 v105, v83
	global_load_dwordx4 v[24:27], v[4:5], off
	v_lshl_add_u64 v[2:3], v[2:3], 0, v[104:105]
	global_load_dwordx4 v[28:31], v[2:3], off
	global_load_dwordx4 v[124:127], v[86:87], off
	global_load_dwordx4 v[128:131], v[90:91], off
	v_lshl_add_u64 v[12:13], v[0:1], 0, v[82:83]
	global_load_dwordx4 v[132:135], v[94:95], off
	global_load_dwordx4 v[0:3], v[12:13], off
	global_load_dwordx4 v[136:139], v[98:99], off
	global_load_dwordx4 v[4:7], v[12:13], off offset:1024
	global_load_dwordx4 v[8:11], v[12:13], off offset:2048
	s_nop 0
	global_load_dwordx4 v[12:15], v[12:13], off offset:3072
	v_mov_b32_e32 v109, v103
	s_waitcnt vmcnt(11)
	v_pk_add_f32 v[18:19], v[18:19], 1.0 op_sel_hi:[1,0]
	v_pk_add_f32 v[16:17], v[16:17], 1.0 op_sel_hi:[1,0]
	s_waitcnt vmcnt(10)
	v_pk_add_f32 v[22:23], v[22:23], 1.0 op_sel_hi:[1,0]
	v_pk_add_f32 v[20:21], v[20:21], 1.0 op_sel_hi:[1,0]
	s_waitcnt vmcnt(9)
	v_pk_add_f32 v[26:27], v[26:27], 1.0 op_sel_hi:[1,0]
	v_pk_add_f32 v[24:25], v[24:25], 1.0 op_sel_hi:[1,0]
	s_waitcnt vmcnt(8)
	v_pk_add_f32 v[30:31], v[30:31], 1.0 op_sel_hi:[1,0]
	v_pk_add_f32 v[28:29], v[28:29], 1.0 op_sel_hi:[1,0]
	s_waitcnt vmcnt(7)
	v_pk_mul_f32 v[18:19], v[126:127], v[18:19]
	v_pk_mul_f32 v[16:17], v[124:125], v[16:17]
	s_waitcnt vmcnt(6)
	v_pk_mul_f32 v[22:23], v[130:131], v[22:23]
	v_pk_mul_f32 v[20:21], v[128:129], v[20:21]
	s_waitcnt vmcnt(5)
	v_pk_mul_f32 v[26:27], v[134:135], v[26:27]
	v_pk_mul_f32 v[24:25], v[132:133], v[24:25]
	s_waitcnt vmcnt(3)
	v_pk_mul_f32 v[30:31], v[138:139], v[30:31]
	v_pk_mul_f32 v[28:29], v[136:137], v[28:29]

; DI float wave_sum(float v) {
;     v += __shfl_xor(v, 32); v += __shfl_xor(v, 16); v += __shfl_xor(v, 8); v += __shfl_xor(v, 4); v += __shfl_xor(v, 2); v += __shfl_xor(v, 1);
;     return v;
; DI void norm_phase(const Params& p, int layer, int which, bool lat_only, const float* __restrict__ part, int npart, int srcmode) {
;     ...
;                 for (int j = 0; j < 4; ++j) ss[q] += v[q][j][0] * v[q][j][0] + v[q][j][1] * v[q][j][1] + v[q][j][2] * v[q][j][2] + v[q][j][3] * v[q][j][3];
;             }
;         }
;         ss[0] = wave_sum(ss[0]); ss[1] = wave_sum(ss[1]); ss[2] = wave_sum(ss[2]);
; #pragma unroll
;         for (int q = 0; q < 3; ++q) {
;             if (!ok[q]) continue;
;             const int row = r0 + 256 * q; const int ci = cond_idx(row);
;             if (ci != cur_ci) { cur_ci = ci; const float* mo = mod + (size_t)ci * 6144 + which * 3072;
; #pragma unroll
;                 for (int j = 0; j < 4; ++j) { const int col = j * 256 + lane * 4; gm[j] = *(const f32x4*)(gain + col) * (1.f + *(const f32x4*)(mo + 1024 + col)); sh[j] = *(const f32x4*)(mo + col); } }
.LBB0_1579:
	s_or_b64 exec, exec, s[14:15]
	s_waitcnt vmcnt(7)
	v_mul_f32_e32 v102, v69, v69
	s_waitcnt vmcnt(6)
	v_mul_f32_e32 v103, v61, v61
	v_fmac_f32_e32 v102, v68, v68
	v_fmac_f32_e32 v103, v60, v60
	v_fmac_f32_e32 v102, v70, v70
	v_fmac_f32_e32 v103, v62, v62
	v_fmac_f32_e32 v102, v71, v71
	v_fmac_f32_e32 v103, v63, v63
	v_add_f32_e32 v102, v103, v102
	s_waitcnt vmcnt(5)
	v_mul_f32_e32 v103, v49, v49
	v_fmac_f32_e32 v103, v48, v48
	v_fmac_f32_e32 v103, v50, v50
	v_fmac_f32_e32 v103, v51, v51
	v_add_f32_e32 v102, v103, v102
	s_waitcnt vmcnt(4)
	v_mul_f32_e32 v103, v41, v41
	v_fmac_f32_e32 v103, v40, v40
	v_fmac_f32_e32 v103, v42, v42
	v_fmac_f32_e32 v103, v43, v43
	v_add_f32_e32 v102, v103, v102
	v_mul_f32_e32 v103, v57, v57
	v_mul_f32_e32 v104, v45, v45
	v_fmac_f32_e32 v103, v56, v56
	v_fmac_f32_e32 v104, v44, v44
	v_fmac_f32_e32 v103, v58, v58
	v_fmac_f32_e32 v104, v46, v46
	v_fmac_f32_e32 v103, v59, v59
	v_fmac_f32_e32 v104, v47, v47
	v_add_f32_e32 v103, v104, v103
	v_mul_f32_e32 v104, v37, v37
	v_fmac_f32_e32 v104, v36, v36
	v_fmac_f32_e32 v104, v38, v38
	v_fmac_f32_e32 v104, v39, v39
	v_add_f32_e32 v103, v104, v103
	v_mul_f32_e32 v104, v33, v33
	v_fmac_f32_e32 v104, v32, v32
	v_fmac_f32_e32 v104, v34, v34
	v_fmac_f32_e32 v104, v35, v35
	v_add_f32_e32 v103, v104, v103
	s_waitcnt vmcnt(3)
	v_mul_f32_e32 v104, v77, v77
	s_waitcnt vmcnt(2)
	v_mul_f32_e32 v105, v73, v73
	v_fmac_f32_e32 v104, v76, v76
	v_fmac_f32_e32 v105, v72, v72
	v_fmac_f32_e32 v104, v78, v78
	v_fmac_f32_e32 v105, v74, v74
	v_fmac_f32_e32 v104, v79, v79
	v_fmac_f32_e32 v105, v75, v75
	v_add_f32_e32 v104, v105, v104
	s_waitcnt vmcnt(1)
	v_mul_f32_e32 v105, v65, v65
	v_fmac_f32_e32 v105, v64, v64
	v_fmac_f32_e32 v105, v66, v66
	v_fmac_f32_e32 v105, v67, v67
	v_add_f32_e32 v104, v105, v104
	s_waitcnt vmcnt(0)
	v_mul_f32_e32 v105, v53, v53
	v_fmac_f32_e32 v105, v52, v52
	v_fmac_f32_e32 v105, v54, v54
	v_fmac_f32_e32 v105, v55, v55
	v_add_f32_e32 v104, v105, v104
	s_nop 0
	s_nop 0
	s_nop 0
	v_cndmask_b32_e64 v119, v106, 8, vcc
	v_cmp_ne_u32_e32 vcc, v119, v107
	s_waitcnt lgkmcnt(2)
	v_mov_b32_e32 v109, v103
	s_nop 1
	v_permlane32_swap_b32_e32 v103, v109
	v_add_f32_e32 v103, v103, v109
	s_waitcnt lgkmcnt(1)
	v_mov_b32_e32 v114, v102
	s_nop 1
	v_permlane32_swap_b32_e32 v102, v114
	v_add_f32_e32 v102, v102, v114
	s_waitcnt lgkmcnt(0)
	v_mov_b32_e32 v105, v104
	s_nop 1
	v_permlane32_swap_b32_e32 v104, v105
	v_add_f32_e32 v104, v104, v105
	ds_bpermute_b32 v109, v93, v103
	ds_bpermute_b32 v114, v93, v102
	ds_bpermute_b32 v105, v93, v104
	v_lshlrev_b32_e32 v106, 2, v88
	s_waitcnt lgkmcnt(2)
	v_add_f32_e32 v103, v103, v109
	s_waitcnt lgkmcnt(1)
	v_add_f32_e32 v102, v102, v114
	s_waitcnt lgkmcnt(0)
	v_add_f32_e32 v104, v104, v105
	s_nop 0
	s_nop 0
	s_nop 0
	s_waitcnt lgkmcnt(2)
	s_nop 1
	v_add_f32_dpp v103, v103, v103 row_ror:8 row_mask:0xf bank_mask:0xf
	s_waitcnt lgkmcnt(1)
	s_nop 1
	v_add_f32_dpp v102, v102, v102 row_ror:8 row_mask:0xf bank_mask:0xf
	s_waitcnt lgkmcnt(0)
	s_nop 1
	v_add_f32_dpp v104, v104, v104 row_ror:8 row_mask:0xf bank_mask:0xf
	s_nop 0
	s_nop 0
	s_nop 0
	s_waitcnt lgkmcnt(2)
	s_nop 1
	v_add_f32_dpp v103, v103, v103 row_ror:4 row_mask:0xf bank_mask:0xf
	s_waitcnt lgkmcnt(1)
	s_nop 1
	v_add_f32_dpp v102, v102, v102 row_ror:4 row_mask:0xf bank_mask:0xf
	s_waitcnt lgkmcnt(0)
	s_nop 1
	v_add_f32_dpp v104, v104, v104 row_ror:4 row_mask:0xf bank_mask:0xf
	s_nop 0
	s_nop 0
	s_nop 0
	s_waitcnt lgkmcnt(2)
	s_nop 1
	v_add_f32_dpp v109, v103, v103 row_ror:2 row_mask:0xf bank_mask:0xf
	s_waitcnt lgkmcnt(1)
	s_nop 1
	v_add_f32_dpp v116, v102, v102 row_ror:2 row_mask:0xf bank_mask:0xf
	s_waitcnt lgkmcnt(0)
	s_nop 1
	v_add_f32_dpp v114, v104, v104 row_ror:2 row_mask:0xf bank_mask:0xf
	ds_bpermute_b32 v118, v122, v109
	ds_bpermute_b32 v117, v122, v116
	ds_bpermute_b32 v115, v122, v114
	v_lshlrev_b32_e32 v104, 2, v92
	v_lshlrev_b32_e32 v102, 2, v96
	s_and_saveexec_b64 s[0:1], vcc
	s_cbranch_execz .LBB0_1581
	v_mul_hi_i32_i24_e32 v1, 0x6000, v119
	v_mul_i32_i24_e32 v0, 0x6000, v119
	v_lshl_add_u64 v[0:1], s[10:11], 0, v[0:1]
	v_lshl_add_u64 v[2:3], v[0:1], 0, s[30:31]
	v_lshl_add_u64 v[4:5], v[2:3], 0, v[82:83]
	v_mov_b32_e32 v107, v83
	global_load_dwordx4 v[16:19], v[4:5], off
	v_lshl_add_u64 v[4:5], v[2:3], 0, v[106:107]
	v_mov_b32_e32 v105, v83
	global_load_dwordx4 v[20:23], v[4:5], off
	v_lshl_add_u64 v[4:5], v[2:3], 0, v[104:105]
	v_mov_b32_e32 v103, v83
	global_load_dwordx4 v[24:27], v[4:5], off
	v_lshl_add_u64 v[2:3], v[2:3], 0, v[102:103]
	global_load_dwordx4 v[28:31], v[2:3], off
	global_load_dwordx4 v[124:127], v[86:87], off
	global_load_dwordx4 v[128:131], v[90:91], off
	v_lshl_add_u64 v[12:13], v[0:1], 0, v[82:83]
	global_load_dwordx4 v[132:135], v[94:95], off
	global_load_dwordx4 v[0:3], v[12:13], off
	global_load_dwordx4 v[136:139], v[98:99], off
	global_load_dwordx4 v[4:7], v[12:13], off offset:1024
	global_load_dwordx4 v[8:11], v[12:13], off offset:2048
	s_nop 0
	global_load_dwordx4 v[12:15], v[12:13], off offset:3072
	v_mov_b32_e32 v107, v119
	s_waitcnt vmcnt(11)
	v_pk_add_f32 v[18:19], v[18:19], 1.0 op_sel_hi:[1,0]
	v_pk_add_f32 v[16:17], v[16:17], 1.0 op_sel_hi:[1,0]
	s_waitcnt vmcnt(10)
	v_pk_add_f32 v[22:23], v[22:23], 1.0 op_sel_hi:[1,0]
	v_pk_add_f32 v[20:21], v[20:21], 1.0 op_sel_hi:[1,0]
	s_waitcnt vmcnt(9)
	v_pk_add_f32 v[26:27], v[26:27], 1.0 op_sel_hi:[1,0]
	v_pk_add_f32 v[24:25], v[24:25], 1.0 op_sel_hi:[1,0]
	s_waitcnt vmcnt(8)
	v_pk_add_f32 v[30:31], v[30:31], 1.0 op_sel_hi:[1,0]
	v_pk_add_f32 v[28:29], v[28:29], 1.0 op_sel_hi:[1,0]
	s_waitcnt vmcnt(7)
	v_pk_mul_f32 v[18:19], v[126:127], v[18:19]
	v_pk_mul_f32 v[16:17], v[124:125], v[16:17]
	s_waitcnt vmcnt(6)
	v_pk_mul_f32 v[22:23], v[130:131], v[22:23]
	v_pk_mul_f32 v[20:21], v[128:129], v[20:21]
	s_waitcnt vmcnt(5)
	v_pk_mul_f32 v[26:27], v[134:135], v[26:27]
	v_pk_mul_f32 v[24:25], v[132:133], v[24:25]
	s_waitcnt vmcnt(3)
	v_pk_mul_f32 v[30:31], v[138:139], v[30:31]
	v_pk_mul_f32 v[28:29], v[136:137], v[28:29]

; DI float wave_sum(float v) {
;     v += __shfl_xor(v, 32); v += __shfl_xor(v, 16); v += __shfl_xor(v, 8); v += __shfl_xor(v, 4); v += __shfl_xor(v, 2); v += __shfl_xor(v, 1);
;     return v;
; DI void norm_phase(const Params& p, int layer, int which, bool lat_only, const float* __restrict__ part, int npart, int srcmode) {
;     ...
;                 for (int j = 0; j < 4; ++j) ss[q] += v[q][j][0] * v[q][j][0] + v[q][j][1] * v[q][j][1] + v[q][j][2] * v[q][j][2] + v[q][j][3] * v[q][j][3];
;             }
;         }
;         ss[0] = wave_sum(ss[0]); ss[1] = wave_sum(ss[1]); ss[2] = wave_sum(ss[2]);
; #pragma unroll
;         for (int q = 0; q < 3; ++q) {
;             if (!ok[q]) continue;
;             const int row = r0 + 256 * q; const int ci = cond_idx(row);
;             if (ci != cur_ci) { cur_ci = ci; const float* mo = mod + (size_t)ci * 6144 + which * 3072;
; #pragma unroll
;                 for (int j = 0; j < 4; ++j) { const int col = j * 256 + lane * 4; gm[j] = *(const f32x4*)(gain + col) * (1.f + *(const f32x4*)(mo + 1024 + col)); sh[j] = *(const f32x4*)(mo + col); } }
.LBB0_1603:
	s_or_b64 exec, exec, s[14:15]
	s_waitcnt vmcnt(7)
	v_mul_f32_e32 v105, v69, v69
	s_waitcnt vmcnt(6)
	v_mul_f32_e32 v111, v61, v61
	v_fmac_f32_e32 v105, v68, v68
	v_fmac_f32_e32 v111, v60, v60
	v_fmac_f32_e32 v105, v70, v70
	v_fmac_f32_e32 v111, v62, v62
	v_fmac_f32_e32 v105, v71, v71
	v_fmac_f32_e32 v111, v63, v63
	v_add_f32_e32 v105, v111, v105
	s_waitcnt vmcnt(5)
	v_mul_f32_e32 v111, v49, v49
	v_fmac_f32_e32 v111, v48, v48
	v_fmac_f32_e32 v111, v50, v50
	v_fmac_f32_e32 v111, v51, v51
	v_add_f32_e32 v105, v111, v105
	s_waitcnt vmcnt(4)
	v_mul_f32_e32 v111, v41, v41
	v_fmac_f32_e32 v111, v40, v40
	v_fmac_f32_e32 v111, v42, v42
	v_fmac_f32_e32 v111, v43, v43
	v_add_f32_e32 v105, v111, v105
	v_mul_f32_e32 v111, v57, v57
	v_mul_f32_e32 v113, v45, v45
	v_fmac_f32_e32 v111, v56, v56
	v_fmac_f32_e32 v113, v44, v44
	v_fmac_f32_e32 v111, v58, v58
	v_fmac_f32_e32 v113, v46, v46
	v_fmac_f32_e32 v111, v59, v59
	v_fmac_f32_e32 v113, v47, v47
	v_add_f32_e32 v111, v113, v111
	v_mul_f32_e32 v113, v37, v37
	v_fmac_f32_e32 v113, v36, v36
	v_fmac_f32_e32 v113, v38, v38
	v_fmac_f32_e32 v113, v39, v39
	v_add_f32_e32 v111, v113, v111
	v_mul_f32_e32 v113, v33, v33
	v_fmac_f32_e32 v113, v32, v32
	v_fmac_f32_e32 v113, v34, v34
	v_fmac_f32_e32 v113, v35, v35
	v_add_f32_e32 v111, v113, v111
	s_waitcnt vmcnt(3)
	v_mul_f32_e32 v113, v77, v77
	s_waitcnt vmcnt(2)
	v_mul_f32_e32 v116, v73, v73
	v_fmac_f32_e32 v113, v76, v76
	v_fmac_f32_e32 v116, v72, v72
	v_fmac_f32_e32 v113, v78, v78
	v_fmac_f32_e32 v116, v74, v74
	v_fmac_f32_e32 v113, v79, v79
	v_fmac_f32_e32 v116, v75, v75
	v_add_f32_e32 v113, v116, v113
	s_waitcnt vmcnt(1)
	v_mul_f32_e32 v116, v65, v65
	v_fmac_f32_e32 v116, v64, v64
	v_fmac_f32_e32 v116, v66, v66
	v_fmac_f32_e32 v116, v67, v67
	v_add_f32_e32 v113, v116, v113
	s_waitcnt vmcnt(0)
	v_mul_f32_e32 v116, v53, v53
	v_fmac_f32_e32 v116, v52, v52
	v_fmac_f32_e32 v116, v54, v54
	v_fmac_f32_e32 v116, v55, v55
	v_add_f32_e32 v113, v116, v113
	s_nop 0
	s_nop 0
	s_nop 0
	s_waitcnt lgkmcnt(2)
	v_mov_b32_e32 v117, v111
	s_nop 1
	v_permlane32_swap_b32_e32 v111, v117
	v_add_f32_e32 v111, v111, v117
	s_waitcnt lgkmcnt(1)
	v_mov_b32_e32 v118, v105
	s_nop 1
	v_permlane32_swap_b32_e32 v105, v118
	v_add_f32_e32 v105, v105, v118
	s_waitcnt lgkmcnt(0)
	v_mov_b32_e32 v116, v113
	s_nop 1
	v_permlane32_swap_b32_e32 v113, v116
	v_add_f32_e32 v113, v113, v116
	ds_bpermute_b32 v117, v93, v111
	ds_bpermute_b32 v118, v93, v105
	ds_bpermute_b32 v116, v93, v113
	s_waitcnt lgkmcnt(2)
	v_add_f32_e32 v111, v111, v117
	s_waitcnt lgkmcnt(1)
	v_add_f32_e32 v105, v105, v118
	s_waitcnt lgkmcnt(0)
	v_add_f32_e32 v113, v113, v116
	s_nop 0
	s_nop 0
	s_nop 0
	s_waitcnt lgkmcnt(2)
	s_nop 1
	v_add_f32_dpp v111, v111, v111 row_ror:8 row_mask:0xf bank_mask:0xf
	s_waitcnt lgkmcnt(1)
	s_nop 1
	v_add_f32_dpp v105, v105, v105 row_ror:8 row_mask:0xf bank_mask:0xf
	s_waitcnt lgkmcnt(0)
	s_nop 1
	v_add_f32_dpp v113, v113, v113 row_ror:8 row_mask:0xf bank_mask:0xf
	s_nop 0
	s_nop 0
	s_nop 0
	s_waitcnt lgkmcnt(2)
	s_nop 1
	v_add_f32_dpp v111, v111, v111 row_ror:4 row_mask:0xf bank_mask:0xf
	s_waitcnt lgkmcnt(1)
	s_nop 1
	v_add_f32_dpp v105, v105, v105 row_ror:4 row_mask:0xf bank_mask:0xf
	s_waitcnt lgkmcnt(0)
	s_nop 1
	v_add_f32_dpp v116, v113, v113 row_ror:4 row_mask:0xf bank_mask:0xf
	s_nop 0
	s_nop 0
	s_nop 0
	s_waitcnt lgkmcnt(2)
	s_nop 1
	v_add_f32_dpp v111, v111, v111 row_ror:2 row_mask:0xf bank_mask:0xf
	s_waitcnt lgkmcnt(1)
	s_nop 1
	v_add_f32_dpp v113, v105, v105 row_ror:2 row_mask:0xf bank_mask:0xf
	s_waitcnt lgkmcnt(0)
	s_nop 1
	v_add_f32_dpp v116, v116, v116 row_ror:2 row_mask:0xf bank_mask:0xf
	ds_bpermute_b32 v119, v122, v111
	ds_bpermute_b32 v118, v122, v113
	ds_bpermute_b32 v117, v122, v116
	v_cndmask_b32_e64 v124, v103, 8, vcc
	v_cmp_ne_u32_e32 vcc, v124, v107
	s_and_saveexec_b64 s[0:1], vcc
	s_cbranch_execz .LBB0_1605
	v_mul_hi_i32_i24_e32 v1, 0x6000, v124
	v_mul_i32_i24_e32 v0, 0x6000, v124
	v_lshl_add_u64 v[0:1], s[10:11], 0, v[0:1]
	v_lshl_add_u64 v[2:3], v[0:1], 0, s[30:31]
	v_lshl_add_u64 v[4:5], v[2:3], 0, v[82:83]
	v_mov_b32_e32 v107, v83
	global_load_dwordx4 v[16:19], v[4:5], off
	v_lshl_add_u64 v[4:5], v[2:3], 0, v[106:107]
	v_mov_b32_e32 v105, v83
	global_load_dwordx4 v[20:23], v[4:5], off
	v_lshl_add_u64 v[4:5], v[2:3], 0, v[104:105]
	v_mov_b32_e32 v103, v83
	global_load_dwordx4 v[24:27], v[4:5], off
	v_lshl_add_u64 v[2:3], v[2:3], 0, v[102:103]
	global_load_dwordx4 v[28:31], v[2:3], off
	global_load_dwordx4 v[126:129], v[86:87], off
	global_load_dwordx4 v[130:133], v[90:91], off
	v_lshl_add_u64 v[12:13], v[0:1], 0, v[82:83]
	global_load_dwordx4 v[134:137], v[94:95], off
	global_load_dwordx4 v[0:3], v[12:13], off
	global_load_dwordx4 v[138:141], v[98:99], off
	global_load_dwordx4 v[4:7], v[12:13], off offset:1024
	global_load_dwordx4 v[8:11], v[12:13], off offset:2048
	s_nop 0
	global_load_dwordx4 v[12:15], v[12:13], off offset:3072
	v_mov_b32_e32 v107, v124
	s_waitcnt vmcnt(11)
	v_pk_add_f32 v[18:19], v[18:19], 1.0 op_sel_hi:[1,0]
	v_pk_add_f32 v[16:17], v[16:17], 1.0 op_sel_hi:[1,0]
	s_waitcnt vmcnt(10)
	v_pk_add_f32 v[22:23], v[22:23], 1.0 op_sel_hi:[1,0]
	v_pk_add_f32 v[20:21], v[20:21], 1.0 op_sel_hi:[1,0]
	s_waitcnt vmcnt(9)
	v_pk_add_f32 v[26:27], v[26:27], 1.0 op_sel_hi:[1,0]
	v_pk_add_f32 v[24:25], v[24:25], 1.0 op_sel_hi:[1,0]
	s_waitcnt vmcnt(8)
	v_pk_add_f32 v[30:31], v[30:31], 1.0 op_sel_hi:[1,0]
	v_pk_add_f32 v[28:29], v[28:29], 1.0 op_sel_hi:[1,0]
	s_waitcnt vmcnt(7)
	v_pk_mul_f32 v[18:19], v[128:129], v[18:19]
	v_pk_mul_f32 v[16:17], v[126:127], v[16:17]
	s_waitcnt vmcnt(6)
	v_pk_mul_f32 v[22:23], v[132:133], v[22:23]
	v_pk_mul_f32 v[20:21], v[130:131], v[20:21]
	s_waitcnt vmcnt(5)
	v_pk_mul_f32 v[26:27], v[136:137], v[26:27]
	v_pk_mul_f32 v[24:25], v[134:135], v[24:25]
	s_waitcnt vmcnt(3)
	v_pk_mul_f32 v[30:31], v[140:141], v[30:31]
	v_pk_mul_f32 v[28:29], v[138:139], v[28:29]

; DI float wave_sum(float v) {
;     v += __shfl_xor(v, 32); v += __shfl_xor(v, 16); v += __shfl_xor(v, 8); v += __shfl_xor(v, 4); v += __shfl_xor(v, 2); v += __shfl_xor(v, 1);
;     return v;
; DI void norm_phase(const Params& p, int layer, int which, bool lat_only, const float* __restrict__ part, int npart, int srcmode) {
;     ...
;                 for (int j = 0; j < 4; ++j) ss[q] += v[q][j][0] * v[q][j][0] + v[q][j][1] * v[q][j][1] + v[q][j][2] * v[q][j][2] + v[q][j][3] * v[q][j][3];
;             }
;         }
;         ss[0] = wave_sum(ss[0]); ss[1] = wave_sum(ss[1]); ss[2] = wave_sum(ss[2]);
; #pragma unroll
;         for (int q = 0; q < 3; ++q) {
;             if (!ok[q]) continue;
;             const int row = r0 + 256 * q; const int ci = cond_idx(row);
;             if (ci != cur_ci) { cur_ci = ci; const float* mo = mod + (size_t)ci * 6144 + which * 3072;
; #pragma unroll
;                 for (int j = 0; j < 4; ++j) { const int col = j * 256 + lane * 4; gm[j] = *(const f32x4*)(gain + col) * (1.f + *(const f32x4*)(mo + 1024 + col)); sh[j] = *(const f32x4*)(mo + col); } }
.LBB0_1627:
	s_or_b64 exec, exec, s[14:15]
	s_waitcnt vmcnt(7)
	v_mul_f32_e32 v105, v69, v69
	s_waitcnt vmcnt(6)
	v_mul_f32_e32 v111, v61, v61
	v_fmac_f32_e32 v105, v68, v68
	v_fmac_f32_e32 v111, v60, v60
	v_fmac_f32_e32 v105, v70, v70
	v_fmac_f32_e32 v111, v62, v62
	v_fmac_f32_e32 v105, v71, v71
	v_fmac_f32_e32 v111, v63, v63
	v_add_f32_e32 v105, v111, v105
	s_waitcnt vmcnt(5)
	v_mul_f32_e32 v111, v49, v49
	v_fmac_f32_e32 v111, v48, v48
	v_fmac_f32_e32 v111, v50, v50
	v_fmac_f32_e32 v111, v51, v51
	v_add_f32_e32 v105, v111, v105
	s_waitcnt vmcnt(4)
	v_mul_f32_e32 v111, v41, v41
	v_fmac_f32_e32 v111, v40, v40
	v_fmac_f32_e32 v111, v42, v42
	v_fmac_f32_e32 v111, v43, v43
	v_add_f32_e32 v105, v111, v105
	v_mul_f32_e32 v111, v57, v57
	v_mul_f32_e32 v113, v45, v45
	v_fmac_f32_e32 v111, v56, v56
	v_fmac_f32_e32 v113, v44, v44
	v_fmac_f32_e32 v111, v58, v58
	v_fmac_f32_e32 v113, v46, v46
	v_fmac_f32_e32 v111, v59, v59
	v_fmac_f32_e32 v113, v47, v47
	v_add_f32_e32 v111, v113, v111
	v_mul_f32_e32 v113, v37, v37
	v_fmac_f32_e32 v113, v36, v36
	v_fmac_f32_e32 v113, v38, v38
	v_fmac_f32_e32 v113, v39, v39
	v_add_f32_e32 v111, v113, v111
	v_mul_f32_e32 v113, v33, v33
	v_fmac_f32_e32 v113, v32, v32
	v_fmac_f32_e32 v113, v34, v34
	v_fmac_f32_e32 v113, v35, v35
	v_add_f32_e32 v111, v113, v111
	s_waitcnt vmcnt(3)
	v_mul_f32_e32 v113, v77, v77
	s_waitcnt vmcnt(2)
	v_mul_f32_e32 v114, v73, v73
	v_fmac_f32_e32 v113, v76, v76
	v_fmac_f32_e32 v114, v72, v72
	v_fmac_f32_e32 v113, v78, v78
	v_fmac_f32_e32 v114, v74, v74
	v_fmac_f32_e32 v113, v79, v79
	v_fmac_f32_e32 v114, v75, v75
	v_add_f32_e32 v113, v114, v113
	s_waitcnt vmcnt(1)
	v_mul_f32_e32 v114, v65, v65
	v_fmac_f32_e32 v114, v64, v64
	v_fmac_f32_e32 v114, v66, v66
	v_fmac_f32_e32 v114, v67, v67
	v_add_f32_e32 v113, v114, v113
	s_waitcnt vmcnt(0)
	v_mul_f32_e32 v114, v53, v53
	v_fmac_f32_e32 v114, v52, v52
	v_fmac_f32_e32 v114, v54, v54
	v_fmac_f32_e32 v114, v55, v55
	v_add_f32_e32 v113, v114, v113
	s_nop 0
	s_nop 0
	s_nop 0
	s_waitcnt lgkmcnt(2)
	v_mov_b32_e32 v115, v111
	s_nop 1
	v_permlane32_swap_b32_e32 v111, v115
	v_add_f32_e32 v111, v111, v115
	s_waitcnt lgkmcnt(1)
	v_mov_b32_e32 v116, v105
	s_nop 1
	v_permlane32_swap_b32_e32 v105, v116
	v_add_f32_e32 v105, v105, v116
	s_waitcnt lgkmcnt(0)
	v_mov_b32_e32 v114, v113
	s_nop 1
	v_permlane32_swap_b32_e32 v113, v114
	v_add_f32_e32 v113, v113, v114
	ds_bpermute_b32 v115, v93, v111
	ds_bpermute_b32 v116, v93, v105
	ds_bpermute_b32 v114, v93, v113
	s_waitcnt lgkmcnt(2)
	v_add_f32_e32 v111, v111, v115
	s_waitcnt lgkmcnt(1)
	v_add_f32_e32 v105, v105, v116
	s_waitcnt lgkmcnt(0)
	v_add_f32_e32 v113, v113, v114
	s_nop 0
	s_nop 0
	s_nop 0
	s_waitcnt lgkmcnt(2)
	s_nop 1
	v_add_f32_dpp v111, v111, v111 row_ror:8 row_mask:0xf bank_mask:0xf
	s_waitcnt lgkmcnt(1)
	s_nop 1
	v_add_f32_dpp v105, v105, v105 row_ror:8 row_mask:0xf bank_mask:0xf
	s_waitcnt lgkmcnt(0)
	s_nop 1
	v_add_f32_dpp v113, v113, v113 row_ror:8 row_mask:0xf bank_mask:0xf
	s_nop 0
	s_nop 0
	s_nop 0
	s_waitcnt lgkmcnt(2)
	s_nop 1
	v_add_f32_dpp v111, v111, v111 row_ror:4 row_mask:0xf bank_mask:0xf
	s_waitcnt lgkmcnt(1)
	s_nop 1
	v_add_f32_dpp v105, v105, v105 row_ror:4 row_mask:0xf bank_mask:0xf
	s_waitcnt lgkmcnt(0)
	s_nop 1
	v_add_f32_dpp v114, v113, v113 row_ror:4 row_mask:0xf bank_mask:0xf
	s_nop 0
	s_nop 0
	s_nop 0
	s_waitcnt lgkmcnt(2)
	s_nop 1
	v_add_f32_dpp v111, v111, v111 row_ror:2 row_mask:0xf bank_mask:0xf
	s_waitcnt lgkmcnt(1)
	s_nop 1
	v_add_f32_dpp v113, v105, v105 row_ror:2 row_mask:0xf bank_mask:0xf
	s_waitcnt lgkmcnt(0)
	s_nop 1
	v_add_f32_dpp v114, v114, v114 row_ror:2 row_mask:0xf bank_mask:0xf
	ds_bpermute_b32 v117, v122, v111
	ds_bpermute_b32 v116, v122, v113
	ds_bpermute_b32 v115, v122, v114
	v_cndmask_b32_e64 v119, v103, 8, vcc
	v_cmp_ne_u32_e32 vcc, v119, v107
	s_and_saveexec_b64 s[0:1], vcc
	s_cbranch_execz .LBB0_1629
	v_mul_hi_i32_i24_e32 v1, 0x6000, v119
	v_mul_i32_i24_e32 v0, 0x6000, v119
	v_lshl_add_u64 v[0:1], s[10:11], 0, v[0:1]
	v_lshl_add_u64 v[2:3], v[0:1], 0, s[30:31]
	v_lshl_add_u64 v[4:5], v[2:3], 0, v[82:83]
	v_mov_b32_e32 v107, v83
	global_load_dwordx4 v[16:19], v[4:5], off
	v_lshl_add_u64 v[4:5], v[2:3], 0, v[106:107]
	v_mov_b32_e32 v105, v83
	global_load_dwordx4 v[20:23], v[4:5], off
	v_lshl_add_u64 v[4:5], v[2:3], 0, v[104:105]
	v_mov_b32_e32 v103, v83
	global_load_dwordx4 v[24:27], v[4:5], off
	v_lshl_add_u64 v[2:3], v[2:3], 0, v[102:103]
	global_load_dwordx4 v[28:31], v[2:3], off
	global_load_dwordx4 v[124:127], v[86:87], off
	global_load_dwordx4 v[128:131], v[90:91], off
	v_lshl_add_u64 v[12:13], v[0:1], 0, v[82:83]
	global_load_dwordx4 v[132:135], v[94:95], off
	global_load_dwordx4 v[0:3], v[12:13], off
	global_load_dwordx4 v[136:139], v[98:99], off
	global_load_dwordx4 v[4:7], v[12:13], off offset:1024
	global_load_dwordx4 v[8:11], v[12:13], off offset:2048
	s_nop 0
	global_load_dwordx4 v[12:15], v[12:13], off offset:3072
	v_mov_b32_e32 v107, v119
	s_waitcnt vmcnt(11)
	v_pk_add_f32 v[18:19], v[18:19], 1.0 op_sel_hi:[1,0]
	v_pk_add_f32 v[16:17], v[16:17], 1.0 op_sel_hi:[1,0]
	s_waitcnt vmcnt(10)
	v_pk_add_f32 v[22:23], v[22:23], 1.0 op_sel_hi:[1,0]
	v_pk_add_f32 v[20:21], v[20:21], 1.0 op_sel_hi:[1,0]
	s_waitcnt vmcnt(9)
	v_pk_add_f32 v[26:27], v[26:27], 1.0 op_sel_hi:[1,0]
	v_pk_add_f32 v[24:25], v[24:25], 1.0 op_sel_hi:[1,0]
	s_waitcnt vmcnt(8)
	v_pk_add_f32 v[30:31], v[30:31], 1.0 op_sel_hi:[1,0]
	v_pk_add_f32 v[28:29], v[28:29], 1.0 op_sel_hi:[1,0]
	s_waitcnt vmcnt(7)
	v_pk_mul_f32 v[18:19], v[126:127], v[18:19]
	v_pk_mul_f32 v[16:17], v[124:125], v[16:17]
	s_waitcnt vmcnt(6)
	v_pk_mul_f32 v[22:23], v[130:131], v[22:23]
	v_pk_mul_f32 v[20:21], v[128:129], v[20:21]
	s_waitcnt vmcnt(5)
	v_pk_mul_f32 v[26:27], v[134:135], v[26:27]
	v_pk_mul_f32 v[24:25], v[132:133], v[24:25]
	s_waitcnt vmcnt(3)
	v_pk_mul_f32 v[30:31], v[138:139], v[30:31]
	v_pk_mul_f32 v[28:29], v[136:137], v[28:29]

; DI float wave_sum(float v) {
;     v += __shfl_xor(v, 32); v += __shfl_xor(v, 16); v += __shfl_xor(v, 8); v += __shfl_xor(v, 4); v += __shfl_xor(v, 2); v += __shfl_xor(v, 1);
;     return v;
; DI void norm_phase(const Params& p, int layer, int which, bool lat_only, const float* __restrict__ part, int npart, int srcmode) {
;     ...
;                 for (int j = 0; j < 4; ++j) ss[q] += v[q][j][0] * v[q][j][0] + v[q][j][1] * v[q][j][1] + v[q][j][2] * v[q][j][2] + v[q][j][3] * v[q][j][3];
;             }
;         }
;         ss[0] = wave_sum(ss[0]); ss[1] = wave_sum(ss[1]); ss[2] = wave_sum(ss[2]);
; #pragma unroll
;         for (int q = 0; q < 3; ++q) {
;             if (!ok[q]) continue;
;             const int row = r0 + 256 * q; const int ci = cond_idx(row);
;             if (ci != cur_ci) { cur_ci = ci; const float* mo = mod + (size_t)ci * 6144 + which * 3072;
; #pragma unroll
;                 for (int j = 0; j < 4; ++j) { const int col = j * 256 + lane * 4; gm[j] = *(const f32x4*)(gain + col) * (1.f + *(const f32x4*)(mo + 1024 + col)); sh[j] = *(const f32x4*)(mo + col); } }
.LBB0_1907:
	s_or_b64 exec, exec, s[14:15]
	s_waitcnt vmcnt(7)
	v_mul_f32_e32 v104, v61, v61
	s_waitcnt vmcnt(6)
	v_mul_f32_e32 v105, v57, v57
	v_fmac_f32_e32 v104, v60, v60
	v_fmac_f32_e32 v105, v56, v56
	v_fmac_f32_e32 v104, v62, v62
	v_fmac_f32_e32 v105, v58, v58
	v_fmac_f32_e32 v104, v63, v63
	v_fmac_f32_e32 v105, v59, v59
	v_add_f32_e32 v104, v105, v104
	s_waitcnt vmcnt(5)
	v_mul_f32_e32 v105, v53, v53
	v_fmac_f32_e32 v105, v52, v52
	v_fmac_f32_e32 v105, v54, v54
	v_fmac_f32_e32 v105, v55, v55
	v_add_f32_e32 v104, v105, v104
	s_waitcnt vmcnt(4)
	v_mul_f32_e32 v105, v49, v49
	v_fmac_f32_e32 v105, v48, v48
	v_fmac_f32_e32 v105, v50, v50
	v_fmac_f32_e32 v105, v51, v51
	v_add_f32_e32 v104, v105, v104
	v_mul_f32_e32 v105, v45, v45
	v_mul_f32_e32 v106, v41, v41
	v_fmac_f32_e32 v105, v44, v44
	v_fmac_f32_e32 v106, v40, v40
	v_fmac_f32_e32 v105, v46, v46
	v_fmac_f32_e32 v106, v42, v42
	v_fmac_f32_e32 v105, v47, v47
	v_fmac_f32_e32 v106, v43, v43
	v_add_f32_e32 v105, v106, v105
	v_mul_f32_e32 v106, v37, v37
	v_fmac_f32_e32 v106, v36, v36
	v_fmac_f32_e32 v106, v38, v38
	v_fmac_f32_e32 v106, v39, v39
	v_add_f32_e32 v105, v106, v105
	v_mul_f32_e32 v106, v33, v33
	v_fmac_f32_e32 v106, v32, v32
	v_fmac_f32_e32 v106, v34, v34
	v_fmac_f32_e32 v106, v35, v35
	v_add_f32_e32 v105, v106, v105
	s_waitcnt vmcnt(3)
	v_mul_f32_e32 v106, v77, v77
	s_waitcnt vmcnt(2)
	v_mul_f32_e32 v107, v73, v73
	v_fmac_f32_e32 v106, v76, v76
	v_fmac_f32_e32 v107, v72, v72
	v_fmac_f32_e32 v106, v78, v78
	v_fmac_f32_e32 v107, v74, v74
	v_fmac_f32_e32 v106, v79, v79
	v_fmac_f32_e32 v107, v75, v75
	v_add_f32_e32 v106, v107, v106
	s_waitcnt vmcnt(1)
	v_mul_f32_e32 v107, v69, v69
	v_fmac_f32_e32 v107, v68, v68
	v_fmac_f32_e32 v107, v70, v70
	v_fmac_f32_e32 v107, v71, v71
	v_add_f32_e32 v106, v107, v106
	s_waitcnt vmcnt(0)
	v_mul_f32_e32 v107, v65, v65
	v_fmac_f32_e32 v107, v64, v64
	v_fmac_f32_e32 v107, v66, v66
	v_fmac_f32_e32 v107, v67, v67
	v_add_f32_e32 v106, v107, v106
	s_nop 0
	s_nop 0
	s_nop 0
	v_cndmask_b32_e64 v103, v103, 8, vcc
	v_cmp_ne_u32_e32 vcc, v103, v109
	s_waitcnt lgkmcnt(2)
	v_mov_b32_e32 v108, v105
	s_nop 1
	v_permlane32_swap_b32_e32 v105, v108
	v_add_f32_e32 v105, v105, v108
	s_waitcnt lgkmcnt(1)
	v_mov_b32_e32 v114, v104
	s_nop 1
	v_permlane32_swap_b32_e32 v104, v114
	v_add_f32_e32 v104, v104, v114
	s_waitcnt lgkmcnt(0)
	v_mov_b32_e32 v107, v106
	s_nop 1
	v_permlane32_swap_b32_e32 v106, v107
	v_add_f32_e32 v106, v106, v107
	ds_bpermute_b32 v108, v93, v105
	ds_bpermute_b32 v114, v93, v104
	ds_bpermute_b32 v107, v93, v106
	s_waitcnt lgkmcnt(2)
	v_add_f32_e32 v105, v105, v108
	s_waitcnt lgkmcnt(1)
	v_add_f32_e32 v104, v104, v114
	s_waitcnt lgkmcnt(0)
	v_add_f32_e32 v106, v106, v107
	s_nop 0
	s_nop 0
	s_nop 0
	s_waitcnt lgkmcnt(2)
	s_nop 1
	v_add_f32_dpp v105, v105, v105 row_ror:8 row_mask:0xf bank_mask:0xf
	s_waitcnt lgkmcnt(1)
	s_nop 1
	v_add_f32_dpp v104, v104, v104 row_ror:8 row_mask:0xf bank_mask:0xf
	s_waitcnt lgkmcnt(0)
	s_nop 1
	v_add_f32_dpp v106, v106, v106 row_ror:8 row_mask:0xf bank_mask:0xf
	s_nop 0
	s_nop 0
	s_nop 0
	s_waitcnt lgkmcnt(2)
	s_nop 1
	v_add_f32_dpp v105, v105, v105 row_ror:4 row_mask:0xf bank_mask:0xf
	s_waitcnt lgkmcnt(1)
	s_nop 1
	v_add_f32_dpp v104, v104, v104 row_ror:4 row_mask:0xf bank_mask:0xf
	s_waitcnt lgkmcnt(0)
	s_nop 1
	v_add_f32_dpp v106, v106, v106 row_ror:4 row_mask:0xf bank_mask:0xf
	s_nop 0
	s_nop 0
	s_nop 0
	s_waitcnt lgkmcnt(2)
	s_nop 1
	v_add_f32_dpp v118, v105, v105 row_ror:2 row_mask:0xf bank_mask:0xf
	s_waitcnt lgkmcnt(1)
	s_nop 1
	v_add_f32_dpp v116, v104, v104 row_ror:2 row_mask:0xf bank_mask:0xf
	s_waitcnt lgkmcnt(0)
	s_nop 1
	v_add_f32_dpp v114, v106, v106 row_ror:2 row_mask:0xf bank_mask:0xf
	ds_bpermute_b32 v119, v122, v118
	ds_bpermute_b32 v117, v122, v116
	ds_bpermute_b32 v115, v122, v114
	v_lshlrev_b32_e32 v108, 2, v88
	v_lshlrev_b32_e32 v106, 2, v92
	v_lshlrev_b32_e32 v104, 2, v96
	s_and_saveexec_b64 s[0:1], vcc
	s_cbranch_execz .LBB0_1909
	v_mul_hi_i32_i24_e32 v1, 0x6000, v103
	v_mul_i32_i24_e32 v0, 0x6000, v103
	v_lshl_add_u64 v[0:1], s[8:9], 0, v[0:1]
	v_lshl_add_u64 v[2:3], v[0:1], 0, s[34:35]
	v_lshl_add_u64 v[4:5], v[2:3], 0, v[82:83]
	v_mov_b32_e32 v109, v83
	global_load_dwordx4 v[16:19], v[4:5], off
	v_lshl_add_u64 v[4:5], v[2:3], 0, v[108:109]
	v_mov_b32_e32 v107, v83
	global_load_dwordx4 v[20:23], v[4:5], off
	v_lshl_add_u64 v[4:5], v[2:3], 0, v[106:107]
	v_mov_b32_e32 v105, v83
	global_load_dwordx4 v[24:27], v[4:5], off
	v_lshl_add_u64 v[2:3], v[2:3], 0, v[104:105]
	global_load_dwordx4 v[28:31], v[2:3], off
	global_load_dwordx4 v[124:127], v[86:87], off
	global_load_dwordx4 v[128:131], v[90:91], off
	v_lshl_add_u64 v[12:13], v[0:1], 0, v[82:83]
	global_load_dwordx4 v[132:135], v[94:95], off
	global_load_dwordx4 v[0:3], v[12:13], off
	global_load_dwordx4 v[136:139], v[98:99], off
	global_load_dwordx4 v[4:7], v[12:13], off offset:1024
	global_load_dwordx4 v[8:11], v[12:13], off offset:2048
	s_nop 0
	global_load_dwordx4 v[12:15], v[12:13], off offset:3072
	v_mov_b32_e32 v109, v103
	s_waitcnt vmcnt(11)
	v_pk_add_f32 v[18:19], v[18:19], 1.0 op_sel_hi:[1,0]
	v_pk_add_f32 v[16:17], v[16:17], 1.0 op_sel_hi:[1,0]
	s_waitcnt vmcnt(10)
	v_pk_add_f32 v[22:23], v[22:23], 1.0 op_sel_hi:[1,0]
	v_pk_add_f32 v[20:21], v[20:21], 1.0 op_sel_hi:[1,0]
	s_waitcnt vmcnt(9)
	v_pk_add_f32 v[26:27], v[26:27], 1.0 op_sel_hi:[1,0]
	v_pk_add_f32 v[24:25], v[24:25], 1.0 op_sel_hi:[1,0]
	s_waitcnt vmcnt(8)
	v_pk_add_f32 v[30:31], v[30:31], 1.0 op_sel_hi:[1,0]
	v_pk_add_f32 v[28:29], v[28:29], 1.0 op_sel_hi:[1,0]
	s_waitcnt vmcnt(7)
	v_pk_mul_f32 v[18:19], v[126:127], v[18:19]
	v_pk_mul_f32 v[16:17], v[124:125], v[16:17]
	s_waitcnt vmcnt(6)
	v_pk_mul_f32 v[22:23], v[130:131], v[22:23]
	v_pk_mul_f32 v[20:21], v[128:129], v[20:21]
	s_waitcnt vmcnt(5)
	v_pk_mul_f32 v[26:27], v[134:135], v[26:27]
	v_pk_mul_f32 v[24:25], v[132:133], v[24:25]
	s_waitcnt vmcnt(3)
	v_pk_mul_f32 v[30:31], v[138:139], v[30:31]
	v_pk_mul_f32 v[28:29], v[136:137], v[28:29]

; DI float wave_sum(float v) {
;     v += __shfl_xor(v, 32); v += __shfl_xor(v, 16); v += __shfl_xor(v, 8); v += __shfl_xor(v, 4); v += __shfl_xor(v, 2); v += __shfl_xor(v, 1);
;     return v;
; DI void norm_phase(const Params& p, int layer, int which, bool lat_only, const float* __restrict__ part, int npart, int srcmode) {
;     ...
;                 for (int j = 0; j < 4; ++j) ss[q] += v[q][j][0] * v[q][j][0] + v[q][j][1] * v[q][j][1] + v[q][j][2] * v[q][j][2] + v[q][j][3] * v[q][j][3];
;             }
;         }
;         ss[0] = wave_sum(ss[0]); ss[1] = wave_sum(ss[1]); ss[2] = wave_sum(ss[2]);
; #pragma unroll
;         for (int q = 0; q < 3; ++q) {
;             if (!ok[q]) continue;
;             const int row = r0 + 256 * q; const int ci = cond_idx(row);
;             if (ci != cur_ci) { cur_ci = ci; const float* mo = mod + (size_t)ci * 6144 + which * 3072;
; #pragma unroll
;                 for (int j = 0; j < 4; ++j) { const int col = j * 256 + lane * 4; gm[j] = *(const f32x4*)(gain + col) * (1.f + *(const f32x4*)(mo + 1024 + col)); sh[j] = *(const f32x4*)(mo + col); } }
.LBB0_1931:
	s_or_b64 exec, exec, s[14:15]
	s_waitcnt vmcnt(7)
	v_mul_f32_e32 v105, v61, v61
	s_waitcnt vmcnt(6)
	v_mul_f32_e32 v107, v57, v57
	v_fmac_f32_e32 v105, v60, v60
	v_fmac_f32_e32 v107, v56, v56
	v_fmac_f32_e32 v105, v62, v62
	v_fmac_f32_e32 v107, v58, v58
	v_fmac_f32_e32 v105, v63, v63
	v_fmac_f32_e32 v107, v59, v59
	v_add_f32_e32 v105, v107, v105
	s_waitcnt vmcnt(5)
	v_mul_f32_e32 v107, v53, v53
	v_fmac_f32_e32 v107, v52, v52
	v_fmac_f32_e32 v107, v54, v54
	v_fmac_f32_e32 v107, v55, v55
	v_add_f32_e32 v105, v107, v105
	s_waitcnt vmcnt(4)
	v_mul_f32_e32 v107, v49, v49
	v_fmac_f32_e32 v107, v48, v48
	v_fmac_f32_e32 v107, v50, v50
	v_fmac_f32_e32 v107, v51, v51
	v_add_f32_e32 v105, v107, v105
	v_mul_f32_e32 v107, v45, v45
	v_mul_f32_e32 v111, v41, v41
	v_fmac_f32_e32 v107, v44, v44
	v_fmac_f32_e32 v111, v40, v40
	v_fmac_f32_e32 v107, v46, v46
	v_fmac_f32_e32 v111, v42, v42
	v_fmac_f32_e32 v107, v47, v47
	v_fmac_f32_e32 v111, v43, v43
	v_add_f32_e32 v107, v111, v107
	v_mul_f32_e32 v111, v37, v37
	v_fmac_f32_e32 v111, v36, v36
	v_fmac_f32_e32 v111, v38, v38
	v_fmac_f32_e32 v111, v39, v39
	v_add_f32_e32 v107, v111, v107
	v_mul_f32_e32 v111, v33, v33
	v_fmac_f32_e32 v111, v32, v32
	v_fmac_f32_e32 v111, v34, v34
	v_fmac_f32_e32 v111, v35, v35
	v_add_f32_e32 v107, v111, v107
	s_waitcnt vmcnt(3)
	v_mul_f32_e32 v111, v77, v77
	s_waitcnt vmcnt(2)
	v_mul_f32_e32 v116, v73, v73
	v_fmac_f32_e32 v111, v76, v76
	v_fmac_f32_e32 v116, v72, v72
	v_fmac_f32_e32 v111, v78, v78
	v_fmac_f32_e32 v116, v74, v74
	v_fmac_f32_e32 v111, v79, v79
	v_fmac_f32_e32 v116, v75, v75
	v_add_f32_e32 v111, v116, v111
	s_waitcnt vmcnt(1)
	v_mul_f32_e32 v116, v69, v69
	v_fmac_f32_e32 v116, v68, v68
	v_fmac_f32_e32 v116, v70, v70
	v_fmac_f32_e32 v116, v71, v71
	v_add_f32_e32 v111, v116, v111
	s_waitcnt vmcnt(0)
	v_mul_f32_e32 v116, v65, v65
	v_fmac_f32_e32 v116, v64, v64
	v_fmac_f32_e32 v116, v66, v66
	v_fmac_f32_e32 v116, v67, v67
	v_add_f32_e32 v111, v116, v111
	s_nop 0
	s_nop 0
	s_nop 0
	v_cndmask_b32_e64 v103, v103, 8, vcc
	v_cmp_ne_u32_e32 vcc, v103, v109
	s_waitcnt lgkmcnt(2)
	v_mov_b32_e32 v117, v107
	s_nop 1
	v_permlane32_swap_b32_e32 v107, v117
	v_add_f32_e32 v107, v107, v117
	s_waitcnt lgkmcnt(1)
	v_mov_b32_e32 v118, v105
	s_nop 1
	v_permlane32_swap_b32_e32 v105, v118
	v_add_f32_e32 v105, v105, v118
	s_waitcnt lgkmcnt(0)
	v_mov_b32_e32 v116, v111
	s_nop 1
	v_permlane32_swap_b32_e32 v111, v116
	v_add_f32_e32 v111, v111, v116
	ds_bpermute_b32 v117, v93, v107
	ds_bpermute_b32 v118, v93, v105
	ds_bpermute_b32 v116, v93, v111
	s_waitcnt lgkmcnt(2)
	v_add_f32_e32 v107, v107, v117
	s_waitcnt lgkmcnt(1)
	v_add_f32_e32 v105, v105, v118
	s_waitcnt lgkmcnt(0)
	v_add_f32_e32 v111, v111, v116
	s_nop 0
	s_nop 0
	s_nop 0
	s_waitcnt lgkmcnt(2)
	s_nop 1
	v_add_f32_dpp v107, v107, v107 row_ror:8 row_mask:0xf bank_mask:0xf
	s_waitcnt lgkmcnt(1)
	s_nop 1
	v_add_f32_dpp v105, v105, v105 row_ror:8 row_mask:0xf bank_mask:0xf
	s_waitcnt lgkmcnt(0)
	s_nop 1
	v_add_f32_dpp v111, v111, v111 row_ror:8 row_mask:0xf bank_mask:0xf
	s_nop 0
	s_nop 0
	s_nop 0
	s_waitcnt lgkmcnt(2)
	s_nop 1
	v_add_f32_dpp v107, v107, v107 row_ror:4 row_mask:0xf bank_mask:0xf
	s_waitcnt lgkmcnt(1)
	s_nop 1
	v_add_f32_dpp v105, v105, v105 row_ror:4 row_mask:0xf bank_mask:0xf
	s_waitcnt lgkmcnt(0)
	s_nop 1
	v_add_f32_dpp v116, v111, v111 row_ror:4 row_mask:0xf bank_mask:0xf
	s_nop 0
	s_nop 0
	s_nop 0
	s_waitcnt lgkmcnt(2)
	s_nop 1
	v_add_f32_dpp v111, v107, v107 row_ror:2 row_mask:0xf bank_mask:0xf
	s_waitcnt lgkmcnt(1)
	s_nop 1
	v_add_f32_dpp v118, v105, v105 row_ror:2 row_mask:0xf bank_mask:0xf
	s_waitcnt lgkmcnt(0)
	s_nop 1
	v_add_f32_dpp v116, v116, v116 row_ror:2 row_mask:0xf bank_mask:0xf
	ds_bpermute_b32 v124, v122, v111
	ds_bpermute_b32 v119, v122, v118
	ds_bpermute_b32 v117, v122, v116
	s_and_saveexec_b64 s[0:1], vcc
	s_cbranch_execz .LBB0_1933
	v_mul_hi_i32_i24_e32 v1, 0x6000, v103
	v_mul_i32_i24_e32 v0, 0x6000, v103
	v_lshl_add_u64 v[0:1], s[8:9], 0, v[0:1]
	v_lshl_add_u64 v[2:3], v[0:1], 0, s[34:35]
	v_lshl_add_u64 v[4:5], v[2:3], 0, v[82:83]
	v_mov_b32_e32 v109, v83
	global_load_dwordx4 v[16:19], v[4:5], off
	v_lshl_add_u64 v[4:5], v[2:3], 0, v[108:109]
	v_mov_b32_e32 v107, v83
	global_load_dwordx4 v[20:23], v[4:5], off
	v_lshl_add_u64 v[4:5], v[2:3], 0, v[106:107]
	v_mov_b32_e32 v105, v83
	global_load_dwordx4 v[24:27], v[4:5], off
	v_lshl_add_u64 v[2:3], v[2:3], 0, v[104:105]
	global_load_dwordx4 v[28:31], v[2:3], off
	global_load_dwordx4 v[126:129], v[86:87], off
	global_load_dwordx4 v[130:133], v[90:91], off
	v_lshl_add_u64 v[12:13], v[0:1], 0, v[82:83]
	global_load_dwordx4 v[134:137], v[94:95], off
	global_load_dwordx4 v[0:3], v[12:13], off
	global_load_dwordx4 v[138:141], v[98:99], off
	global_load_dwordx4 v[4:7], v[12:13], off offset:1024
	global_load_dwordx4 v[8:11], v[12:13], off offset:2048
	s_nop 0
	global_load_dwordx4 v[12:15], v[12:13], off offset:3072
	v_mov_b32_e32 v109, v103
	s_waitcnt vmcnt(11)
	v_pk_add_f32 v[18:19], v[18:19], 1.0 op_sel_hi:[1,0]
	v_pk_add_f32 v[16:17], v[16:17], 1.0 op_sel_hi:[1,0]
	s_waitcnt vmcnt(10)
	v_pk_add_f32 v[22:23], v[22:23], 1.0 op_sel_hi:[1,0]
	v_pk_add_f32 v[20:21], v[20:21], 1.0 op_sel_hi:[1,0]
	s_waitcnt vmcnt(9)
	v_pk_add_f32 v[26:27], v[26:27], 1.0 op_sel_hi:[1,0]
	v_pk_add_f32 v[24:25], v[24:25], 1.0 op_sel_hi:[1,0]
	s_waitcnt vmcnt(8)
	v_pk_add_f32 v[30:31], v[30:31], 1.0 op_sel_hi:[1,0]
	v_pk_add_f32 v[28:29], v[28:29], 1.0 op_sel_hi:[1,0]
	s_waitcnt vmcnt(7)
	v_pk_mul_f32 v[18:19], v[128:129], v[18:19]
	v_pk_mul_f32 v[16:17], v[126:127], v[16:17]
	s_waitcnt vmcnt(6)
	v_pk_mul_f32 v[22:23], v[132:133], v[22:23]
	v_pk_mul_f32 v[20:21], v[130:131], v[20:21]
	s_waitcnt vmcnt(5)
	v_pk_mul_f32 v[26:27], v[136:137], v[26:27]
	v_pk_mul_f32 v[24:25], v[134:135], v[24:25]
	s_waitcnt vmcnt(3)
	v_pk_mul_f32 v[30:31], v[140:141], v[30:31]
	v_pk_mul_f32 v[28:29], v[138:139], v[28:29]

; DI float wave_sum(float v) {
;     v += __shfl_xor(v, 32); v += __shfl_xor(v, 16); v += __shfl_xor(v, 8); v += __shfl_xor(v, 4); v += __shfl_xor(v, 2); v += __shfl_xor(v, 1);
;     return v;
; DI void norm_phase(const Params& p, int layer, int which, bool lat_only, const float* __restrict__ part, int npart, int srcmode) {
;     ...
;                 for (int j = 0; j < 4; ++j) ss[q] += v[q][j][0] * v[q][j][0] + v[q][j][1] * v[q][j][1] + v[q][j][2] * v[q][j][2] + v[q][j][3] * v[q][j][3];
;             }
;         }
;         ss[0] = wave_sum(ss[0]); ss[1] = wave_sum(ss[1]); ss[2] = wave_sum(ss[2]);
; #pragma unroll
;         for (int q = 0; q < 3; ++q) {
;             if (!ok[q]) continue;
;             const int row = r0 + 256 * q; const int ci = cond_idx(row);
;             if (ci != cur_ci) { cur_ci = ci; const float* mo = mod + (size_t)ci * 6144 + which * 3072;
; #pragma unroll
;                 for (int j = 0; j < 4; ++j) { const int col = j * 256 + lane * 4; gm[j] = *(const f32x4*)(gain + col) * (1.f + *(const f32x4*)(mo + 1024 + col)); sh[j] = *(const f32x4*)(mo + col); } }
.LBB0_1955:
	s_or_b64 exec, exec, s[14:15]
	s_waitcnt vmcnt(7)
	v_mul_f32_e32 v105, v61, v61
	s_waitcnt vmcnt(6)
	v_mul_f32_e32 v107, v57, v57
	v_fmac_f32_e32 v105, v60, v60
	v_fmac_f32_e32 v107, v56, v56
	v_fmac_f32_e32 v105, v62, v62
	v_fmac_f32_e32 v107, v58, v58
	v_fmac_f32_e32 v105, v63, v63
	v_fmac_f32_e32 v107, v59, v59
	v_add_f32_e32 v105, v107, v105
	s_waitcnt vmcnt(5)
	v_mul_f32_e32 v107, v53, v53
	v_fmac_f32_e32 v107, v52, v52
	v_fmac_f32_e32 v107, v54, v54
	v_fmac_f32_e32 v107, v55, v55
	v_add_f32_e32 v105, v107, v105
	s_waitcnt vmcnt(4)
	v_mul_f32_e32 v107, v49, v49
	v_fmac_f32_e32 v107, v48, v48
	v_fmac_f32_e32 v107, v50, v50
	v_fmac_f32_e32 v107, v51, v51
	v_add_f32_e32 v105, v107, v105
	v_mul_f32_e32 v107, v45, v45
	v_mul_f32_e32 v111, v41, v41
	v_fmac_f32_e32 v107, v44, v44
	v_fmac_f32_e32 v111, v40, v40
	v_fmac_f32_e32 v107, v46, v46
	v_fmac_f32_e32 v111, v42, v42
	v_fmac_f32_e32 v107, v47, v47
	v_fmac_f32_e32 v111, v43, v43
	v_add_f32_e32 v107, v111, v107
	v_mul_f32_e32 v111, v37, v37
	v_fmac_f32_e32 v111, v36, v36
	v_fmac_f32_e32 v111, v38, v38
	v_fmac_f32_e32 v111, v39, v39
	v_add_f32_e32 v107, v111, v107
	v_mul_f32_e32 v111, v33, v33
	v_fmac_f32_e32 v111, v32, v32
	v_fmac_f32_e32 v111, v34, v34
	v_fmac_f32_e32 v111, v35, v35
	v_add_f32_e32 v107, v111, v107
	s_waitcnt vmcnt(3)
	v_mul_f32_e32 v111, v77, v77
	s_waitcnt vmcnt(2)
	v_mul_f32_e32 v114, v73, v73
	v_fmac_f32_e32 v111, v76, v76
	v_fmac_f32_e32 v114, v72, v72
	v_fmac_f32_e32 v111, v78, v78
	v_fmac_f32_e32 v114, v74, v74
	v_fmac_f32_e32 v111, v79, v79
	v_fmac_f32_e32 v114, v75, v75
	v_add_f32_e32 v111, v114, v111
	s_waitcnt vmcnt(1)
	v_mul_f32_e32 v114, v69, v69
	v_fmac_f32_e32 v114, v68, v68
	v_fmac_f32_e32 v114, v70, v70
	v_fmac_f32_e32 v114, v71, v71
	v_add_f32_e32 v111, v114, v111
	s_waitcnt vmcnt(0)
	v_mul_f32_e32 v114, v65, v65
	v_fmac_f32_e32 v114, v64, v64
	v_fmac_f32_e32 v114, v66, v66
	v_fmac_f32_e32 v114, v67, v67
	v_add_f32_e32 v111, v114, v111
	s_nop 0
	s_nop 0
	s_nop 0
	v_cndmask_b32_e64 v103, v103, 8, vcc
	v_cmp_ne_u32_e32 vcc, v103, v109
	s_waitcnt lgkmcnt(2)
	v_mov_b32_e32 v115, v107
	s_nop 1
	v_permlane32_swap_b32_e32 v107, v115
	v_add_f32_e32 v107, v107, v115
	s_waitcnt lgkmcnt(1)
	v_mov_b32_e32 v116, v105
	s_nop 1
	v_permlane32_swap_b32_e32 v105, v116
	v_add_f32_e32 v105, v105, v116
	s_waitcnt lgkmcnt(0)
	v_mov_b32_e32 v114, v111
	s_nop 1
	v_permlane32_swap_b32_e32 v111, v114
	v_add_f32_e32 v111, v111, v114
	ds_bpermute_b32 v115, v93, v107
	ds_bpermute_b32 v116, v93, v105
	ds_bpermute_b32 v114, v93, v111
	s_waitcnt lgkmcnt(2)
	v_add_f32_e32 v107, v107, v115
	s_waitcnt lgkmcnt(1)
	v_add_f32_e32 v105, v105, v116
	s_waitcnt lgkmcnt(0)
	v_add_f32_e32 v111, v111, v114
	s_nop 0
	s_nop 0
	s_nop 0
	s_waitcnt lgkmcnt(2)
	s_nop 1
	v_add_f32_dpp v107, v107, v107 row_ror:8 row_mask:0xf bank_mask:0xf
	s_waitcnt lgkmcnt(1)
	s_nop 1
	v_add_f32_dpp v105, v105, v105 row_ror:8 row_mask:0xf bank_mask:0xf
	s_waitcnt lgkmcnt(0)
	s_nop 1
	v_add_f32_dpp v111, v111, v111 row_ror:8 row_mask:0xf bank_mask:0xf
	s_nop 0
	s_nop 0
	s_nop 0
	s_waitcnt lgkmcnt(2)
	s_nop 1
	v_add_f32_dpp v107, v107, v107 row_ror:4 row_mask:0xf bank_mask:0xf
	s_waitcnt lgkmcnt(1)
	s_nop 1
	v_add_f32_dpp v105, v105, v105 row_ror:4 row_mask:0xf bank_mask:0xf
	s_waitcnt lgkmcnt(0)
	s_nop 1
	v_add_f32_dpp v114, v111, v111 row_ror:4 row_mask:0xf bank_mask:0xf
	s_nop 0
	s_nop 0
	s_nop 0
	s_waitcnt lgkmcnt(2)
	s_nop 1
	v_add_f32_dpp v111, v107, v107 row_ror:2 row_mask:0xf bank_mask:0xf
	s_waitcnt lgkmcnt(1)
	s_nop 1
	v_add_f32_dpp v116, v105, v105 row_ror:2 row_mask:0xf bank_mask:0xf
	s_waitcnt lgkmcnt(0)
	s_nop 1
	v_add_f32_dpp v114, v114, v114 row_ror:2 row_mask:0xf bank_mask:0xf
	ds_bpermute_b32 v119, v122, v111
	ds_bpermute_b32 v117, v122, v116
	ds_bpermute_b32 v115, v122, v114
	s_and_saveexec_b64 s[0:1], vcc
	s_cbranch_execz .LBB0_1957
	v_mul_hi_i32_i24_e32 v1, 0x6000, v103
	v_mul_i32_i24_e32 v0, 0x6000, v103
	v_lshl_add_u64 v[0:1], s[8:9], 0, v[0:1]
	v_lshl_add_u64 v[2:3], v[0:1], 0, s[34:35]
	v_lshl_add_u64 v[4:5], v[2:3], 0, v[82:83]
	v_mov_b32_e32 v109, v83
	global_load_dwordx4 v[16:19], v[4:5], off
	v_lshl_add_u64 v[4:5], v[2:3], 0, v[108:109]
	v_mov_b32_e32 v107, v83
	global_load_dwordx4 v[20:23], v[4:5], off
	v_lshl_add_u64 v[4:5], v[2:3], 0, v[106:107]
	v_mov_b32_e32 v105, v83
	global_load_dwordx4 v[24:27], v[4:5], off
	v_lshl_add_u64 v[2:3], v[2:3], 0, v[104:105]
	global_load_dwordx4 v[28:31], v[2:3], off
	global_load_dwordx4 v[124:127], v[86:87], off
	global_load_dwordx4 v[128:131], v[90:91], off
	v_lshl_add_u64 v[12:13], v[0:1], 0, v[82:83]
	global_load_dwordx4 v[132:135], v[94:95], off
	global_load_dwordx4 v[0:3], v[12:13], off
	global_load_dwordx4 v[136:139], v[98:99], off
	global_load_dwordx4 v[4:7], v[12:13], off offset:1024
	global_load_dwordx4 v[8:11], v[12:13], off offset:2048
	s_nop 0
	global_load_dwordx4 v[12:15], v[12:13], off offset:3072
	v_mov_b32_e32 v109, v103
	s_waitcnt vmcnt(11)
	v_pk_add_f32 v[18:19], v[18:19], 1.0 op_sel_hi:[1,0]
	v_pk_add_f32 v[16:17], v[16:17], 1.0 op_sel_hi:[1,0]
	s_waitcnt vmcnt(10)
	v_pk_add_f32 v[22:23], v[22:23], 1.0 op_sel_hi:[1,0]
	v_pk_add_f32 v[20:21], v[20:21], 1.0 op_sel_hi:[1,0]
	s_waitcnt vmcnt(9)
	v_pk_add_f32 v[26:27], v[26:27], 1.0 op_sel_hi:[1,0]
	v_pk_add_f32 v[24:25], v[24:25], 1.0 op_sel_hi:[1,0]
	s_waitcnt vmcnt(8)
	v_pk_add_f32 v[30:31], v[30:31], 1.0 op_sel_hi:[1,0]
	v_pk_add_f32 v[28:29], v[28:29], 1.0 op_sel_hi:[1,0]
	s_waitcnt vmcnt(7)
	v_pk_mul_f32 v[18:19], v[126:127], v[18:19]
	v_pk_mul_f32 v[16:17], v[124:125], v[16:17]
	s_waitcnt vmcnt(6)
	v_pk_mul_f32 v[22:23], v[130:131], v[22:23]
	v_pk_mul_f32 v[20:21], v[128:129], v[20:21]
	s_waitcnt vmcnt(5)
	v_pk_mul_f32 v[26:27], v[134:135], v[26:27]
	v_pk_mul_f32 v[24:25], v[132:133], v[24:25]
	s_waitcnt vmcnt(3)
	v_pk_mul_f32 v[30:31], v[138:139], v[30:31]
	v_pk_mul_f32 v[28:29], v[136:137], v[28:29]

; DI float wave_sum(float v) {
;     v += __shfl_xor(v, 32); v += __shfl_xor(v, 16); v += __shfl_xor(v, 8); v += __shfl_xor(v, 4); v += __shfl_xor(v, 2); v += __shfl_xor(v, 1);
;     return v;
; DI void norm_phase(const Params& p, int layer, int which, bool lat_only, const float* __restrict__ part, int npart, int srcmode) {
;     ...
;                 for (int j = 0; j < 4; ++j) ss[q] += v[q][j][0] * v[q][j][0] + v[q][j][1] * v[q][j][1] + v[q][j][2] * v[q][j][2] + v[q][j][3] * v[q][j][3];
;             }
;         }
;         ss[0] = wave_sum(ss[0]); ss[1] = wave_sum(ss[1]); ss[2] = wave_sum(ss[2]);
; #pragma unroll
;         for (int q = 0; q < 3; ++q) {
;             if (!ok[q]) continue;
;             const int row = r0 + 256 * q; const int ci = cond_idx(row);
;             if (ci != cur_ci) { cur_ci = ci; const float* mo = mod + (size_t)ci * 6144 + which * 3072;
; #pragma unroll
;                 for (int j = 0; j < 4; ++j) { const int col = j * 256 + lane * 4; gm[j] = *(const f32x4*)(gain + col) * (1.f + *(const f32x4*)(mo + 1024 + col)); sh[j] = *(const f32x4*)(mo + col); } }
.LBB0_2690:
	s_or_b64 exec, exec, s[14:15]
	s_waitcnt vmcnt(7)
	v_mul_f32_e32 v102, v69, v69
	s_waitcnt vmcnt(6)
	v_mul_f32_e32 v103, v61, v61
	v_fmac_f32_e32 v102, v68, v68
	v_fmac_f32_e32 v103, v60, v60
	v_fmac_f32_e32 v102, v70, v70
	v_fmac_f32_e32 v103, v62, v62
	v_fmac_f32_e32 v102, v71, v71
	v_fmac_f32_e32 v103, v63, v63
	v_add_f32_e32 v102, v103, v102
	s_waitcnt vmcnt(5)
	v_mul_f32_e32 v103, v49, v49
	v_fmac_f32_e32 v103, v48, v48
	v_fmac_f32_e32 v103, v50, v50
	v_fmac_f32_e32 v103, v51, v51
	v_add_f32_e32 v102, v103, v102
	s_waitcnt vmcnt(4)
	v_mul_f32_e32 v103, v41, v41
	v_fmac_f32_e32 v103, v40, v40
	v_fmac_f32_e32 v103, v42, v42
	v_fmac_f32_e32 v103, v43, v43
	v_add_f32_e32 v102, v103, v102
	v_mul_f32_e32 v103, v57, v57
	v_mul_f32_e32 v104, v45, v45
	v_fmac_f32_e32 v103, v56, v56
	v_fmac_f32_e32 v104, v44, v44
	v_fmac_f32_e32 v103, v58, v58
	v_fmac_f32_e32 v104, v46, v46
	v_fmac_f32_e32 v103, v59, v59
	v_fmac_f32_e32 v104, v47, v47
	v_add_f32_e32 v103, v104, v103
	v_mul_f32_e32 v104, v37, v37
	v_fmac_f32_e32 v104, v36, v36
	v_fmac_f32_e32 v104, v38, v38
	v_fmac_f32_e32 v104, v39, v39
	v_add_f32_e32 v103, v104, v103
	v_mul_f32_e32 v104, v33, v33
	v_fmac_f32_e32 v104, v32, v32
	v_fmac_f32_e32 v104, v34, v34
	v_fmac_f32_e32 v104, v35, v35
	v_add_f32_e32 v103, v104, v103
	s_waitcnt vmcnt(3)
	v_mul_f32_e32 v104, v77, v77
	s_waitcnt vmcnt(2)
	v_mul_f32_e32 v105, v73, v73
	v_fmac_f32_e32 v104, v76, v76
	v_fmac_f32_e32 v105, v72, v72
	v_fmac_f32_e32 v104, v78, v78
	v_fmac_f32_e32 v105, v74, v74
	v_fmac_f32_e32 v104, v79, v79
	v_fmac_f32_e32 v105, v75, v75
	v_add_f32_e32 v104, v105, v104
	s_waitcnt vmcnt(1)
	v_mul_f32_e32 v105, v65, v65
	v_fmac_f32_e32 v105, v64, v64
	v_fmac_f32_e32 v105, v66, v66
	v_fmac_f32_e32 v105, v67, v67
	v_add_f32_e32 v104, v105, v104
	s_waitcnt vmcnt(0)
	v_mul_f32_e32 v105, v53, v53
	v_fmac_f32_e32 v105, v52, v52
	v_fmac_f32_e32 v105, v54, v54
	v_fmac_f32_e32 v105, v55, v55
	v_add_f32_e32 v104, v105, v104
	s_nop 0
	s_nop 0
	s_nop 0
	v_cndmask_b32_e64 v119, v106, 8, vcc
	v_cmp_ne_u32_e32 vcc, v119, v107
	s_waitcnt lgkmcnt(2)
	v_mov_b32_e32 v109, v103
	s_nop 1
	v_permlane32_swap_b32_e32 v103, v109
	v_add_f32_e32 v103, v103, v109
	s_waitcnt lgkmcnt(1)
	v_mov_b32_e32 v114, v102
	s_nop 1
	v_permlane32_swap_b32_e32 v102, v114
	v_add_f32_e32 v102, v102, v114
	s_waitcnt lgkmcnt(0)
	v_mov_b32_e32 v105, v104
	s_nop 1
	v_permlane32_swap_b32_e32 v104, v105
	v_add_f32_e32 v104, v104, v105
	ds_bpermute_b32 v109, v93, v103
	ds_bpermute_b32 v114, v93, v102
	ds_bpermute_b32 v105, v93, v104
	v_lshlrev_b32_e32 v106, 2, v88
	s_waitcnt lgkmcnt(2)
	v_add_f32_e32 v103, v103, v109
	s_waitcnt lgkmcnt(1)
	v_add_f32_e32 v102, v102, v114
	s_waitcnt lgkmcnt(0)
	v_add_f32_e32 v104, v104, v105
	s_nop 0
	s_nop 0
	s_nop 0
	s_waitcnt lgkmcnt(2)
	s_nop 1
	v_add_f32_dpp v103, v103, v103 row_ror:8 row_mask:0xf bank_mask:0xf
	s_waitcnt lgkmcnt(1)
	s_nop 1
	v_add_f32_dpp v102, v102, v102 row_ror:8 row_mask:0xf bank_mask:0xf
	s_waitcnt lgkmcnt(0)
	s_nop 1
	v_add_f32_dpp v104, v104, v104 row_ror:8 row_mask:0xf bank_mask:0xf
	s_nop 0
	s_nop 0
	s_nop 0
	s_waitcnt lgkmcnt(2)
	s_nop 1
	v_add_f32_dpp v103, v103, v103 row_ror:4 row_mask:0xf bank_mask:0xf
	s_waitcnt lgkmcnt(1)
	s_nop 1
	v_add_f32_dpp v102, v102, v102 row_ror:4 row_mask:0xf bank_mask:0xf
	s_waitcnt lgkmcnt(0)
	s_nop 1
	v_add_f32_dpp v104, v104, v104 row_ror:4 row_mask:0xf bank_mask:0xf
	s_nop 0
	s_nop 0
	s_nop 0
	s_waitcnt lgkmcnt(2)
	s_nop 1
	v_add_f32_dpp v109, v103, v103 row_ror:2 row_mask:0xf bank_mask:0xf
	s_waitcnt lgkmcnt(1)
	s_nop 1
	v_add_f32_dpp v116, v102, v102 row_ror:2 row_mask:0xf bank_mask:0xf
	s_waitcnt lgkmcnt(0)
	s_nop 1
	v_add_f32_dpp v114, v104, v104 row_ror:2 row_mask:0xf bank_mask:0xf
	ds_bpermute_b32 v118, v122, v109
	ds_bpermute_b32 v117, v122, v116
	ds_bpermute_b32 v115, v122, v114
	v_lshlrev_b32_e32 v104, 2, v92
	v_lshlrev_b32_e32 v102, 2, v96
	s_and_saveexec_b64 s[0:1], vcc
	s_cbranch_execz .LBB0_2692
	v_mul_hi_i32_i24_e32 v1, 0x6000, v119
	v_mul_i32_i24_e32 v0, 0x6000, v119
	v_lshl_add_u64 v[0:1], s[8:9], 0, v[0:1]
	v_lshl_add_u64 v[2:3], v[0:1], 0, s[12:13]
	v_lshl_add_u64 v[4:5], v[2:3], 0, v[82:83]
	v_mov_b32_e32 v107, v83
	global_load_dwordx4 v[16:19], v[4:5], off
	v_lshl_add_u64 v[4:5], v[2:3], 0, v[106:107]
	v_mov_b32_e32 v105, v83
	global_load_dwordx4 v[20:23], v[4:5], off
	v_lshl_add_u64 v[4:5], v[2:3], 0, v[104:105]
	v_mov_b32_e32 v103, v83
	global_load_dwordx4 v[24:27], v[4:5], off
	v_lshl_add_u64 v[2:3], v[2:3], 0, v[102:103]
	global_load_dwordx4 v[28:31], v[2:3], off
	global_load_dwordx4 v[124:127], v[86:87], off
	global_load_dwordx4 v[128:131], v[90:91], off
	v_lshl_add_u64 v[12:13], v[0:1], 0, v[82:83]
	global_load_dwordx4 v[132:135], v[94:95], off
	global_load_dwordx4 v[0:3], v[12:13], off
	global_load_dwordx4 v[136:139], v[98:99], off
	global_load_dwordx4 v[4:7], v[12:13], off offset:1024
	global_load_dwordx4 v[8:11], v[12:13], off offset:2048
	s_nop 0
	global_load_dwordx4 v[12:15], v[12:13], off offset:3072
	v_mov_b32_e32 v107, v119
	s_waitcnt vmcnt(11)
	v_pk_add_f32 v[18:19], v[18:19], 1.0 op_sel_hi:[1,0]
	v_pk_add_f32 v[16:17], v[16:17], 1.0 op_sel_hi:[1,0]
	s_waitcnt vmcnt(10)
	v_pk_add_f32 v[22:23], v[22:23], 1.0 op_sel_hi:[1,0]
	v_pk_add_f32 v[20:21], v[20:21], 1.0 op_sel_hi:[1,0]
	s_waitcnt vmcnt(9)
	v_pk_add_f32 v[26:27], v[26:27], 1.0 op_sel_hi:[1,0]
	v_pk_add_f32 v[24:25], v[24:25], 1.0 op_sel_hi:[1,0]
	s_waitcnt vmcnt(8)
	v_pk_add_f32 v[30:31], v[30:31], 1.0 op_sel_hi:[1,0]
	v_pk_add_f32 v[28:29], v[28:29], 1.0 op_sel_hi:[1,0]
	s_waitcnt vmcnt(7)
	v_pk_mul_f32 v[18:19], v[126:127], v[18:19]
	v_pk_mul_f32 v[16:17], v[124:125], v[16:17]
	s_waitcnt vmcnt(6)
	v_pk_mul_f32 v[22:23], v[130:131], v[22:23]
	v_pk_mul_f32 v[20:21], v[128:129], v[20:21]
	s_waitcnt vmcnt(5)
	v_pk_mul_f32 v[26:27], v[134:135], v[26:27]
	v_pk_mul_f32 v[24:25], v[132:133], v[24:25]
	s_waitcnt vmcnt(3)
	v_pk_mul_f32 v[30:31], v[138:139], v[30:31]
	v_pk_mul_f32 v[28:29], v[136:137], v[28:29]

; DI float wave_sum(float v) {
;     v += __shfl_xor(v, 32); v += __shfl_xor(v, 16); v += __shfl_xor(v, 8); v += __shfl_xor(v, 4); v += __shfl_xor(v, 2); v += __shfl_xor(v, 1);
;     return v;
; DI void norm_phase(const Params& p, int layer, int which, bool lat_only, const float* __restrict__ part, int npart, int srcmode) {
;     ...
;                 for (int j = 0; j < 4; ++j) ss[q] += v[q][j][0] * v[q][j][0] + v[q][j][1] * v[q][j][1] + v[q][j][2] * v[q][j][2] + v[q][j][3] * v[q][j][3];
;             }
;         }
;         ss[0] = wave_sum(ss[0]); ss[1] = wave_sum(ss[1]); ss[2] = wave_sum(ss[2]);
; #pragma unroll
;         for (int q = 0; q < 3; ++q) {
;             if (!ok[q]) continue;
;             const int row = r0 + 256 * q; const int ci = cond_idx(row);
;             if (ci != cur_ci) { cur_ci = ci; const float* mo = mod + (size_t)ci * 6144 + which * 3072;
; #pragma unroll
;                 for (int j = 0; j < 4; ++j) { const int col = j * 256 + lane * 4; gm[j] = *(const f32x4*)(gain + col) * (1.f + *(const f32x4*)(mo + 1024 + col)); sh[j] = *(const f32x4*)(mo + col); } }
.LBB0_2714:
	s_or_b64 exec, exec, s[14:15]
	s_waitcnt vmcnt(7)
	v_mul_f32_e32 v105, v69, v69
	s_waitcnt vmcnt(6)
	v_mul_f32_e32 v111, v61, v61
	v_fmac_f32_e32 v105, v68, v68
	v_fmac_f32_e32 v111, v60, v60
	v_fmac_f32_e32 v105, v70, v70
	v_fmac_f32_e32 v111, v62, v62
	v_fmac_f32_e32 v105, v71, v71
	v_fmac_f32_e32 v111, v63, v63
	v_add_f32_e32 v105, v111, v105
	s_waitcnt vmcnt(5)
	v_mul_f32_e32 v111, v49, v49
	v_fmac_f32_e32 v111, v48, v48
	v_fmac_f32_e32 v111, v50, v50
	v_fmac_f32_e32 v111, v51, v51
	v_add_f32_e32 v105, v111, v105
	s_waitcnt vmcnt(4)
	v_mul_f32_e32 v111, v41, v41
	v_fmac_f32_e32 v111, v40, v40
	v_fmac_f32_e32 v111, v42, v42
	v_fmac_f32_e32 v111, v43, v43
	v_add_f32_e32 v105, v111, v105
	v_mul_f32_e32 v111, v57, v57
	v_mul_f32_e32 v113, v45, v45
	v_fmac_f32_e32 v111, v56, v56
	v_fmac_f32_e32 v113, v44, v44
	v_fmac_f32_e32 v111, v58, v58
	v_fmac_f32_e32 v113, v46, v46
	v_fmac_f32_e32 v111, v59, v59
	v_fmac_f32_e32 v113, v47, v47
	v_add_f32_e32 v111, v113, v111
	v_mul_f32_e32 v113, v37, v37
	v_fmac_f32_e32 v113, v36, v36
	v_fmac_f32_e32 v113, v38, v38
	v_fmac_f32_e32 v113, v39, v39
	v_add_f32_e32 v111, v113, v111
	v_mul_f32_e32 v113, v33, v33
	v_fmac_f32_e32 v113, v32, v32
	v_fmac_f32_e32 v113, v34, v34
	v_fmac_f32_e32 v113, v35, v35
	v_add_f32_e32 v111, v113, v111
	s_waitcnt vmcnt(3)
	v_mul_f32_e32 v113, v77, v77
	s_waitcnt vmcnt(2)
	v_mul_f32_e32 v116, v73, v73
	v_fmac_f32_e32 v113, v76, v76
	v_fmac_f32_e32 v116, v72, v72
	v_fmac_f32_e32 v113, v78, v78
	v_fmac_f32_e32 v116, v74, v74
	v_fmac_f32_e32 v113, v79, v79
	v_fmac_f32_e32 v116, v75, v75
	v_add_f32_e32 v113, v116, v113
	s_waitcnt vmcnt(1)
	v_mul_f32_e32 v116, v65, v65
	v_fmac_f32_e32 v116, v64, v64
	v_fmac_f32_e32 v116, v66, v66
	v_fmac_f32_e32 v116, v67, v67
	v_add_f32_e32 v113, v116, v113
	s_waitcnt vmcnt(0)
	v_mul_f32_e32 v116, v53, v53
	v_fmac_f32_e32 v116, v52, v52
	v_fmac_f32_e32 v116, v54, v54
	v_fmac_f32_e32 v116, v55, v55
	v_add_f32_e32 v113, v116, v113
	s_nop 0
	s_nop 0
	s_nop 0
	s_waitcnt lgkmcnt(2)
	v_mov_b32_e32 v117, v111
	s_nop 1
	v_permlane32_swap_b32_e32 v111, v117
	v_add_f32_e32 v111, v111, v117
	s_waitcnt lgkmcnt(1)
	v_mov_b32_e32 v118, v105
	s_nop 1
	v_permlane32_swap_b32_e32 v105, v118
	v_add_f32_e32 v105, v105, v118
	s_waitcnt lgkmcnt(0)
	v_mov_b32_e32 v116, v113
	s_nop 1
	v_permlane32_swap_b32_e32 v113, v116
	v_add_f32_e32 v113, v113, v116
	ds_bpermute_b32 v117, v93, v111
	ds_bpermute_b32 v118, v93, v105
	ds_bpermute_b32 v116, v93, v113
	s_waitcnt lgkmcnt(2)
	v_add_f32_e32 v111, v111, v117
	s_waitcnt lgkmcnt(1)
	v_add_f32_e32 v105, v105, v118
	s_waitcnt lgkmcnt(0)
	v_add_f32_e32 v113, v113, v116
	s_nop 0
	s_nop 0
	s_nop 0
	s_waitcnt lgkmcnt(2)
	s_nop 1
	v_add_f32_dpp v111, v111, v111 row_ror:8 row_mask:0xf bank_mask:0xf
	s_waitcnt lgkmcnt(1)
	s_nop 1
	v_add_f32_dpp v105, v105, v105 row_ror:8 row_mask:0xf bank_mask:0xf
	s_waitcnt lgkmcnt(0)
	s_nop 1
	v_add_f32_dpp v113, v113, v113 row_ror:8 row_mask:0xf bank_mask:0xf
	s_nop 0
	s_nop 0
	s_nop 0
	s_waitcnt lgkmcnt(2)
	s_nop 1
	v_add_f32_dpp v111, v111, v111 row_ror:4 row_mask:0xf bank_mask:0xf
	s_waitcnt lgkmcnt(1)
	s_nop 1
	v_add_f32_dpp v105, v105, v105 row_ror:4 row_mask:0xf bank_mask:0xf
	s_waitcnt lgkmcnt(0)
	s_nop 1
	v_add_f32_dpp v116, v113, v113 row_ror:4 row_mask:0xf bank_mask:0xf
	s_nop 0
	s_nop 0
	s_nop 0
	s_waitcnt lgkmcnt(2)
	s_nop 1
	v_add_f32_dpp v111, v111, v111 row_ror:2 row_mask:0xf bank_mask:0xf
	s_waitcnt lgkmcnt(1)
	s_nop 1
	v_add_f32_dpp v113, v105, v105 row_ror:2 row_mask:0xf bank_mask:0xf
	s_waitcnt lgkmcnt(0)
	s_nop 1
	v_add_f32_dpp v116, v116, v116 row_ror:2 row_mask:0xf bank_mask:0xf
	ds_bpermute_b32 v119, v122, v111
	ds_bpermute_b32 v118, v122, v113
	ds_bpermute_b32 v117, v122, v116
	v_cndmask_b32_e64 v124, v103, 8, vcc
	v_cmp_ne_u32_e32 vcc, v124, v107
	s_and_saveexec_b64 s[0:1], vcc
	s_cbranch_execz .LBB0_2716
	v_mul_hi_i32_i24_e32 v1, 0x6000, v124
	v_mul_i32_i24_e32 v0, 0x6000, v124
	v_lshl_add_u64 v[0:1], s[8:9], 0, v[0:1]
	v_lshl_add_u64 v[2:3], v[0:1], 0, s[12:13]
	v_lshl_add_u64 v[4:5], v[2:3], 0, v[82:83]
	v_mov_b32_e32 v107, v83
	global_load_dwordx4 v[16:19], v[4:5], off
	v_lshl_add_u64 v[4:5], v[2:3], 0, v[106:107]
	v_mov_b32_e32 v105, v83
	global_load_dwordx4 v[20:23], v[4:5], off
	v_lshl_add_u64 v[4:5], v[2:3], 0, v[104:105]
	v_mov_b32_e32 v103, v83
	global_load_dwordx4 v[24:27], v[4:5], off
	v_lshl_add_u64 v[2:3], v[2:3], 0, v[102:103]
	global_load_dwordx4 v[28:31], v[2:3], off
	global_load_dwordx4 v[126:129], v[86:87], off
	global_load_dwordx4 v[130:133], v[90:91], off
	v_lshl_add_u64 v[12:13], v[0:1], 0, v[82:83]
	global_load_dwordx4 v[134:137], v[94:95], off
	global_load_dwordx4 v[0:3], v[12:13], off
	global_load_dwordx4 v[138:141], v[98:99], off
	global_load_dwordx4 v[4:7], v[12:13], off offset:1024
	global_load_dwordx4 v[8:11], v[12:13], off offset:2048
	s_nop 0
	global_load_dwordx4 v[12:15], v[12:13], off offset:3072
	v_mov_b32_e32 v107, v124
	s_waitcnt vmcnt(11)
	v_pk_add_f32 v[18:19], v[18:19], 1.0 op_sel_hi:[1,0]
	v_pk_add_f32 v[16:17], v[16:17], 1.0 op_sel_hi:[1,0]
	s_waitcnt vmcnt(10)
	v_pk_add_f32 v[22:23], v[22:23], 1.0 op_sel_hi:[1,0]
	v_pk_add_f32 v[20:21], v[20:21], 1.0 op_sel_hi:[1,0]
	s_waitcnt vmcnt(9)
	v_pk_add_f32 v[26:27], v[26:27], 1.0 op_sel_hi:[1,0]
	v_pk_add_f32 v[24:25], v[24:25], 1.0 op_sel_hi:[1,0]
	s_waitcnt vmcnt(8)
	v_pk_add_f32 v[30:31], v[30:31], 1.0 op_sel_hi:[1,0]
	v_pk_add_f32 v[28:29], v[28:29], 1.0 op_sel_hi:[1,0]
	s_waitcnt vmcnt(7)
	v_pk_mul_f32 v[18:19], v[128:129], v[18:19]
	v_pk_mul_f32 v[16:17], v[126:127], v[16:17]
	s_waitcnt vmcnt(6)
	v_pk_mul_f32 v[22:23], v[132:133], v[22:23]
	v_pk_mul_f32 v[20:21], v[130:131], v[20:21]
	s_waitcnt vmcnt(5)
	v_pk_mul_f32 v[26:27], v[136:137], v[26:27]
	v_pk_mul_f32 v[24:25], v[134:135], v[24:25]
	s_waitcnt vmcnt(3)
	v_pk_mul_f32 v[30:31], v[140:141], v[30:31]
	v_pk_mul_f32 v[28:29], v[138:139], v[28:29]

; DI float wave_sum(float v) {
;     v += __shfl_xor(v, 32); v += __shfl_xor(v, 16); v += __shfl_xor(v, 8); v += __shfl_xor(v, 4); v += __shfl_xor(v, 2); v += __shfl_xor(v, 1);
;     return v;
; DI void norm_phase(const Params& p, int layer, int which, bool lat_only, const float* __restrict__ part, int npart, int srcmode) {
;     ...
;                 for (int j = 0; j < 4; ++j) ss[q] += v[q][j][0] * v[q][j][0] + v[q][j][1] * v[q][j][1] + v[q][j][2] * v[q][j][2] + v[q][j][3] * v[q][j][3];
;             }
;         }
;         ss[0] = wave_sum(ss[0]); ss[1] = wave_sum(ss[1]); ss[2] = wave_sum(ss[2]);
; #pragma unroll
;         for (int q = 0; q < 3; ++q) {
;             if (!ok[q]) continue;
;             const int row = r0 + 256 * q; const int ci = cond_idx(row);
;             if (ci != cur_ci) { cur_ci = ci; const float* mo = mod + (size_t)ci * 6144 + which * 3072;
; #pragma unroll
;                 for (int j = 0; j < 4; ++j) { const int col = j * 256 + lane * 4; gm[j] = *(const f32x4*)(gain + col) * (1.f + *(const f32x4*)(mo + 1024 + col)); sh[j] = *(const f32x4*)(mo + col); } }
.LBB0_2738:
	s_or_b64 exec, exec, s[14:15]
	s_waitcnt vmcnt(7)
	v_mul_f32_e32 v105, v69, v69
	s_waitcnt vmcnt(6)
	v_mul_f32_e32 v111, v61, v61
	v_fmac_f32_e32 v105, v68, v68
	v_fmac_f32_e32 v111, v60, v60
	v_fmac_f32_e32 v105, v70, v70
	v_fmac_f32_e32 v111, v62, v62
	v_fmac_f32_e32 v105, v71, v71
	v_fmac_f32_e32 v111, v63, v63
	v_add_f32_e32 v105, v111, v105
	s_waitcnt vmcnt(5)
	v_mul_f32_e32 v111, v49, v49
	v_fmac_f32_e32 v111, v48, v48
	v_fmac_f32_e32 v111, v50, v50
	v_fmac_f32_e32 v111, v51, v51
	v_add_f32_e32 v105, v111, v105
	s_waitcnt vmcnt(4)
	v_mul_f32_e32 v111, v41, v41
	v_fmac_f32_e32 v111, v40, v40
	v_fmac_f32_e32 v111, v42, v42
	v_fmac_f32_e32 v111, v43, v43
	v_add_f32_e32 v105, v111, v105
	v_mul_f32_e32 v111, v57, v57
	v_mul_f32_e32 v113, v45, v45
	v_fmac_f32_e32 v111, v56, v56
	v_fmac_f32_e32 v113, v44, v44
	v_fmac_f32_e32 v111, v58, v58
	v_fmac_f32_e32 v113, v46, v46
	v_fmac_f32_e32 v111, v59, v59
	v_fmac_f32_e32 v113, v47, v47
	v_add_f32_e32 v111, v113, v111
	v_mul_f32_e32 v113, v37, v37
	v_fmac_f32_e32 v113, v36, v36
	v_fmac_f32_e32 v113, v38, v38
	v_fmac_f32_e32 v113, v39, v39
	v_add_f32_e32 v111, v113, v111
	v_mul_f32_e32 v113, v33, v33
	v_fmac_f32_e32 v113, v32, v32
	v_fmac_f32_e32 v113, v34, v34
	v_fmac_f32_e32 v113, v35, v35
	v_add_f32_e32 v111, v113, v111
	s_waitcnt vmcnt(3)
	v_mul_f32_e32 v113, v77, v77
	s_waitcnt vmcnt(2)
	v_mul_f32_e32 v114, v73, v73
	v_fmac_f32_e32 v113, v76, v76
	v_fmac_f32_e32 v114, v72, v72
	v_fmac_f32_e32 v113, v78, v78
	v_fmac_f32_e32 v114, v74, v74
	v_fmac_f32_e32 v113, v79, v79
	v_fmac_f32_e32 v114, v75, v75
	v_add_f32_e32 v113, v114, v113
	s_waitcnt vmcnt(1)
	v_mul_f32_e32 v114, v65, v65
	v_fmac_f32_e32 v114, v64, v64
	v_fmac_f32_e32 v114, v66, v66
	v_fmac_f32_e32 v114, v67, v67
	v_add_f32_e32 v113, v114, v113
	s_waitcnt vmcnt(0)
	v_mul_f32_e32 v114, v53, v53
	v_fmac_f32_e32 v114, v52, v52
	v_fmac_f32_e32 v114, v54, v54
	v_fmac_f32_e32 v114, v55, v55
	v_add_f32_e32 v113, v114, v113
	s_nop 0
	s_nop 0
	s_nop 0
	s_waitcnt lgkmcnt(2)
	v_mov_b32_e32 v115, v111
	s_nop 1
	v_permlane32_swap_b32_e32 v111, v115
	v_add_f32_e32 v111, v111, v115
	s_waitcnt lgkmcnt(1)
	v_mov_b32_e32 v116, v105
	s_nop 1
	v_permlane32_swap_b32_e32 v105, v116
	v_add_f32_e32 v105, v105, v116
	s_waitcnt lgkmcnt(0)
	v_mov_b32_e32 v114, v113
	s_nop 1
	v_permlane32_swap_b32_e32 v113, v114
	v_add_f32_e32 v113, v113, v114
	ds_bpermute_b32 v115, v93, v111
	ds_bpermute_b32 v116, v93, v105
	ds_bpermute_b32 v114, v93, v113
	s_waitcnt lgkmcnt(2)
	v_add_f32_e32 v111, v111, v115
	s_waitcnt lgkmcnt(1)
	v_add_f32_e32 v105, v105, v116
	s_waitcnt lgkmcnt(0)
	v_add_f32_e32 v113, v113, v114
	s_nop 0
	s_nop 0
	s_nop 0
	s_waitcnt lgkmcnt(2)
	s_nop 1
	v_add_f32_dpp v111, v111, v111 row_ror:8 row_mask:0xf bank_mask:0xf
	s_waitcnt lgkmcnt(1)
	s_nop 1
	v_add_f32_dpp v105, v105, v105 row_ror:8 row_mask:0xf bank_mask:0xf
	s_waitcnt lgkmcnt(0)
	s_nop 1
	v_add_f32_dpp v113, v113, v113 row_ror:8 row_mask:0xf bank_mask:0xf
	s_nop 0
	s_nop 0
	s_nop 0
	s_waitcnt lgkmcnt(2)
	s_nop 1
	v_add_f32_dpp v111, v111, v111 row_ror:4 row_mask:0xf bank_mask:0xf
	s_waitcnt lgkmcnt(1)
	s_nop 1
	v_add_f32_dpp v105, v105, v105 row_ror:4 row_mask:0xf bank_mask:0xf
	s_waitcnt lgkmcnt(0)
	s_nop 1
	v_add_f32_dpp v114, v113, v113 row_ror:4 row_mask:0xf bank_mask:0xf
	s_nop 0
	s_nop 0
	s_nop 0
	s_waitcnt lgkmcnt(2)
	s_nop 1
	v_add_f32_dpp v111, v111, v111 row_ror:2 row_mask:0xf bank_mask:0xf
	s_waitcnt lgkmcnt(1)
	s_nop 1
	v_add_f32_dpp v113, v105, v105 row_ror:2 row_mask:0xf bank_mask:0xf
	s_waitcnt lgkmcnt(0)
	s_nop 1
	v_add_f32_dpp v114, v114, v114 row_ror:2 row_mask:0xf bank_mask:0xf
	ds_bpermute_b32 v117, v122, v111
	ds_bpermute_b32 v116, v122, v113
	ds_bpermute_b32 v115, v122, v114
	v_cndmask_b32_e64 v119, v103, 8, vcc
	v_cmp_ne_u32_e32 vcc, v119, v107
	s_and_saveexec_b64 s[0:1], vcc
	s_cbranch_execz .LBB0_2740
	v_mul_hi_i32_i24_e32 v1, 0x6000, v119
	v_mul_i32_i24_e32 v0, 0x6000, v119
	v_lshl_add_u64 v[0:1], s[8:9], 0, v[0:1]
	v_lshl_add_u64 v[2:3], v[0:1], 0, s[12:13]
	v_lshl_add_u64 v[4:5], v[2:3], 0, v[82:83]
	v_mov_b32_e32 v107, v83
	global_load_dwordx4 v[16:19], v[4:5], off
	v_lshl_add_u64 v[4:5], v[2:3], 0, v[106:107]
	v_mov_b32_e32 v105, v83
	global_load_dwordx4 v[20:23], v[4:5], off
	v_lshl_add_u64 v[4:5], v[2:3], 0, v[104:105]
	v_mov_b32_e32 v103, v83
	global_load_dwordx4 v[24:27], v[4:5], off
	v_lshl_add_u64 v[2:3], v[2:3], 0, v[102:103]
	global_load_dwordx4 v[28:31], v[2:3], off
	global_load_dwordx4 v[124:127], v[86:87], off
	global_load_dwordx4 v[128:131], v[90:91], off
	v_lshl_add_u64 v[12:13], v[0:1], 0, v[82:83]
	global_load_dwordx4 v[132:135], v[94:95], off
	global_load_dwordx4 v[0:3], v[12:13], off
	global_load_dwordx4 v[136:139], v[98:99], off
	global_load_dwordx4 v[4:7], v[12:13], off offset:1024
	global_load_dwordx4 v[8:11], v[12:13], off offset:2048
	s_nop 0
	global_load_dwordx4 v[12:15], v[12:13], off offset:3072
	v_mov_b32_e32 v107, v119
	s_waitcnt vmcnt(11)
	v_pk_add_f32 v[18:19], v[18:19], 1.0 op_sel_hi:[1,0]
	v_pk_add_f32 v[16:17], v[16:17], 1.0 op_sel_hi:[1,0]
	s_waitcnt vmcnt(10)
	v_pk_add_f32 v[22:23], v[22:23], 1.0 op_sel_hi:[1,0]
	v_pk_add_f32 v[20:21], v[20:21], 1.0 op_sel_hi:[1,0]
	s_waitcnt vmcnt(9)
	v_pk_add_f32 v[26:27], v[26:27], 1.0 op_sel_hi:[1,0]
	v_pk_add_f32 v[24:25], v[24:25], 1.0 op_sel_hi:[1,0]
	s_waitcnt vmcnt(8)
	v_pk_add_f32 v[30:31], v[30:31], 1.0 op_sel_hi:[1,0]
	v_pk_add_f32 v[28:29], v[28:29], 1.0 op_sel_hi:[1,0]
	s_waitcnt vmcnt(7)
	v_pk_mul_f32 v[18:19], v[126:127], v[18:19]
	v_pk_mul_f32 v[16:17], v[124:125], v[16:17]
	s_waitcnt vmcnt(6)
	v_pk_mul_f32 v[22:23], v[130:131], v[22:23]
	v_pk_mul_f32 v[20:21], v[128:129], v[20:21]
	s_waitcnt vmcnt(5)
	v_pk_mul_f32 v[26:27], v[134:135], v[26:27]
	v_pk_mul_f32 v[24:25], v[132:133], v[24:25]
	s_waitcnt vmcnt(3)
	v_pk_mul_f32 v[30:31], v[138:139], v[30:31]
	v_pk_mul_f32 v[28:29], v[136:137], v[28:29]

; DI float wave_sum(float v) {
;     v += __shfl_xor(v, 32); v += __shfl_xor(v, 16); v += __shfl_xor(v, 8); v += __shfl_xor(v, 4); v += __shfl_xor(v, 2); v += __shfl_xor(v, 1);
;     return v;
; DI void norm_phase(const Params& p, int layer, int which, bool lat_only, const float* __restrict__ part, int npart, int srcmode) {
;     ...
;                 for (int j = 0; j < 4; ++j) ss[q] += v[q][j][0] * v[q][j][0] + v[q][j][1] * v[q][j][1] + v[q][j][2] * v[q][j][2] + v[q][j][3] * v[q][j][3];
;             }
;         }
;         ss[0] = wave_sum(ss[0]); ss[1] = wave_sum(ss[1]); ss[2] = wave_sum(ss[2]);
; #pragma unroll
;         for (int q = 0; q < 3; ++q) {
;             if (!ok[q]) continue;
;             const int row = r0 + 256 * q; const int ci = cond_idx(row);
;             if (ci != cur_ci) { cur_ci = ci; const float* mo = mod + (size_t)ci * 6144 + which * 3072;
; #pragma unroll
;                 for (int j = 0; j < 4; ++j) { const int col = j * 256 + lane * 4; gm[j] = *(const f32x4*)(gain + col) * (1.f + *(const f32x4*)(mo + 1024 + col)); sh[j] = *(const f32x4*)(mo + col); } }
.LBB0_3018:
	s_or_b64 exec, exec, s[14:15]
	s_waitcnt vmcnt(7)
	v_mul_f32_e32 v104, v61, v61
	s_waitcnt vmcnt(6)
	v_mul_f32_e32 v105, v57, v57
	v_fmac_f32_e32 v104, v60, v60
	v_fmac_f32_e32 v105, v56, v56
	v_fmac_f32_e32 v104, v62, v62
	v_fmac_f32_e32 v105, v58, v58
	v_fmac_f32_e32 v104, v63, v63
	v_fmac_f32_e32 v105, v59, v59
	v_add_f32_e32 v104, v105, v104
	s_waitcnt vmcnt(5)
	v_mul_f32_e32 v105, v53, v53
	v_fmac_f32_e32 v105, v52, v52
	v_fmac_f32_e32 v105, v54, v54
	v_fmac_f32_e32 v105, v55, v55
	v_add_f32_e32 v104, v105, v104
	s_waitcnt vmcnt(4)
	v_mul_f32_e32 v105, v49, v49
	v_fmac_f32_e32 v105, v48, v48
	v_fmac_f32_e32 v105, v50, v50
	v_fmac_f32_e32 v105, v51, v51
	v_add_f32_e32 v104, v105, v104
	v_mul_f32_e32 v105, v45, v45
	v_mul_f32_e32 v106, v41, v41
	v_fmac_f32_e32 v105, v44, v44
	v_fmac_f32_e32 v106, v40, v40
	v_fmac_f32_e32 v105, v46, v46
	v_fmac_f32_e32 v106, v42, v42
	v_fmac_f32_e32 v105, v47, v47
	v_fmac_f32_e32 v106, v43, v43
	v_add_f32_e32 v105, v106, v105
	v_mul_f32_e32 v106, v37, v37
	v_fmac_f32_e32 v106, v36, v36
	v_fmac_f32_e32 v106, v38, v38
	v_fmac_f32_e32 v106, v39, v39
	v_add_f32_e32 v105, v106, v105
	v_mul_f32_e32 v106, v33, v33
	v_fmac_f32_e32 v106, v32, v32
	v_fmac_f32_e32 v106, v34, v34
	v_fmac_f32_e32 v106, v35, v35
	v_add_f32_e32 v105, v106, v105
	s_waitcnt vmcnt(3)
	v_mul_f32_e32 v106, v77, v77
	s_waitcnt vmcnt(2)
	v_mul_f32_e32 v107, v73, v73
	v_fmac_f32_e32 v106, v76, v76
	v_fmac_f32_e32 v107, v72, v72
	v_fmac_f32_e32 v106, v78, v78
	v_fmac_f32_e32 v107, v74, v74
	v_fmac_f32_e32 v106, v79, v79
	v_fmac_f32_e32 v107, v75, v75
	v_add_f32_e32 v106, v107, v106
	s_waitcnt vmcnt(1)
	v_mul_f32_e32 v107, v69, v69
	v_fmac_f32_e32 v107, v68, v68
	v_fmac_f32_e32 v107, v70, v70
	v_fmac_f32_e32 v107, v71, v71
	v_add_f32_e32 v106, v107, v106
	s_waitcnt vmcnt(0)
	v_mul_f32_e32 v107, v65, v65
	v_fmac_f32_e32 v107, v64, v64
	v_fmac_f32_e32 v107, v66, v66
	v_fmac_f32_e32 v107, v67, v67
	v_add_f32_e32 v106, v107, v106
	s_nop 0
	s_nop 0
	s_nop 0
	v_cndmask_b32_e64 v103, v103, 8, vcc
	v_cmp_ne_u32_e32 vcc, v103, v109
	s_waitcnt lgkmcnt(2)
	v_mov_b32_e32 v108, v105
	s_nop 1
	v_permlane32_swap_b32_e32 v105, v108
	v_add_f32_e32 v105, v105, v108
	s_waitcnt lgkmcnt(1)
	v_mov_b32_e32 v114, v104
	s_nop 1
	v_permlane32_swap_b32_e32 v104, v114
	v_add_f32_e32 v104, v104, v114
	s_waitcnt lgkmcnt(0)
	v_mov_b32_e32 v107, v106
	s_nop 1
	v_permlane32_swap_b32_e32 v106, v107
	v_add_f32_e32 v106, v106, v107
	ds_bpermute_b32 v108, v93, v105
	ds_bpermute_b32 v114, v93, v104
	ds_bpermute_b32 v107, v93, v106
	s_waitcnt lgkmcnt(2)
	v_add_f32_e32 v105, v105, v108
	s_waitcnt lgkmcnt(1)
	v_add_f32_e32 v104, v104, v114
	s_waitcnt lgkmcnt(0)
	v_add_f32_e32 v106, v106, v107
	s_nop 0
	s_nop 0
	s_nop 0
	s_waitcnt lgkmcnt(2)
	s_nop 1
	v_add_f32_dpp v105, v105, v105 row_ror:8 row_mask:0xf bank_mask:0xf
	s_waitcnt lgkmcnt(1)
	s_nop 1
	v_add_f32_dpp v104, v104, v104 row_ror:8 row_mask:0xf bank_mask:0xf
	s_waitcnt lgkmcnt(0)
	s_nop 1
	v_add_f32_dpp v106, v106, v106 row_ror:8 row_mask:0xf bank_mask:0xf
	s_nop 0
	s_nop 0
	s_nop 0
	s_waitcnt lgkmcnt(2)
	s_nop 1
	v_add_f32_dpp v105, v105, v105 row_ror:4 row_mask:0xf bank_mask:0xf
	s_waitcnt lgkmcnt(1)
	s_nop 1
	v_add_f32_dpp v104, v104, v104 row_ror:4 row_mask:0xf bank_mask:0xf
	s_waitcnt lgkmcnt(0)
	s_nop 1
	v_add_f32_dpp v106, v106, v106 row_ror:4 row_mask:0xf bank_mask:0xf
	s_nop 0
	s_nop 0
	s_nop 0
	s_waitcnt lgkmcnt(2)
	s_nop 1
	v_add_f32_dpp v118, v105, v105 row_ror:2 row_mask:0xf bank_mask:0xf
	s_waitcnt lgkmcnt(1)
	s_nop 1
	v_add_f32_dpp v116, v104, v104 row_ror:2 row_mask:0xf bank_mask:0xf
	s_waitcnt lgkmcnt(0)
	s_nop 1
	v_add_f32_dpp v114, v106, v106 row_ror:2 row_mask:0xf bank_mask:0xf
	ds_bpermute_b32 v119, v122, v118
	ds_bpermute_b32 v117, v122, v116
	ds_bpermute_b32 v115, v122, v114
	v_lshlrev_b32_e32 v108, 2, v88
	v_lshlrev_b32_e32 v106, 2, v92
	v_lshlrev_b32_e32 v104, 2, v96
	s_and_saveexec_b64 s[0:1], vcc
	s_cbranch_execz .LBB0_3020
	v_mul_hi_i32_i24_e32 v1, 0x6000, v103
	v_mul_i32_i24_e32 v0, 0x6000, v103
	v_lshl_add_u64 v[0:1], s[8:9], 0, v[0:1]
	v_lshl_add_u64 v[2:3], v[0:1], 0, s[12:13]
	v_lshl_add_u64 v[4:5], v[2:3], 0, v[82:83]
	v_mov_b32_e32 v109, v83
	global_load_dwordx4 v[16:19], v[4:5], off
	v_lshl_add_u64 v[4:5], v[2:3], 0, v[108:109]
	v_mov_b32_e32 v107, v83
	global_load_dwordx4 v[20:23], v[4:5], off
	v_lshl_add_u64 v[4:5], v[2:3], 0, v[106:107]
	v_mov_b32_e32 v105, v83
	global_load_dwordx4 v[24:27], v[4:5], off
	v_lshl_add_u64 v[2:3], v[2:3], 0, v[104:105]
	global_load_dwordx4 v[28:31], v[2:3], off
	global_load_dwordx4 v[124:127], v[86:87], off
	global_load_dwordx4 v[128:131], v[90:91], off
	v_lshl_add_u64 v[12:13], v[0:1], 0, v[82:83]
	global_load_dwordx4 v[132:135], v[94:95], off
	global_load_dwordx4 v[0:3], v[12:13], off
	global_load_dwordx4 v[136:139], v[98:99], off
	global_load_dwordx4 v[4:7], v[12:13], off offset:1024
	global_load_dwordx4 v[8:11], v[12:13], off offset:2048
	s_nop 0
	global_load_dwordx4 v[12:15], v[12:13], off offset:3072
	v_mov_b32_e32 v109, v103
	s_waitcnt vmcnt(11)
	v_pk_add_f32 v[18:19], v[18:19], 1.0 op_sel_hi:[1,0]
	v_pk_add_f32 v[16:17], v[16:17], 1.0 op_sel_hi:[1,0]
	s_waitcnt vmcnt(10)
	v_pk_add_f32 v[22:23], v[22:23], 1.0 op_sel_hi:[1,0]
	v_pk_add_f32 v[20:21], v[20:21], 1.0 op_sel_hi:[1,0]
	s_waitcnt vmcnt(9)
	v_pk_add_f32 v[26:27], v[26:27], 1.0 op_sel_hi:[1,0]
	v_pk_add_f32 v[24:25], v[24:25], 1.0 op_sel_hi:[1,0]
	s_waitcnt vmcnt(8)
	v_pk_add_f32 v[30:31], v[30:31], 1.0 op_sel_hi:[1,0]
	v_pk_add_f32 v[28:29], v[28:29], 1.0 op_sel_hi:[1,0]
	s_waitcnt vmcnt(7)
	v_pk_mul_f32 v[18:19], v[126:127], v[18:19]
	v_pk_mul_f32 v[16:17], v[124:125], v[16:17]
	s_waitcnt vmcnt(6)
	v_pk_mul_f32 v[22:23], v[130:131], v[22:23]
	v_pk_mul_f32 v[20:21], v[128:129], v[20:21]
	s_waitcnt vmcnt(5)
	v_pk_mul_f32 v[26:27], v[134:135], v[26:27]
	v_pk_mul_f32 v[24:25], v[132:133], v[24:25]
	s_waitcnt vmcnt(3)
	v_pk_mul_f32 v[30:31], v[138:139], v[30:31]
	v_pk_mul_f32 v[28:29], v[136:137], v[28:29]

; DI float wave_sum(float v) {
;     v += __shfl_xor(v, 32); v += __shfl_xor(v, 16); v += __shfl_xor(v, 8); v += __shfl_xor(v, 4); v += __shfl_xor(v, 2); v += __shfl_xor(v, 1);
;     return v;
; DI void norm_phase(const Params& p, int layer, int which, bool lat_only, const float* __restrict__ part, int npart, int srcmode) {
;     ...
;                 for (int j = 0; j < 4; ++j) ss[q] += v[q][j][0] * v[q][j][0] + v[q][j][1] * v[q][j][1] + v[q][j][2] * v[q][j][2] + v[q][j][3] * v[q][j][3];
;             }
;         }
;         ss[0] = wave_sum(ss[0]); ss[1] = wave_sum(ss[1]); ss[2] = wave_sum(ss[2]);
; #pragma unroll
;         for (int q = 0; q < 3; ++q) {
;             if (!ok[q]) continue;
;             const int row = r0 + 256 * q; const int ci = cond_idx(row);
;             if (ci != cur_ci) { cur_ci = ci; const float* mo = mod + (size_t)ci * 6144 + which * 3072;
; #pragma unroll
;                 for (int j = 0; j < 4; ++j) { const int col = j * 256 + lane * 4; gm[j] = *(const f32x4*)(gain + col) * (1.f + *(const f32x4*)(mo + 1024 + col)); sh[j] = *(const f32x4*)(mo + col); } }
.LBB0_3042:
	s_or_b64 exec, exec, s[14:15]
	s_waitcnt vmcnt(7)
	v_mul_f32_e32 v105, v61, v61
	s_waitcnt vmcnt(6)
	v_mul_f32_e32 v107, v57, v57
	v_fmac_f32_e32 v105, v60, v60
	v_fmac_f32_e32 v107, v56, v56
	v_fmac_f32_e32 v105, v62, v62
	v_fmac_f32_e32 v107, v58, v58
	v_fmac_f32_e32 v105, v63, v63
	v_fmac_f32_e32 v107, v59, v59
	v_add_f32_e32 v105, v107, v105
	s_waitcnt vmcnt(5)
	v_mul_f32_e32 v107, v53, v53
	v_fmac_f32_e32 v107, v52, v52
	v_fmac_f32_e32 v107, v54, v54
	v_fmac_f32_e32 v107, v55, v55
	v_add_f32_e32 v105, v107, v105
	s_waitcnt vmcnt(4)
	v_mul_f32_e32 v107, v49, v49
	v_fmac_f32_e32 v107, v48, v48
	v_fmac_f32_e32 v107, v50, v50
	v_fmac_f32_e32 v107, v51, v51
	v_add_f32_e32 v105, v107, v105
	v_mul_f32_e32 v107, v45, v45
	v_mul_f32_e32 v111, v41, v41
	v_fmac_f32_e32 v107, v44, v44
	v_fmac_f32_e32 v111, v40, v40
	v_fmac_f32_e32 v107, v46, v46
	v_fmac_f32_e32 v111, v42, v42
	v_fmac_f32_e32 v107, v47, v47
	v_fmac_f32_e32 v111, v43, v43
	v_add_f32_e32 v107, v111, v107
	v_mul_f32_e32 v111, v37, v37
	v_fmac_f32_e32 v111, v36, v36
	v_fmac_f32_e32 v111, v38, v38
	v_fmac_f32_e32 v111, v39, v39
	v_add_f32_e32 v107, v111, v107
	v_mul_f32_e32 v111, v33, v33
	v_fmac_f32_e32 v111, v32, v32
	v_fmac_f32_e32 v111, v34, v34
	v_fmac_f32_e32 v111, v35, v35
	v_add_f32_e32 v107, v111, v107
	s_waitcnt vmcnt(3)
	v_mul_f32_e32 v111, v77, v77
	s_waitcnt vmcnt(2)
	v_mul_f32_e32 v116, v73, v73
	v_fmac_f32_e32 v111, v76, v76
	v_fmac_f32_e32 v116, v72, v72
	v_fmac_f32_e32 v111, v78, v78
	v_fmac_f32_e32 v116, v74, v74
	v_fmac_f32_e32 v111, v79, v79
	v_fmac_f32_e32 v116, v75, v75
	v_add_f32_e32 v111, v116, v111
	s_waitcnt vmcnt(1)
	v_mul_f32_e32 v116, v69, v69
	v_fmac_f32_e32 v116, v68, v68
	v_fmac_f32_e32 v116, v70, v70
	v_fmac_f32_e32 v116, v71, v71
	v_add_f32_e32 v111, v116, v111
	s_waitcnt vmcnt(0)
	v_mul_f32_e32 v116, v65, v65
	v_fmac_f32_e32 v116, v64, v64
	v_fmac_f32_e32 v116, v66, v66
	v_fmac_f32_e32 v116, v67, v67
	v_add_f32_e32 v111, v116, v111
	s_nop 0
	s_nop 0
	s_nop 0
	v_cndmask_b32_e64 v103, v103, 8, vcc
	v_cmp_ne_u32_e32 vcc, v103, v109
	s_waitcnt lgkmcnt(2)
	v_mov_b32_e32 v117, v107
	s_nop 1
	v_permlane32_swap_b32_e32 v107, v117
	v_add_f32_e32 v107, v107, v117
	s_waitcnt lgkmcnt(1)
	v_mov_b32_e32 v118, v105
	s_nop 1
	v_permlane32_swap_b32_e32 v105, v118
	v_add_f32_e32 v105, v105, v118
	s_waitcnt lgkmcnt(0)
	v_mov_b32_e32 v116, v111
	s_nop 1
	v_permlane32_swap_b32_e32 v111, v116
	v_add_f32_e32 v111, v111, v116
	ds_bpermute_b32 v117, v93, v107
	ds_bpermute_b32 v118, v93, v105
	ds_bpermute_b32 v116, v93, v111
	s_waitcnt lgkmcnt(2)
	v_add_f32_e32 v107, v107, v117
	s_waitcnt lgkmcnt(1)
	v_add_f32_e32 v105, v105, v118
	s_waitcnt lgkmcnt(0)
	v_add_f32_e32 v111, v111, v116
	s_nop 0
	s_nop 0
	s_nop 0
	s_waitcnt lgkmcnt(2)
	s_nop 1
	v_add_f32_dpp v107, v107, v107 row_ror:8 row_mask:0xf bank_mask:0xf
	s_waitcnt lgkmcnt(1)
	s_nop 1
	v_add_f32_dpp v105, v105, v105 row_ror:8 row_mask:0xf bank_mask:0xf
	s_waitcnt lgkmcnt(0)
	s_nop 1
	v_add_f32_dpp v111, v111, v111 row_ror:8 row_mask:0xf bank_mask:0xf
	s_nop 0
	s_nop 0
	s_nop 0
	s_waitcnt lgkmcnt(2)
	s_nop 1
	v_add_f32_dpp v107, v107, v107 row_ror:4 row_mask:0xf bank_mask:0xf
	s_waitcnt lgkmcnt(1)
	s_nop 1
	v_add_f32_dpp v105, v105, v105 row_ror:4 row_mask:0xf bank_mask:0xf
	s_waitcnt lgkmcnt(0)
	s_nop 1
	v_add_f32_dpp v116, v111, v111 row_ror:4 row_mask:0xf bank_mask:0xf
	s_nop 0
	s_nop 0
	s_nop 0
	s_waitcnt lgkmcnt(2)
	s_nop 1
	v_add_f32_dpp v111, v107, v107 row_ror:2 row_mask:0xf bank_mask:0xf
	s_waitcnt lgkmcnt(1)
	s_nop 1
	v_add_f32_dpp v118, v105, v105 row_ror:2 row_mask:0xf bank_mask:0xf
	s_waitcnt lgkmcnt(0)
	s_nop 1
	v_add_f32_dpp v116, v116, v116 row_ror:2 row_mask:0xf bank_mask:0xf
	ds_bpermute_b32 v124, v122, v111
	ds_bpermute_b32 v119, v122, v118
	ds_bpermute_b32 v117, v122, v116
	s_and_saveexec_b64 s[0:1], vcc
	s_cbranch_execz .LBB0_3044
	v_mul_hi_i32_i24_e32 v1, 0x6000, v103
	v_mul_i32_i24_e32 v0, 0x6000, v103
	v_lshl_add_u64 v[0:1], s[8:9], 0, v[0:1]
	v_lshl_add_u64 v[2:3], v[0:1], 0, s[12:13]
	v_lshl_add_u64 v[4:5], v[2:3], 0, v[82:83]
	v_mov_b32_e32 v109, v83
	global_load_dwordx4 v[16:19], v[4:5], off
	v_lshl_add_u64 v[4:5], v[2:3], 0, v[108:109]
	v_mov_b32_e32 v107, v83
	global_load_dwordx4 v[20:23], v[4:5], off
	v_lshl_add_u64 v[4:5], v[2:3], 0, v[106:107]
	v_mov_b32_e32 v105, v83
	global_load_dwordx4 v[24:27], v[4:5], off
	v_lshl_add_u64 v[2:3], v[2:3], 0, v[104:105]
	global_load_dwordx4 v[28:31], v[2:3], off
	global_load_dwordx4 v[126:129], v[86:87], off
	global_load_dwordx4 v[130:133], v[90:91], off
	v_lshl_add_u64 v[12:13], v[0:1], 0, v[82:83]
	global_load_dwordx4 v[134:137], v[94:95], off
	global_load_dwordx4 v[0:3], v[12:13], off
	global_load_dwordx4 v[138:141], v[98:99], off
	global_load_dwordx4 v[4:7], v[12:13], off offset:1024
	global_load_dwordx4 v[8:11], v[12:13], off offset:2048
	s_nop 0
	global_load_dwordx4 v[12:15], v[12:13], off offset:3072
	v_mov_b32_e32 v109, v103
	s_waitcnt vmcnt(11)
	v_pk_add_f32 v[18:19], v[18:19], 1.0 op_sel_hi:[1,0]
	v_pk_add_f32 v[16:17], v[16:17], 1.0 op_sel_hi:[1,0]
	s_waitcnt vmcnt(10)
	v_pk_add_f32 v[22:23], v[22:23], 1.0 op_sel_hi:[1,0]
	v_pk_add_f32 v[20:21], v[20:21], 1.0 op_sel_hi:[1,0]
	s_waitcnt vmcnt(9)
	v_pk_add_f32 v[26:27], v[26:27], 1.0 op_sel_hi:[1,0]
	v_pk_add_f32 v[24:25], v[24:25], 1.0 op_sel_hi:[1,0]
	s_waitcnt vmcnt(8)
	v_pk_add_f32 v[30:31], v[30:31], 1.0 op_sel_hi:[1,0]
	v_pk_add_f32 v[28:29], v[28:29], 1.0 op_sel_hi:[1,0]
	s_waitcnt vmcnt(7)
	v_pk_mul_f32 v[18:19], v[128:129], v[18:19]
	v_pk_mul_f32 v[16:17], v[126:127], v[16:17]
	s_waitcnt vmcnt(6)
	v_pk_mul_f32 v[22:23], v[132:133], v[22:23]
	v_pk_mul_f32 v[20:21], v[130:131], v[20:21]
	s_waitcnt vmcnt(5)
	v_pk_mul_f32 v[26:27], v[136:137], v[26:27]
	v_pk_mul_f32 v[24:25], v[134:135], v[24:25]
	s_waitcnt vmcnt(3)
	v_pk_mul_f32 v[30:31], v[140:141], v[30:31]
	v_pk_mul_f32 v[28:29], v[138:139], v[28:29]

; DI float wave_sum(float v) {
;     v += __shfl_xor(v, 32); v += __shfl_xor(v, 16); v += __shfl_xor(v, 8); v += __shfl_xor(v, 4); v += __shfl_xor(v, 2); v += __shfl_xor(v, 1);
;     return v;
; DI void norm_phase(const Params& p, int layer, int which, bool lat_only, const float* __restrict__ part, int npart, int srcmode) {
;     ...
;                 for (int j = 0; j < 4; ++j) ss[q] += v[q][j][0] * v[q][j][0] + v[q][j][1] * v[q][j][1] + v[q][j][2] * v[q][j][2] + v[q][j][3] * v[q][j][3];
;             }
;         }
;         ss[0] = wave_sum(ss[0]); ss[1] = wave_sum(ss[1]); ss[2] = wave_sum(ss[2]);
; #pragma unroll
;         for (int q = 0; q < 3; ++q) {
;             if (!ok[q]) continue;
;             const int row = r0 + 256 * q; const int ci = cond_idx(row);
;             if (ci != cur_ci) { cur_ci = ci; const float* mo = mod + (size_t)ci * 6144 + which * 3072;
; #pragma unroll
;                 for (int j = 0; j < 4; ++j) { const int col = j * 256 + lane * 4; gm[j] = *(const f32x4*)(gain + col) * (1.f + *(const f32x4*)(mo + 1024 + col)); sh[j] = *(const f32x4*)(mo + col); } }
.LBB0_3066:
	s_or_b64 exec, exec, s[14:15]
	s_waitcnt vmcnt(7)
	v_mul_f32_e32 v105, v61, v61
	s_waitcnt vmcnt(6)
	v_mul_f32_e32 v107, v57, v57
	v_fmac_f32_e32 v105, v60, v60
	v_fmac_f32_e32 v107, v56, v56
	v_fmac_f32_e32 v105, v62, v62
	v_fmac_f32_e32 v107, v58, v58
	v_fmac_f32_e32 v105, v63, v63
	v_fmac_f32_e32 v107, v59, v59
	v_add_f32_e32 v105, v107, v105
	s_waitcnt vmcnt(5)
	v_mul_f32_e32 v107, v53, v53
	v_fmac_f32_e32 v107, v52, v52
	v_fmac_f32_e32 v107, v54, v54
	v_fmac_f32_e32 v107, v55, v55
	v_add_f32_e32 v105, v107, v105
	s_waitcnt vmcnt(4)
	v_mul_f32_e32 v107, v49, v49
	v_fmac_f32_e32 v107, v48, v48
	v_fmac_f32_e32 v107, v50, v50
	v_fmac_f32_e32 v107, v51, v51
	v_add_f32_e32 v105, v107, v105
	v_mul_f32_e32 v107, v45, v45
	v_mul_f32_e32 v111, v41, v41
	v_fmac_f32_e32 v107, v44, v44
	v_fmac_f32_e32 v111, v40, v40
	v_fmac_f32_e32 v107, v46, v46
	v_fmac_f32_e32 v111, v42, v42
	v_fmac_f32_e32 v107, v47, v47
	v_fmac_f32_e32 v111, v43, v43
	v_add_f32_e32 v107, v111, v107
	v_mul_f32_e32 v111, v37, v37
	v_fmac_f32_e32 v111, v36, v36
	v_fmac_f32_e32 v111, v38, v38
	v_fmac_f32_e32 v111, v39, v39
	v_add_f32_e32 v107, v111, v107
	v_mul_f32_e32 v111, v33, v33
	v_fmac_f32_e32 v111, v32, v32
	v_fmac_f32_e32 v111, v34, v34
	v_fmac_f32_e32 v111, v35, v35
	v_add_f32_e32 v107, v111, v107
	s_waitcnt vmcnt(3)
	v_mul_f32_e32 v111, v77, v77
	s_waitcnt vmcnt(2)
	v_mul_f32_e32 v114, v73, v73
	v_fmac_f32_e32 v111, v76, v76
	v_fmac_f32_e32 v114, v72, v72
	v_fmac_f32_e32 v111, v78, v78
	v_fmac_f32_e32 v114, v74, v74
	v_fmac_f32_e32 v111, v79, v79
	v_fmac_f32_e32 v114, v75, v75
	v_add_f32_e32 v111, v114, v111
	s_waitcnt vmcnt(1)
	v_mul_f32_e32 v114, v69, v69
	v_fmac_f32_e32 v114, v68, v68
	v_fmac_f32_e32 v114, v70, v70
	v_fmac_f32_e32 v114, v71, v71
	v_add_f32_e32 v111, v114, v111
	s_waitcnt vmcnt(0)
	v_mul_f32_e32 v114, v65, v65
	v_fmac_f32_e32 v114, v64, v64
	v_fmac_f32_e32 v114, v66, v66
	v_fmac_f32_e32 v114, v67, v67
	v_add_f32_e32 v111, v114, v111
	s_nop 0
	s_nop 0
	s_nop 0
	v_cndmask_b32_e64 v103, v103, 8, vcc
	v_cmp_ne_u32_e32 vcc, v103, v109
	s_waitcnt lgkmcnt(2)
	v_mov_b32_e32 v115, v107
	s_nop 1
	v_permlane32_swap_b32_e32 v107, v115
	v_add_f32_e32 v107, v107, v115
	s_waitcnt lgkmcnt(1)
	v_mov_b32_e32 v116, v105
	s_nop 1
	v_permlane32_swap_b32_e32 v105, v116
	v_add_f32_e32 v105, v105, v116
	s_waitcnt lgkmcnt(0)
	v_mov_b32_e32 v114, v111
	s_nop 1
	v_permlane32_swap_b32_e32 v111, v114
	v_add_f32_e32 v111, v111, v114
	ds_bpermute_b32 v115, v93, v107
	ds_bpermute_b32 v116, v93, v105
	ds_bpermute_b32 v114, v93, v111
	s_waitcnt lgkmcnt(2)
	v_add_f32_e32 v107, v107, v115
	s_waitcnt lgkmcnt(1)
	v_add_f32_e32 v105, v105, v116
	s_waitcnt lgkmcnt(0)
	v_add_f32_e32 v111, v111, v114
	s_nop 0
	s_nop 0
	s_nop 0
	s_waitcnt lgkmcnt(2)
	s_nop 1
	v_add_f32_dpp v107, v107, v107 row_ror:8 row_mask:0xf bank_mask:0xf
	s_waitcnt lgkmcnt(1)
	s_nop 1
	v_add_f32_dpp v105, v105, v105 row_ror:8 row_mask:0xf bank_mask:0xf
	s_waitcnt lgkmcnt(0)
	s_nop 1
	v_add_f32_dpp v111, v111, v111 row_ror:8 row_mask:0xf bank_mask:0xf
	s_nop 0
	s_nop 0
	s_nop 0
	s_waitcnt lgkmcnt(2)
	s_nop 1
	v_add_f32_dpp v107, v107, v107 row_ror:4 row_mask:0xf bank_mask:0xf
	s_waitcnt lgkmcnt(1)
	s_nop 1
	v_add_f32_dpp v105, v105, v105 row_ror:4 row_mask:0xf bank_mask:0xf
	s_waitcnt lgkmcnt(0)
	s_nop 1
	v_add_f32_dpp v114, v111, v111 row_ror:4 row_mask:0xf bank_mask:0xf
	s_nop 0
	s_nop 0
	s_nop 0
	s_waitcnt lgkmcnt(2)
	s_nop 1
	v_add_f32_dpp v111, v107, v107 row_ror:2 row_mask:0xf bank_mask:0xf
	s_waitcnt lgkmcnt(1)
	s_nop 1
	v_add_f32_dpp v116, v105, v105 row_ror:2 row_mask:0xf bank_mask:0xf
	s_waitcnt lgkmcnt(0)
	s_nop 1
	v_add_f32_dpp v114, v114, v114 row_ror:2 row_mask:0xf bank_mask:0xf
	ds_bpermute_b32 v119, v122, v111
	ds_bpermute_b32 v117, v122, v116
	ds_bpermute_b32 v115, v122, v114
	s_and_saveexec_b64 s[0:1], vcc
	s_cbranch_execz .LBB0_3068
	v_mul_hi_i32_i24_e32 v1, 0x6000, v103
	v_mul_i32_i24_e32 v0, 0x6000, v103
	v_lshl_add_u64 v[0:1], s[8:9], 0, v[0:1]
	v_lshl_add_u64 v[2:3], v[0:1], 0, s[12:13]
	v_lshl_add_u64 v[4:5], v[2:3], 0, v[82:83]
	v_mov_b32_e32 v109, v83
	global_load_dwordx4 v[16:19], v[4:5], off
	v_lshl_add_u64 v[4:5], v[2:3], 0, v[108:109]
	v_mov_b32_e32 v107, v83
	global_load_dwordx4 v[20:23], v[4:5], off
	v_lshl_add_u64 v[4:5], v[2:3], 0, v[106:107]
	v_mov_b32_e32 v105, v83
	global_load_dwordx4 v[24:27], v[4:5], off
	v_lshl_add_u64 v[2:3], v[2:3], 0, v[104:105]
	global_load_dwordx4 v[28:31], v[2:3], off
	global_load_dwordx4 v[124:127], v[86:87], off
	global_load_dwordx4 v[128:131], v[90:91], off
	v_lshl_add_u64 v[12:13], v[0:1], 0, v[82:83]
	global_load_dwordx4 v[132:135], v[94:95], off
	global_load_dwordx4 v[0:3], v[12:13], off
	global_load_dwordx4 v[136:139], v[98:99], off
	global_load_dwordx4 v[4:7], v[12:13], off offset:1024
	global_load_dwordx4 v[8:11], v[12:13], off offset:2048
	s_nop 0
	global_load_dwordx4 v[12:15], v[12:13], off offset:3072
	v_mov_b32_e32 v109, v103
	s_waitcnt vmcnt(11)
	v_pk_add_f32 v[18:19], v[18:19], 1.0 op_sel_hi:[1,0]
	v_pk_add_f32 v[16:17], v[16:17], 1.0 op_sel_hi:[1,0]
	s_waitcnt vmcnt(10)
	v_pk_add_f32 v[22:23], v[22:23], 1.0 op_sel_hi:[1,0]
	v_pk_add_f32 v[20:21], v[20:21], 1.0 op_sel_hi:[1,0]
	s_waitcnt vmcnt(9)
	v_pk_add_f32 v[26:27], v[26:27], 1.0 op_sel_hi:[1,0]
	v_pk_add_f32 v[24:25], v[24:25], 1.0 op_sel_hi:[1,0]
	s_waitcnt vmcnt(8)
	v_pk_add_f32 v[30:31], v[30:31], 1.0 op_sel_hi:[1,0]
	v_pk_add_f32 v[28:29], v[28:29], 1.0 op_sel_hi:[1,0]
	s_waitcnt vmcnt(7)
	v_pk_mul_f32 v[18:19], v[126:127], v[18:19]
	v_pk_mul_f32 v[16:17], v[124:125], v[16:17]
	s_waitcnt vmcnt(6)
	v_pk_mul_f32 v[22:23], v[130:131], v[22:23]
	v_pk_mul_f32 v[20:21], v[128:129], v[20:21]
	s_waitcnt vmcnt(5)
	v_pk_mul_f32 v[26:27], v[134:135], v[26:27]
	v_pk_mul_f32 v[24:25], v[132:133], v[24:25]
	s_waitcnt vmcnt(3)
	v_pk_mul_f32 v[30:31], v[138:139], v[30:31]
	v_pk_mul_f32 v[28:29], v[136:137], v[28:29]
